# nt (streaming) policy also on out-phase residual loads, glu epilogue staging loads and the phase-0/phase-18 weight-conversion loads
# baseline (speedup 1.0000x reference)
.LBB0_21:
	s_ashr_i32 s6, s19, 31
	s_lshr_b32 s6, s6, 29
	s_add_i32 s6, s19, s6
	s_ashr_i32 s14, s6, 3
	s_lshl_b32 s22, s14, 6
	v_or_b32_e32 v0, s22, v14
	v_lshl_add_u32 v1, s14, 5, v15
	v_add_u32_e32 v2, 0xfffff800, v0
	v_cmp_gt_i32_e32 vcc, s18, v0
	s_mul_i32 s10, s14, 0xffa00000
	v_add_u32_e32 v6, s10, v23
	v_cndmask_b32_e32 v10, v2, v1, vcc
	v_cmp_lt_i32_e64 s[6:7], -1, v10
	v_lshl_add_u64 v[4:5], v[10:11], 2, s[42:43]
	v_mov_b32_e32 v10, v11
	v_mov_b64_e32 v[0:1], v[10:11]
	v_mov_b64_e32 v[2:3], v[10:11]
	s_waitcnt lgkmcnt(0)
	s_barrier
	s_and_saveexec_b64 s[10:11], s[6:7]
	s_cbranch_execz .LBB0_23
	v_ashrrev_i32_e32 v7, 31, v6
	v_lshl_add_u64 v[0:1], v[6:7], 2, v[4:5]
	global_load_dwordx4 v[0:3], v[0:1], off nt
	v_add_u32_e32 v56, 0x30000, v6
	v_ashrrev_i32_e32 v57, 31, v56
	v_lshl_add_u64 v[56:57], v[56:57], 2, v[4:5]
	global_load_dwordx4 v[40:43], v[56:57], off nt
	v_add_u32_e32 v56, 0x60000, v6
	v_ashrrev_i32_e32 v57, 31, v56
	v_lshl_add_u64 v[56:57], v[56:57], 2, v[4:5]
	global_load_dwordx4 v[44:47], v[56:57], off nt
	v_add_u32_e32 v56, 0x90000, v6
	v_ashrrev_i32_e32 v57, 31, v56
	v_lshl_add_u64 v[56:57], v[56:57], 2, v[4:5]
	global_load_dwordx4 v[48:51], v[56:57], off nt
.LBB0_23:
	s_or_b64 exec, exec, s[10:11]
	s_lshl_b32 s10, s14, 10
	s_and_b64 vcc, exec, s[4:5]
	s_sub_i32 s14, 0, s10
	s_cbranch_vccnz .LBB0_25
	s_add_i32 s10, s14, s3
	v_add_u32_e32 v24, s10, v8
	v_ashrrev_i32_e32 v25, 31, v24
	v_lshl_add_u64 v[24:25], v[24:25], 2, s[40:41]
	global_load_dword v10, v[24:25], off nt
	global_load_dword v52, v[24:25], off offset:128 nt
	global_load_dword v53, v[24:25], off offset:256 nt
	global_load_dword v54, v[24:25], off offset:384 nt
	s_waitcnt vmcnt(0)
	v_pk_mul_f32 v[0:1], v[0:1], v[10:11] op_sel_hi:[1,0]
	v_pk_mul_f32 v[2:3], v[2:3], v[10:11] op_sel_hi:[1,0]

.LBB0_44:
	s_ashr_i32 s5, s9, 31
	s_lshr_b32 s5, s5, 28
	s_add_i32 s5, s9, s5
	s_ashr_i32 s5, s5, 4
	s_lshl_b32 s10, s5, 11
	s_sub_i32 s10, 0, s10
	s_lshl_b32 s5, s5, 6
	v_mov_b32_e32 v0, 0
	s_andn2_b64 vcc, exec, s[6:7]
	v_mov_b32_e32 v1, 0
	v_mov_b32_e32 v2, 0
	v_mov_b32_e32 v3, 0
	v_mov_b32_e32 v4, 0
	v_mov_b32_e32 v5, 0
	v_mov_b32_e32 v6, 0
	v_mov_b32_e32 v7, 0
	s_cbranch_vccnz .LBB0_41
	s_add_i32 s6, s10, s3
	v_add_u32_e32 v2, s6, v12
	v_or_b32_e32 v8, s5, v13
	v_ashrrev_i32_e32 v3, 31, v2
	v_add_u32_e32 v6, 32, v2
	v_lshl_add_u64 v[0:1], v[8:9], 2, s[60:61]
	v_lshlrev_b64 v[4:5], 12, v[2:3]
	v_ashrrev_i32_e32 v7, 31, v6
	v_lshl_add_u64 v[4:5], v[0:1], 0, v[4:5]
	v_lshlrev_b64 v[6:7], 12, v[6:7]
	v_lshl_add_u64 v[6:7], v[0:1], 0, v[6:7]
	global_load_dwordx4 v[22:25], v[4:5], off nt
	global_load_dwordx4 v[26:29], v[6:7], off nt
	v_add_u32_e32 v4, 64, v2
	v_add_u32_e32 v2, 0x60, v2
	v_ashrrev_i32_e32 v5, 31, v4
	v_ashrrev_i32_e32 v3, 31, v2
	v_lshlrev_b64 v[4:5], 12, v[4:5]
	v_lshlrev_b64 v[2:3], 12, v[2:3]
	v_lshl_add_u64 v[4:5], v[0:1], 0, v[4:5]
	v_lshl_add_u64 v[0:1], v[0:1], 0, v[2:3]
	global_load_dwordx4 v[4:7], v[4:5], off nt
	s_nop 0
	global_load_dwordx4 v[0:3], v[0:1], off nt
	s_waitcnt vmcnt(3)
	ds_write_b128 v15, v[22:25]
	s_waitcnt vmcnt(2)
	ds_write_b128 v17, v[26:29]
	s_branch .LBB0_41

.LBB0_262:
	s_add_i32 s58, s58, s82
	s_add_i32 s57, s57, s82
	v_and_b32_e32 v231, 15, v181
	v_bfe_u32 v135, v181, 4, 2
	v_lshlrev_b32_e32 v230, 4, v231
	s_movk_i32 s20, 0x110
	v_mad_u32_u24 v230, v135, s20, v230
	v_lshlrev_b32_e32 v180, 2, v231
	s_movk_i32 s20, 0x440
	v_mad_u32_u24 v180, v135, s20, v180
	v_lshlrev_b32_e32 v135, 12, v135
	v_lshl_add_u32 v135, v231, 4, v135
	v_lshrrev_b32_e32 v231, 6, v181
	v_mul_u32_u24_e32 v231, 0x4400, v231
	v_add_u32_e32 v230, v230, v231
	v_add_u32_e32 v180, v180, v231
	v_bfe_u32 v231, v181, 6, 2
	v_lshl_add_u32 v135, v231, 8, v135
	v_lshrrev_b32_e32 v231, 8, v181
	v_lshl_add_u32 v135, v231, 19, v135
	s_lshl_b32 s20, s48, 20
	v_add_u32_e32 v135, s20, v135
	s_lshl_b32 s20, s6, 10
	v_add_u32_e32 v135, s20, v135
	s_mov_b32 s50, s36
	s_mov_b32 s51, s37
	s_mov_b32 s52, s78
	s_mov_b32 s53, s79
	global_load_dwordx4 v[130:133], v135, s[50:51] nt
	s_add_u32 s50, s50, 0x4000
	s_addc_u32 s51, s51, 0
	global_load_dwordx4 v[136:139], v135, s[50:51] nt
	s_add_u32 s50, s50, 0x4000
	s_addc_u32 s51, s51, 0
	global_load_dwordx4 v[140:143], v135, s[50:51] nt
	s_add_u32 s50, s50, 0x4000
	s_addc_u32 s51, s51, 0
	global_load_dwordx4 v[144:147], v135, s[50:51] nt
	s_add_u32 s50, s50, 0x4000
	s_addc_u32 s51, s51, 0
	global_load_dwordx4 v[148:151], v135, s[50:51] nt
	s_add_u32 s50, s50, 0x4000
	s_addc_u32 s51, s51, 0
	global_load_dwordx4 v[152:155], v135, s[50:51] nt
	s_add_u32 s50, s50, 0x4000
	s_addc_u32 s51, s51, 0
	global_load_dwordx4 v[156:159], v135, s[50:51] nt
	s_add_u32 s50, s50, 0x4000
	s_addc_u32 s51, s51, 0
	global_load_dwordx4 v[160:163], v135, s[50:51] nt
	s_add_u32 s50, s50, 0x4000
	s_addc_u32 s51, s51, 0
	global_load_dwordx4 v[164:167], v135, s[50:51] nt
	s_add_u32 s50, s50, 0x4000
	s_addc_u32 s51, s51, 0
	global_load_dwordx4 v[168:171], v135, s[50:51] nt
	s_add_u32 s50, s50, 0x4000
	s_addc_u32 s51, s51, 0
	global_load_dwordx4 v[172:175], v135, s[50:51] nt
	s_add_u32 s50, s50, 0x4000
	s_addc_u32 s51, s51, 0
	global_load_dwordx4 v[176:179], v135, s[50:51] nt
	s_add_u32 s50, s50, 0x4000
	s_addc_u32 s51, s51, 0
	global_load_dwordx4 v[182:185], v135, s[50:51] nt
	s_add_u32 s50, s50, 0x4000
	s_addc_u32 s51, s51, 0
	global_load_dwordx4 v[186:189], v135, s[50:51] nt
	s_add_u32 s50, s50, 0x4000
	s_addc_u32 s51, s51, 0
	global_load_dwordx4 v[190:193], v135, s[50:51] nt
	s_add_u32 s50, s50, 0x4000
	s_addc_u32 s51, s51, 0
	global_load_dwordx4 v[194:197], v135, s[50:51] nt
	s_add_u32 s50, s50, 0x4000
	s_addc_u32 s51, s51, 0
	ds_write_b32 v180, v124
	ds_write_b32 v180, v125 offset:272
	ds_write_b32 v180, v126 offset:544
	ds_write_b32 v180, v127 offset:816
	ds_write_b32 v180, v120 offset:64
	ds_write_b32 v180, v121 offset:336
	ds_write_b32 v180, v122 offset:608
	ds_write_b32 v180, v123 offset:880
	ds_write_b32 v180, v116 offset:128
	ds_write_b32 v180, v117 offset:400
	ds_write_b32 v180, v118 offset:672
	ds_write_b32 v180, v119 offset:944
	ds_write_b32 v180, v112 offset:192
	ds_write_b32 v180, v113 offset:464
	ds_write_b32 v180, v114 offset:736
	ds_write_b32 v180, v115 offset:1008
	ds_write_b32 v180, v108 offset:4352
	ds_write_b32 v180, v109 offset:4624
	ds_write_b32 v180, v110 offset:4896
	ds_write_b32 v180, v111 offset:5168
	ds_write_b32 v180, v104 offset:4416
	ds_write_b32 v180, v105 offset:4688
	ds_write_b32 v180, v106 offset:4960
	ds_write_b32 v180, v107 offset:5232
	ds_write_b32 v180, v100 offset:4480
	ds_write_b32 v180, v101 offset:4752
	ds_write_b32 v180, v102 offset:5024
	ds_write_b32 v180, v103 offset:5296
	ds_write_b32 v180, v96 offset:4544
	ds_write_b32 v180, v97 offset:4816
	ds_write_b32 v180, v98 offset:5088
	ds_write_b32 v180, v99 offset:5360
	ds_write_b32 v180, v92 offset:8704
	ds_write_b32 v180, v93 offset:8976
	ds_write_b32 v180, v94 offset:9248
	ds_write_b32 v180, v95 offset:9520
	ds_write_b32 v180, v88 offset:8768
	ds_write_b32 v180, v89 offset:9040
	ds_write_b32 v180, v90 offset:9312
	ds_write_b32 v180, v91 offset:9584
	ds_write_b32 v180, v84 offset:8832
	ds_write_b32 v180, v85 offset:9104
	ds_write_b32 v180, v86 offset:9376
	ds_write_b32 v180, v87 offset:9648
	ds_write_b32 v180, v80 offset:8896
	ds_write_b32 v180, v81 offset:9168
	ds_write_b32 v180, v82 offset:9440
	ds_write_b32 v180, v83 offset:9712
	ds_write_b32 v180, v76 offset:13056
	ds_write_b32 v180, v77 offset:13328
	ds_write_b32 v180, v78 offset:13600
	ds_write_b32 v180, v79 offset:13872
	ds_write_b32 v180, v72 offset:13120
	ds_write_b32 v180, v73 offset:13392
	ds_write_b32 v180, v74 offset:13664
	ds_write_b32 v180, v75 offset:13936
	ds_write_b32 v180, v68 offset:13184
	ds_write_b32 v180, v69 offset:13456
	ds_write_b32 v180, v70 offset:13728
	ds_write_b32 v180, v71 offset:14000
	ds_write_b32 v180, v64 offset:13248
	ds_write_b32 v180, v65 offset:13520
	ds_write_b32 v180, v66 offset:13792
	ds_write_b32 v180, v67 offset:14064
	s_waitcnt lgkmcnt(0)
	ds_read_b128 v[198:201], v230
	ds_read_b128 v[202:205], v230 offset:1088
	ds_read_b128 v[206:209], v230 offset:2176
	ds_read_b128 v[210:213], v230 offset:3264
	ds_read_b128 v[214:217], v230 offset:4352
	ds_read_b128 v[218:221], v230 offset:5440
	ds_read_b128 v[222:225], v230 offset:6528
	ds_read_b128 v[226:229], v230 offset:7616
	s_waitcnt vmcnt(15) lgkmcnt(7)
	v_pk_add_f32 v[130:131], v[130:131], v[198:199]
	v_pk_add_f32 v[132:133], v[132:133], v[200:201]
	global_store_dwordx4 v135, v[130:133], s[52:53] sc1
	s_add_u32 s52, s52, 0x4000
	s_addc_u32 s53, s53, 0
	s_waitcnt vmcnt(15) lgkmcnt(6)
	v_pk_add_f32 v[136:137], v[136:137], v[202:203]
	v_pk_add_f32 v[138:139], v[138:139], v[204:205]
	global_store_dwordx4 v135, v[136:139], s[52:53] sc1
	s_add_u32 s52, s52, 0x4000
	s_addc_u32 s53, s53, 0
	s_waitcnt vmcnt(15) lgkmcnt(5)
	v_pk_add_f32 v[140:141], v[140:141], v[206:207]
	v_pk_add_f32 v[142:143], v[142:143], v[208:209]
	global_store_dwordx4 v135, v[140:143], s[52:53] sc1
	s_add_u32 s52, s52, 0x4000
	s_addc_u32 s53, s53, 0
	s_waitcnt vmcnt(15) lgkmcnt(4)
	v_pk_add_f32 v[144:145], v[144:145], v[210:211]
	v_pk_add_f32 v[146:147], v[146:147], v[212:213]
	global_store_dwordx4 v135, v[144:147], s[52:53] sc1
	s_add_u32 s52, s52, 0x4000
	s_addc_u32 s53, s53, 0
	s_waitcnt vmcnt(15) lgkmcnt(3)
	v_pk_add_f32 v[148:149], v[148:149], v[214:215]
	v_pk_add_f32 v[150:151], v[150:151], v[216:217]
	global_store_dwordx4 v135, v[148:151], s[52:53] sc1
	s_add_u32 s52, s52, 0x4000
	s_addc_u32 s53, s53, 0
	s_waitcnt vmcnt(15) lgkmcnt(2)
	v_pk_add_f32 v[152:153], v[152:153], v[218:219]
	v_pk_add_f32 v[154:155], v[154:155], v[220:221]
	global_store_dwordx4 v135, v[152:155], s[52:53] sc1
	s_add_u32 s52, s52, 0x4000
	s_addc_u32 s53, s53, 0
	s_waitcnt vmcnt(15) lgkmcnt(1)
	v_pk_add_f32 v[156:157], v[156:157], v[222:223]
	v_pk_add_f32 v[158:159], v[158:159], v[224:225]
	global_store_dwordx4 v135, v[156:159], s[52:53] sc1
	s_add_u32 s52, s52, 0x4000
	s_addc_u32 s53, s53, 0
	s_waitcnt vmcnt(15) lgkmcnt(0)
	v_pk_add_f32 v[160:161], v[160:161], v[226:227]
	v_pk_add_f32 v[162:163], v[162:163], v[228:229]
	global_store_dwordx4 v135, v[160:163], s[52:53] sc1
	s_add_u32 s52, s52, 0x4000
	s_addc_u32 s53, s53, 0
	global_load_dwordx4 v[130:133], v135, s[50:51] nt
	s_add_u32 s50, s50, 0x4000
	s_addc_u32 s51, s51, 0
	global_load_dwordx4 v[136:139], v135, s[50:51] nt
	s_add_u32 s50, s50, 0x4000
	s_addc_u32 s51, s51, 0
	global_load_dwordx4 v[140:143], v135, s[50:51] nt
	s_add_u32 s50, s50, 0x4000
	s_addc_u32 s51, s51, 0
	global_load_dwordx4 v[144:147], v135, s[50:51] nt
	s_add_u32 s50, s50, 0x4000
	s_addc_u32 s51, s51, 0
	global_load_dwordx4 v[148:151], v135, s[50:51] nt
	s_add_u32 s50, s50, 0x4000
	s_addc_u32 s51, s51, 0
	global_load_dwordx4 v[152:155], v135, s[50:51] nt
	s_add_u32 s50, s50, 0x4000
	s_addc_u32 s51, s51, 0
	global_load_dwordx4 v[156:159], v135, s[50:51] nt
	s_add_u32 s50, s50, 0x4000
	s_addc_u32 s51, s51, 0
	global_load_dwordx4 v[160:163], v135, s[50:51] nt
	s_add_u32 s50, s50, 0x4000
	s_addc_u32 s51, s51, 0
	ds_read_b128 v[198:201], v230 offset:8704
	ds_read_b128 v[202:205], v230 offset:9792
	ds_read_b128 v[206:209], v230 offset:10880
	ds_read_b128 v[210:213], v230 offset:11968
	ds_read_b128 v[214:217], v230 offset:13056
	ds_read_b128 v[218:221], v230 offset:14144
	ds_read_b128 v[222:225], v230 offset:15232
	ds_read_b128 v[226:229], v230 offset:16320
	s_waitcnt vmcnt(15) lgkmcnt(7)
	v_pk_add_f32 v[164:165], v[164:165], v[198:199]
	v_pk_add_f32 v[166:167], v[166:167], v[200:201]
	global_store_dwordx4 v135, v[164:167], s[52:53] sc1
	s_add_u32 s52, s52, 0x4000
	s_addc_u32 s53, s53, 0
	s_waitcnt vmcnt(15) lgkmcnt(6)
	v_pk_add_f32 v[168:169], v[168:169], v[202:203]
	v_pk_add_f32 v[170:171], v[170:171], v[204:205]
	global_store_dwordx4 v135, v[168:171], s[52:53] sc1
	s_add_u32 s52, s52, 0x4000
	s_addc_u32 s53, s53, 0
	s_waitcnt vmcnt(15) lgkmcnt(5)
	v_pk_add_f32 v[172:173], v[172:173], v[206:207]
	v_pk_add_f32 v[174:175], v[174:175], v[208:209]
	global_store_dwordx4 v135, v[172:175], s[52:53] sc1
	s_add_u32 s52, s52, 0x4000
	s_addc_u32 s53, s53, 0
	s_waitcnt vmcnt(15) lgkmcnt(4)
	v_pk_add_f32 v[176:177], v[176:177], v[210:211]
	v_pk_add_f32 v[178:179], v[178:179], v[212:213]
	global_store_dwordx4 v135, v[176:179], s[52:53] sc1
	s_add_u32 s52, s52, 0x4000
	s_addc_u32 s53, s53, 0
	s_waitcnt vmcnt(15) lgkmcnt(3)
	v_pk_add_f32 v[182:183], v[182:183], v[214:215]
	v_pk_add_f32 v[184:185], v[184:185], v[216:217]
	global_store_dwordx4 v135, v[182:185], s[52:53] sc1
	s_add_u32 s52, s52, 0x4000
	s_addc_u32 s53, s53, 0
	s_waitcnt vmcnt(15) lgkmcnt(2)
	v_pk_add_f32 v[186:187], v[186:187], v[218:219]
	v_pk_add_f32 v[188:189], v[188:189], v[220:221]
	global_store_dwordx4 v135, v[186:189], s[52:53] sc1
	s_add_u32 s52, s52, 0x4000
	s_addc_u32 s53, s53, 0
	s_waitcnt vmcnt(15) lgkmcnt(1)
	v_pk_add_f32 v[190:191], v[190:191], v[222:223]
	v_pk_add_f32 v[192:193], v[192:193], v[224:225]
	global_store_dwordx4 v135, v[190:193], s[52:53] sc1
	s_add_u32 s52, s52, 0x4000
	s_addc_u32 s53, s53, 0
	s_waitcnt vmcnt(15) lgkmcnt(0)
	v_pk_add_f32 v[194:195], v[194:195], v[226:227]
	v_pk_add_f32 v[196:197], v[196:197], v[228:229]
	global_store_dwordx4 v135, v[194:197], s[52:53] sc1
	s_add_u32 s52, s52, 0x4000
	s_addc_u32 s53, s53, 0
	s_waitcnt lgkmcnt(0)
	global_load_dwordx4 v[164:167], v135, s[50:51] nt
	s_add_u32 s50, s50, 0x4000
	s_addc_u32 s51, s51, 0
	global_load_dwordx4 v[168:171], v135, s[50:51] nt
	s_add_u32 s50, s50, 0x4000
	s_addc_u32 s51, s51, 0
	global_load_dwordx4 v[172:175], v135, s[50:51] nt
	s_add_u32 s50, s50, 0x4000
	s_addc_u32 s51, s51, 0
	global_load_dwordx4 v[176:179], v135, s[50:51] nt
	s_add_u32 s50, s50, 0x4000
	s_addc_u32 s51, s51, 0
	global_load_dwordx4 v[182:185], v135, s[50:51] nt
	s_add_u32 s50, s50, 0x4000
	s_addc_u32 s51, s51, 0
	global_load_dwordx4 v[186:189], v135, s[50:51] nt
	s_add_u32 s50, s50, 0x4000
	s_addc_u32 s51, s51, 0
	global_load_dwordx4 v[190:193], v135, s[50:51] nt
	s_add_u32 s50, s50, 0x4000
	s_addc_u32 s51, s51, 0
	global_load_dwordx4 v[194:197], v135, s[50:51] nt
	s_add_u32 s50, s50, 0x4000
	s_addc_u32 s51, s51, 0
	ds_write_b32 v180, v60
	ds_write_b32 v180, v61 offset:272
	ds_write_b32 v180, v62 offset:544
	ds_write_b32 v180, v63 offset:816
	ds_write_b32 v180, v56 offset:64
	ds_write_b32 v180, v57 offset:336
	ds_write_b32 v180, v58 offset:608
	ds_write_b32 v180, v59 offset:880
	ds_write_b32 v180, v52 offset:128
	ds_write_b32 v180, v53 offset:400
	ds_write_b32 v180, v54 offset:672
	ds_write_b32 v180, v55 offset:944
	ds_write_b32 v180, v48 offset:192
	ds_write_b32 v180, v49 offset:464
	ds_write_b32 v180, v50 offset:736
	ds_write_b32 v180, v51 offset:1008
	ds_write_b32 v180, v44 offset:4352
	ds_write_b32 v180, v45 offset:4624
	ds_write_b32 v180, v46 offset:4896
	ds_write_b32 v180, v47 offset:5168
	ds_write_b32 v180, v40 offset:4416
	ds_write_b32 v180, v41 offset:4688
	ds_write_b32 v180, v42 offset:4960
	ds_write_b32 v180, v43 offset:5232
	ds_write_b32 v180, v36 offset:4480
	ds_write_b32 v180, v37 offset:4752
	ds_write_b32 v180, v38 offset:5024
	ds_write_b32 v180, v39 offset:5296
	ds_write_b32 v180, v32 offset:4544
	ds_write_b32 v180, v33 offset:4816
	ds_write_b32 v180, v34 offset:5088
	ds_write_b32 v180, v35 offset:5360
	ds_write_b32 v180, v28 offset:8704
	ds_write_b32 v180, v29 offset:8976
	ds_write_b32 v180, v30 offset:9248
	ds_write_b32 v180, v31 offset:9520
	ds_write_b32 v180, v20 offset:8768
	ds_write_b32 v180, v21 offset:9040
	ds_write_b32 v180, v22 offset:9312
	ds_write_b32 v180, v23 offset:9584
	ds_write_b32 v180, v16 offset:8832
	ds_write_b32 v180, v17 offset:9104
	ds_write_b32 v180, v18 offset:9376
	ds_write_b32 v180, v19 offset:9648
	ds_write_b32 v180, v8 offset:8896
	ds_write_b32 v180, v9 offset:9168
	ds_write_b32 v180, v10 offset:9440
	ds_write_b32 v180, v11 offset:9712
	ds_write_b32 v180, v4 offset:13056
	ds_write_b32 v180, v5 offset:13328
	ds_write_b32 v180, v6 offset:13600
	ds_write_b32 v180, v7 offset:13872
	ds_write_b32 v180, v0 offset:13120
	ds_write_b32 v180, v1 offset:13392
	ds_write_b32 v180, v2 offset:13664
	ds_write_b32 v180, v3 offset:13936
	ds_write_b32 v180, v24 offset:13184
	ds_write_b32 v180, v25 offset:13456
	ds_write_b32 v180, v26 offset:13728
	ds_write_b32 v180, v27 offset:14000
	ds_write_b32 v180, v12 offset:13248
	ds_write_b32 v180, v13 offset:13520
	ds_write_b32 v180, v14 offset:13792
	ds_write_b32 v180, v15 offset:14064
	s_waitcnt lgkmcnt(0)
	ds_read_b128 v[198:201], v230
	ds_read_b128 v[202:205], v230 offset:1088
	ds_read_b128 v[206:209], v230 offset:2176
	ds_read_b128 v[210:213], v230 offset:3264
	ds_read_b128 v[214:217], v230 offset:4352
	ds_read_b128 v[218:221], v230 offset:5440
	ds_read_b128 v[222:225], v230 offset:6528
	ds_read_b128 v[226:229], v230 offset:7616
	s_waitcnt vmcnt(15) lgkmcnt(7)
	v_pk_add_f32 v[130:131], v[130:131], v[198:199]
	v_pk_add_f32 v[132:133], v[132:133], v[200:201]
	global_store_dwordx4 v135, v[130:133], s[52:53] sc1
	s_add_u32 s52, s52, 0x4000
	s_addc_u32 s53, s53, 0
	s_waitcnt vmcnt(15) lgkmcnt(6)
	v_pk_add_f32 v[136:137], v[136:137], v[202:203]
	v_pk_add_f32 v[138:139], v[138:139], v[204:205]
	global_store_dwordx4 v135, v[136:139], s[52:53] sc1
	s_add_u32 s52, s52, 0x4000
	s_addc_u32 s53, s53, 0
	s_waitcnt vmcnt(15) lgkmcnt(5)
	v_pk_add_f32 v[140:141], v[140:141], v[206:207]
	v_pk_add_f32 v[142:143], v[142:143], v[208:209]
	global_store_dwordx4 v135, v[140:143], s[52:53] sc1
	s_add_u32 s52, s52, 0x4000
	s_addc_u32 s53, s53, 0
	s_waitcnt vmcnt(15) lgkmcnt(4)
	v_pk_add_f32 v[144:145], v[144:145], v[210:211]
	v_pk_add_f32 v[146:147], v[146:147], v[212:213]
	global_store_dwordx4 v135, v[144:147], s[52:53] sc1
	s_add_u32 s52, s52, 0x4000
	s_addc_u32 s53, s53, 0
	s_waitcnt vmcnt(15) lgkmcnt(3)
	v_pk_add_f32 v[148:149], v[148:149], v[214:215]
	v_pk_add_f32 v[150:151], v[150:151], v[216:217]
	global_store_dwordx4 v135, v[148:151], s[52:53] sc1
	s_add_u32 s52, s52, 0x4000
	s_addc_u32 s53, s53, 0
	s_waitcnt vmcnt(15) lgkmcnt(2)
	v_pk_add_f32 v[152:153], v[152:153], v[218:219]
	v_pk_add_f32 v[154:155], v[154:155], v[220:221]
	global_store_dwordx4 v135, v[152:155], s[52:53] sc1
	s_add_u32 s52, s52, 0x4000
	s_addc_u32 s53, s53, 0
	s_waitcnt vmcnt(15) lgkmcnt(1)
	v_pk_add_f32 v[156:157], v[156:157], v[222:223]
	v_pk_add_f32 v[158:159], v[158:159], v[224:225]
	global_store_dwordx4 v135, v[156:159], s[52:53] sc1
	s_add_u32 s52, s52, 0x4000
	s_addc_u32 s53, s53, 0
	s_waitcnt vmcnt(15) lgkmcnt(0)
	v_pk_add_f32 v[160:161], v[160:161], v[226:227]
	v_pk_add_f32 v[162:163], v[162:163], v[228:229]
	global_store_dwordx4 v135, v[160:163], s[52:53] sc1
	s_add_u32 s52, s52, 0x4000
	s_addc_u32 s53, s53, 0
	ds_read_b128 v[198:201], v230 offset:8704
	ds_read_b128 v[202:205], v230 offset:9792
	ds_read_b128 v[206:209], v230 offset:10880
	ds_read_b128 v[210:213], v230 offset:11968
	ds_read_b128 v[214:217], v230 offset:13056
	ds_read_b128 v[218:221], v230 offset:14144
	ds_read_b128 v[222:225], v230 offset:15232
	ds_read_b128 v[226:229], v230 offset:16320
	s_waitcnt vmcnt(7) lgkmcnt(7)
	v_pk_add_f32 v[164:165], v[164:165], v[198:199]
	v_pk_add_f32 v[166:167], v[166:167], v[200:201]
	global_store_dwordx4 v135, v[164:167], s[52:53] sc1
	s_add_u32 s52, s52, 0x4000
	s_addc_u32 s53, s53, 0
	s_waitcnt vmcnt(7) lgkmcnt(6)
	v_pk_add_f32 v[168:169], v[168:169], v[202:203]
	v_pk_add_f32 v[170:171], v[170:171], v[204:205]
	global_store_dwordx4 v135, v[168:171], s[52:53] sc1
	s_add_u32 s52, s52, 0x4000
	s_addc_u32 s53, s53, 0
	s_waitcnt vmcnt(7) lgkmcnt(5)
	v_pk_add_f32 v[172:173], v[172:173], v[206:207]
	v_pk_add_f32 v[174:175], v[174:175], v[208:209]
	global_store_dwordx4 v135, v[172:175], s[52:53] sc1
	s_add_u32 s52, s52, 0x4000
	s_addc_u32 s53, s53, 0
	s_waitcnt vmcnt(7) lgkmcnt(4)
	v_pk_add_f32 v[176:177], v[176:177], v[210:211]
	v_pk_add_f32 v[178:179], v[178:179], v[212:213]
	global_store_dwordx4 v135, v[176:179], s[52:53] sc1
	s_add_u32 s52, s52, 0x4000
	s_addc_u32 s53, s53, 0
	s_waitcnt vmcnt(7) lgkmcnt(3)
	v_pk_add_f32 v[182:183], v[182:183], v[214:215]
	v_pk_add_f32 v[184:185], v[184:185], v[216:217]
	global_store_dwordx4 v135, v[182:185], s[52:53] sc1
	s_add_u32 s52, s52, 0x4000
	s_addc_u32 s53, s53, 0
	s_waitcnt vmcnt(7) lgkmcnt(2)
	v_pk_add_f32 v[186:187], v[186:187], v[218:219]
	v_pk_add_f32 v[188:189], v[188:189], v[220:221]
	global_store_dwordx4 v135, v[186:189], s[52:53] sc1
	s_add_u32 s52, s52, 0x4000
	s_addc_u32 s53, s53, 0
	s_waitcnt vmcnt(7) lgkmcnt(1)
	v_pk_add_f32 v[190:191], v[190:191], v[222:223]
	v_pk_add_f32 v[192:193], v[192:193], v[224:225]
	global_store_dwordx4 v135, v[190:193], s[52:53] sc1
	s_add_u32 s52, s52, 0x4000
	s_addc_u32 s53, s53, 0
	s_waitcnt vmcnt(7) lgkmcnt(0)
	v_pk_add_f32 v[194:195], v[194:195], v[226:227]
	v_pk_add_f32 v[196:197], v[196:197], v[228:229]
	global_store_dwordx4 v135, v[194:197], s[52:53] sc1
	s_add_u32 s52, s52, 0x4000
	s_addc_u32 s53, s53, 0
	s_cmpk_lt_i32 s58, 0x100
	s_cbranch_scc0 .LBB0_269

.LBB0_674:
	s_lshl_b32 s20, s95, 2
	s_mov_b32 s21, s7
	v_lshl_add_u64 v[174:175], v[132:133], 0, s[20:21]
	global_load_dword v145, v[174:175], off
	global_load_dword v144, v[174:175], off offset:64
	global_load_dword v143, v[174:175], off offset:128
	global_load_dword v142, v[174:175], off offset:192
	v_lshlrev_b64 v[140:141], 11, v[140:141]
	s_lshl_b32 s6, s6, 8
	v_lshl_add_u64 v[140:141], v[128:129], 0, v[140:141]
	v_lshl_add_u64 v[140:141], v[140:141], 0, s[6:7]
	v_lshl_add_u64 v[140:141], v[140:141], 1, v[136:137]
	s_mov_b64 s[64:65], 0
	v_mov_b32_e32 v174, v171
	s_mov_b64 s[64:65], 0xa000000
	v_lshl_add_u64 v[250:251], v[140:141], 0, s[64:65]
	s_mov_b64 s[64:65], 0x8000
	global_load_dwordx4 v[194:197], v[250:251], off nt
	v_lshl_add_u64 v[250:251], v[250:251], 0, s[64:65]
	global_load_dwordx4 v[198:201], v[250:251], off nt
	v_lshl_add_u64 v[250:251], v[250:251], 0, s[64:65]
	global_load_dwordx4 v[202:205], v[250:251], off nt
	v_lshl_add_u64 v[250:251], v[250:251], 0, s[64:65]
	global_load_dwordx4 v[206:209], v[250:251], off nt
	v_lshl_add_u64 v[250:251], v[250:251], 0, s[64:65]
	global_load_dwordx4 v[210:213], v[250:251], off nt
	v_lshl_add_u64 v[250:251], v[250:251], 0, s[64:65]
	global_load_dwordx4 v[214:217], v[250:251], off nt
	v_lshl_add_u64 v[250:251], v[250:251], 0, s[64:65]
	global_load_dwordx4 v[218:221], v[250:251], off nt
	v_lshl_add_u64 v[250:251], v[250:251], 0, s[64:65]
	global_load_dwordx4 v[222:225], v[250:251], off nt
	s_mov_b64 s[64:65], 0x6000000
	v_lshl_add_u64 v[250:251], v[140:141], 0, s[64:65]
	s_mov_b64 s[64:65], 0x8000
	global_load_dwordx4 v[226:229], v[250:251], off nt
	v_lshl_add_u64 v[250:251], v[250:251], 0, s[64:65]
	global_load_dwordx4 v[230:233], v[250:251], off nt
	v_lshl_add_u64 v[250:251], v[250:251], 0, s[64:65]
	global_load_dwordx4 v[234:237], v[250:251], off nt
	v_lshl_add_u64 v[250:251], v[250:251], 0, s[64:65]
	global_load_dwordx4 v[238:241], v[250:251], off nt
	v_lshl_add_u64 v[250:251], v[250:251], 0, s[64:65]
	global_load_dwordx4 v[242:245], v[250:251], off nt
	v_lshl_add_u64 v[250:251], v[250:251], 0, s[64:65]
	global_load_dwordx4 v[246:249], v[250:251], off nt
	v_lshl_add_u64 v[250:251], v[250:251], 0, s[64:65]
	s_waitcnt vmcnt(13)
	ds_write_b128 v171, v[194:197]
	s_waitcnt vmcnt(12)
	ds_write_b128 v171, v[198:201] offset:1152
	s_mov_b64 s[64:65], 0x8000
	global_load_dwordx4 v[194:197], v[250:251], off nt
	v_lshl_add_u64 v[250:251], v[250:251], 0, s[64:65]
	global_load_dwordx4 v[198:201], v[250:251], off nt
	s_waitcnt vmcnt(13)
	ds_write_b128 v171, v[202:205] offset:2304
	s_waitcnt vmcnt(12)
	ds_write_b128 v171, v[206:209] offset:3456
	s_waitcnt vmcnt(11)
	ds_write_b128 v171, v[210:213] offset:4608
	s_waitcnt vmcnt(10)
	ds_write_b128 v171, v[214:217] offset:5760
	s_waitcnt vmcnt(9)
	ds_write_b128 v171, v[218:221] offset:6912
	s_waitcnt vmcnt(8)
	ds_write_b128 v171, v[222:225] offset:8064
	s_waitcnt vmcnt(7)
	ds_write_b128 v130, v[226:229]
	s_waitcnt vmcnt(6)
	ds_write_b128 v130, v[230:233] offset:1152
	s_waitcnt vmcnt(5)
	ds_write_b128 v130, v[234:237] offset:2304
	s_waitcnt vmcnt(4)
	ds_write_b128 v130, v[238:241] offset:3456
	s_waitcnt vmcnt(3)
	ds_write_b128 v130, v[242:245] offset:4608
	s_waitcnt vmcnt(2)
	ds_write_b128 v130, v[246:249] offset:5760
	s_waitcnt vmcnt(1)
	ds_write_b128 v130, v[194:197] offset:6912
	s_waitcnt vmcnt(0)
	ds_write_b128 v130, v[198:201] offset:8064
	s_mov_b64 s[64:65], 0xa040000
	v_lshl_add_u64 v[250:251], v[138:139], 0, s[64:65]
	s_mov_b64 s[64:65], 0x8000
	global_load_dwordx4 v[194:197], v[250:251], off nt
	v_lshl_add_u64 v[250:251], v[250:251], 0, s[64:65]
	global_load_dwordx4 v[198:201], v[250:251], off nt
	v_lshl_add_u64 v[250:251], v[250:251], 0, s[64:65]
	global_load_dwordx4 v[202:205], v[250:251], off nt
	v_lshl_add_u64 v[250:251], v[250:251], 0, s[64:65]
	global_load_dwordx4 v[206:209], v[250:251], off nt
	v_lshl_add_u64 v[250:251], v[250:251], 0, s[64:65]
	global_load_dwordx4 v[210:213], v[250:251], off nt
	v_lshl_add_u64 v[250:251], v[250:251], 0, s[64:65]
	global_load_dwordx4 v[214:217], v[250:251], off nt
	v_lshl_add_u64 v[250:251], v[250:251], 0, s[64:65]
	global_load_dwordx4 v[218:221], v[250:251], off nt
	v_lshl_add_u64 v[250:251], v[250:251], 0, s[64:65]
	global_load_dwordx4 v[222:225], v[250:251], off nt
	s_mov_b64 s[64:65], 0x6040000
	v_lshl_add_u64 v[250:251], v[138:139], 0, s[64:65]
	s_mov_b64 s[64:65], 0x8000
	global_load_dwordx4 v[226:229], v[250:251], off nt
	v_lshl_add_u64 v[250:251], v[250:251], 0, s[64:65]
	global_load_dwordx4 v[230:233], v[250:251], off nt
	v_lshl_add_u64 v[250:251], v[250:251], 0, s[64:65]
	global_load_dwordx4 v[234:237], v[250:251], off nt
	v_lshl_add_u64 v[250:251], v[250:251], 0, s[64:65]
	global_load_dwordx4 v[238:241], v[250:251], off nt
	v_lshl_add_u64 v[250:251], v[250:251], 0, s[64:65]
	global_load_dwordx4 v[242:245], v[250:251], off nt
	v_lshl_add_u64 v[250:251], v[250:251], 0, s[64:65]
	global_load_dwordx4 v[246:249], v[250:251], off nt
	v_lshl_add_u64 v[250:251], v[250:251], 0, s[64:65]
	v_add_f32_e32 v124, v124, v145
	v_mul_f32_e32 v124, 0xbfb8aa3b, v124
	v_exp_f32_e32 v124, v124
	s_waitcnt lgkmcnt(0)
	ds_read_u16 v174, v148
	ds_read_u16 v175, v148 offset:9216
	v_add_f32_e32 v125, v125, v145
	v_add_f32_e32 v124, 1.0, v124
	v_rcp_f32_e32 v124, v124
	s_waitcnt lgkmcnt(1)
	v_lshlrev_b32_e32 v174, 16, v174
	s_waitcnt lgkmcnt(0)
	v_lshlrev_b32_e32 v175, 16, v175
	v_mul_f32_e32 v125, 0xbfb8aa3b, v125
	v_mul_f32_e32 v124, v124, v174
	v_mul_f32_e32 v124, v124, v175
	v_exp_f32_e32 v125, v125
	v_cvt_pk_bf16_f32 v124, v124, s0
	ds_write_b16 v148, v124 offset:9216
	ds_read_u16 v124, v147 offset:144
	v_add_f32_e32 v125, 1.0, v125
	ds_read_u16 v174, v147 offset:9360
	v_rcp_f32_e32 v125, v125
	v_add_f32_e32 v120, v120, v144
	s_waitcnt lgkmcnt(1)
	v_lshlrev_b32_e32 v124, 16, v124
	v_mul_f32_e32 v120, 0xbfb8aa3b, v120
	v_mul_f32_e32 v124, v125, v124
	s_waitcnt lgkmcnt(0)
	v_lshlrev_b32_e32 v125, 16, v174
	v_mul_f32_e32 v124, v124, v125
	v_add_f32_e32 v125, v126, v145
	v_mul_f32_e32 v125, 0xbfb8aa3b, v125
	v_exp_f32_e32 v125, v125
	v_cvt_pk_bf16_f32 v124, v124, s0
	ds_write_b16 v147, v124 offset:9360
	ds_read_u16 v124, v149
	v_add_f32_e32 v125, 1.0, v125
	ds_read_u16 v126, v149 offset:9216
	v_rcp_f32_e32 v125, v125
	v_exp_f32_e32 v120, v120
	s_waitcnt lgkmcnt(1)
	v_lshlrev_b32_e32 v124, 16, v124
	v_add_f32_e32 v121, v121, v144
	v_mul_f32_e32 v124, v125, v124
	s_waitcnt lgkmcnt(0)
	v_lshlrev_b32_e32 v125, 16, v126
	v_mul_f32_e32 v124, v124, v125
	v_add_f32_e32 v125, v127, v145
	v_mul_f32_e32 v125, 0xbfb8aa3b, v125
	v_exp_f32_e32 v125, v125
	v_cvt_pk_bf16_f32 v124, v124, s0
	ds_write_b16 v149, v124 offset:9216
	ds_read_u16 v124, v151
	v_add_f32_e32 v125, 1.0, v125
	v_rcp_f32_e32 v125, v125
	ds_read_u16 v126, v151 offset:9216
	ds_read_u16 v127, v152 offset:32
	ds_read_u16 v174, v152 offset:9248
	v_add_f32_e32 v120, 1.0, v120
	s_waitcnt lgkmcnt(3)
	v_lshlrev_b32_e32 v124, 16, v124
	v_mul_f32_e32 v124, v125, v124
	s_waitcnt lgkmcnt(2)
	v_lshlrev_b32_e32 v125, 16, v126
	v_rcp_f32_e32 v120, v120
	v_mul_f32_e32 v124, v124, v125
	v_cvt_pk_bf16_f32 v124, v124, s0
	ds_write_b16 v151, v124 offset:9216
	s_waitcnt lgkmcnt(2)
	v_lshlrev_b32_e32 v124, 16, v127
	v_mul_f32_e32 v120, v120, v124
	s_waitcnt lgkmcnt(1)
	v_lshlrev_b32_e32 v124, 16, v174
	v_mul_f32_e32 v121, 0xbfb8aa3b, v121
	v_mul_f32_e32 v120, v120, v124
	v_exp_f32_e32 v121, v121
	v_cvt_pk_bf16_f32 v120, v120, s0
	ds_write_b16 v152, v120 offset:9248
	ds_read_u16 v120, v147 offset:176
	v_add_f32_e32 v121, 1.0, v121
	ds_read_u16 v124, v147 offset:9392
	v_rcp_f32_e32 v121, v121
	v_add_f32_e32 v122, v122, v144
	v_mul_f32_e32 v122, 0xbfb8aa3b, v122
	s_waitcnt lgkmcnt(1)
	v_lshlrev_b32_e32 v120, 16, v120
	v_exp_f32_e32 v122, v122
	v_mul_f32_e32 v120, v121, v120
	s_waitcnt lgkmcnt(0)
	v_lshlrev_b32_e32 v121, 16, v124
	v_mul_f32_e32 v120, v120, v121
	v_cvt_pk_bf16_f32 v120, v120, s0
	ds_write_b16 v147, v120 offset:9392
	v_add_f32_e32 v120, 1.0, v122
	v_rcp_f32_e32 v120, v120
	ds_read_u16 v121, v150 offset:32
	ds_read_u16 v122, v150 offset:9248
	ds_read_u16 v124, v151 offset:32
	ds_read_u16 v125, v151 offset:9248
	ds_read_u16 v126, v152 offset:64
	ds_read_u16 v127, v152 offset:9280
	s_waitcnt lgkmcnt(5)
	v_lshlrev_b32_e32 v121, 16, v121
	v_add_f32_e32 v116, v116, v143
	v_mul_f32_e32 v120, v120, v121
	s_waitcnt lgkmcnt(4)
	v_lshlrev_b32_e32 v121, 16, v122
	v_mul_f32_e32 v120, v120, v121
	v_add_f32_e32 v121, v123, v144
	v_mul_f32_e32 v121, 0xbfb8aa3b, v121
	v_exp_f32_e32 v121, v121
	v_mul_f32_e32 v116, 0xbfb8aa3b, v116
	v_exp_f32_e32 v116, v116
	v_cvt_pk_bf16_f32 v120, v120, s0
	v_add_f32_e32 v121, 1.0, v121
	v_rcp_f32_e32 v121, v121
	ds_write_b16 v150, v120 offset:9248
	s_waitcnt lgkmcnt(4)
	v_lshlrev_b32_e32 v120, 16, v124
	v_add_f32_e32 v116, 1.0, v116
	v_mul_f32_e32 v120, v121, v120
	s_waitcnt lgkmcnt(3)
	v_lshlrev_b32_e32 v121, 16, v125
	v_rcp_f32_e32 v116, v116
	v_mul_f32_e32 v120, v120, v121
	v_cvt_pk_bf16_f32 v120, v120, s0
	ds_write_b16 v151, v120 offset:9248
	s_waitcnt lgkmcnt(3)
	v_lshlrev_b32_e32 v120, 16, v126
	v_add_f32_e32 v117, v117, v143
	v_mul_f32_e32 v116, v116, v120
	s_waitcnt lgkmcnt(2)
	v_lshlrev_b32_e32 v120, 16, v127
	v_mul_f32_e32 v117, 0xbfb8aa3b, v117
	v_mul_f32_e32 v116, v116, v120
	v_exp_f32_e32 v117, v117
	v_cvt_pk_bf16_f32 v116, v116, s0
	ds_write_b16 v152, v116 offset:9280
	ds_read_u16 v116, v147 offset:208
	v_add_f32_e32 v117, 1.0, v117
	ds_read_u16 v120, v147 offset:9424
	v_rcp_f32_e32 v117, v117
	v_add_f32_e32 v118, v118, v143
	v_mul_f32_e32 v118, 0xbfb8aa3b, v118
	s_waitcnt lgkmcnt(1)
	v_lshlrev_b32_e32 v116, 16, v116
	v_exp_f32_e32 v118, v118
	v_mul_f32_e32 v116, v117, v116
	s_waitcnt lgkmcnt(0)
	v_lshlrev_b32_e32 v117, 16, v120
	v_mul_f32_e32 v116, v116, v117
	v_cvt_pk_bf16_f32 v116, v116, s0
	ds_write_b16 v147, v116 offset:9424
	v_add_f32_e32 v116, 1.0, v118
	v_rcp_f32_e32 v116, v116
	ds_read_u16 v117, v150 offset:64
	ds_read_u16 v118, v150 offset:9280
	ds_read_u16 v120, v151 offset:64
	ds_read_u16 v121, v151 offset:9280
	ds_read_u16 v122, v152 offset:96
	ds_read_u16 v123, v152 offset:9312
	s_waitcnt lgkmcnt(5)
	v_lshlrev_b32_e32 v117, 16, v117
	v_add_f32_e32 v112, v112, v142
	v_mul_f32_e32 v116, v116, v117
	s_waitcnt lgkmcnt(4)
	v_lshlrev_b32_e32 v117, 16, v118
	v_mul_f32_e32 v116, v116, v117
	v_add_f32_e32 v117, v119, v143
	v_mul_f32_e32 v117, 0xbfb8aa3b, v117
	v_exp_f32_e32 v117, v117
	v_mul_f32_e32 v112, 0xbfb8aa3b, v112
	v_exp_f32_e32 v112, v112
	v_cvt_pk_bf16_f32 v116, v116, s0
	v_add_f32_e32 v117, 1.0, v117
	v_rcp_f32_e32 v117, v117
	ds_write_b16 v150, v116 offset:9280
	s_waitcnt lgkmcnt(4)
	v_lshlrev_b32_e32 v116, 16, v120
	v_add_f32_e32 v112, 1.0, v112
	v_mul_f32_e32 v116, v117, v116
	s_waitcnt lgkmcnt(3)
	v_lshlrev_b32_e32 v117, 16, v121
	v_rcp_f32_e32 v112, v112
	v_mul_f32_e32 v116, v116, v117
	v_cvt_pk_bf16_f32 v116, v116, s0
	ds_write_b16 v151, v116 offset:9280
	s_waitcnt lgkmcnt(3)
	v_lshlrev_b32_e32 v116, 16, v122
	v_add_f32_e32 v113, v113, v142
	v_mul_f32_e32 v112, v112, v116
	s_waitcnt lgkmcnt(2)
	v_lshlrev_b32_e32 v116, 16, v123
	v_mul_f32_e32 v113, 0xbfb8aa3b, v113
	v_mul_f32_e32 v112, v112, v116
	v_exp_f32_e32 v113, v113
	v_cvt_pk_bf16_f32 v112, v112, s0
	ds_write_b16 v152, v112 offset:9312
	ds_read_u16 v112, v147 offset:240
	v_add_f32_e32 v113, 1.0, v113
	ds_read_u16 v116, v147 offset:9456
	v_rcp_f32_e32 v113, v113
	v_add_f32_e32 v115, v115, v142
	s_waitcnt lgkmcnt(1)
	v_lshlrev_b32_e32 v112, 16, v112
	v_mul_f32_e32 v115, 0xbfb8aa3b, v115
	v_mul_f32_e32 v112, v113, v112
	s_waitcnt lgkmcnt(0)
	v_lshlrev_b32_e32 v113, 16, v116
	v_mul_f32_e32 v112, v112, v113
	v_add_f32_e32 v113, v114, v142
	v_mul_f32_e32 v113, 0xbfb8aa3b, v113
	v_exp_f32_e32 v113, v113
	v_cvt_pk_bf16_f32 v112, v112, s0
	ds_write_b16 v147, v112 offset:9456
	ds_read_u16 v112, v150 offset:96
	v_add_f32_e32 v113, 1.0, v113
	v_rcp_f32_e32 v113, v113
	ds_read_u16 v114, v150 offset:9312
	ds_read_u16 v116, v151 offset:96
	ds_read_u16 v117, v151 offset:9312
	v_exp_f32_e32 v115, v115
	s_waitcnt lgkmcnt(3)
	v_lshlrev_b32_e32 v112, 16, v112
	v_mul_f32_e32 v112, v113, v112
	s_waitcnt lgkmcnt(2)
	v_lshlrev_b32_e32 v113, 16, v114
	v_mul_f32_e32 v112, v112, v113
	v_add_f32_e32 v113, 1.0, v115
	v_rcp_f32_e32 v113, v113
	v_cvt_pk_bf16_f32 v112, v112, s0
	ds_write_b16 v150, v112 offset:9312
	s_waitcnt lgkmcnt(2)
	v_lshlrev_b32_e32 v112, 16, v116
	v_add_f32_e32 v108, v108, v145
	v_mul_f32_e32 v112, v113, v112
	s_waitcnt lgkmcnt(1)
	v_lshlrev_b32_e32 v113, 16, v117
	v_mul_f32_e32 v108, 0xbfb8aa3b, v108
	v_mul_f32_e32 v112, v112, v113
	v_exp_f32_e32 v108, v108
	v_cvt_pk_bf16_f32 v112, v112, s0
	ds_write_b16 v151, v112 offset:9312
	ds_read_u16 v112, v153
	v_add_f32_e32 v108, 1.0, v108
	ds_read_u16 v113, v153 offset:9216
	v_rcp_f32_e32 v108, v108
	v_add_f32_e32 v109, v109, v145
	s_waitcnt lgkmcnt(1)
	v_lshlrev_b32_e32 v112, 16, v112
	v_mul_f32_e32 v109, 0xbfb8aa3b, v109
	v_mul_f32_e32 v108, v108, v112
	s_waitcnt lgkmcnt(0)
	v_lshlrev_b32_e32 v112, 16, v113
	v_mul_f32_e32 v108, v108, v112
	v_exp_f32_e32 v109, v109
	v_cvt_pk_bf16_f32 v108, v108, s0
	ds_write_b16 v153, v108 offset:9216
	ds_read_u16 v108, v155
	v_add_f32_e32 v109, 1.0, v109
	ds_read_u16 v112, v155 offset:9216
	v_rcp_f32_e32 v109, v109
	v_add_f32_e32 v104, v104, v144
	s_waitcnt lgkmcnt(1)
	v_lshlrev_b32_e32 v108, 16, v108
	v_mul_f32_e32 v104, 0xbfb8aa3b, v104
	v_mul_f32_e32 v108, v109, v108
	s_waitcnt lgkmcnt(0)
	v_lshlrev_b32_e32 v109, 16, v112
	v_mul_f32_e32 v108, v108, v109
	v_add_f32_e32 v109, v110, v145
	v_mul_f32_e32 v109, 0xbfb8aa3b, v109
	v_exp_f32_e32 v109, v109
	v_cvt_pk_bf16_f32 v108, v108, s0
	ds_write_b16 v155, v108 offset:9216
	ds_read_u16 v108, v156
	v_add_f32_e32 v109, 1.0, v109
	ds_read_u16 v110, v156 offset:9216
	v_rcp_f32_e32 v109, v109
	v_exp_f32_e32 v104, v104
	s_waitcnt lgkmcnt(1)
	v_lshlrev_b32_e32 v108, 16, v108
	v_add_f32_e32 v106, v106, v144
	v_mul_f32_e32 v108, v109, v108
	s_waitcnt lgkmcnt(0)
	v_lshlrev_b32_e32 v109, 16, v110
	v_mul_f32_e32 v108, v108, v109
	v_add_f32_e32 v109, v111, v145
	v_mul_f32_e32 v109, 0xbfb8aa3b, v109
	v_exp_f32_e32 v109, v109
	v_cvt_pk_bf16_f32 v108, v108, s0
	ds_write_b16 v156, v108 offset:9216
	ds_read_u16 v108, v158
	v_add_f32_e32 v109, 1.0, v109
	v_rcp_f32_e32 v109, v109
	ds_read_u16 v110, v158 offset:32
	ds_read_u16 v111, v155 offset:9312
	v_add_f32_e32 v104, 1.0, v104
	s_waitcnt lgkmcnt(2)
	v_lshlrev_b32_e32 v108, 16, v108
	v_mul_f32_e32 v108, v109, v108
	ds_read_u16 v109, v158 offset:9216
	ds_read_u16 v112, v154 offset:32
	ds_read_u16 v113, v154 offset:64
	ds_read_u16 v114, v158 offset:9248
	ds_read_u16 v115, v158 offset:64
	ds_read_u16 v116, v158 offset:9280
	ds_read_u16 v117, v158 offset:9312
	ds_read_u16 v118, v158 offset:96
	s_waitcnt lgkmcnt(7)
	v_lshlrev_b32_e32 v109, 16, v109
	v_rcp_f32_e32 v104, v104
	v_mul_f32_e32 v108, v108, v109
	v_cvt_pk_bf16_f32 v108, v108, s0
	ds_write_b16 v158, v108 offset:9216
	s_waitcnt lgkmcnt(7)
	v_lshlrev_b32_e32 v108, 16, v112
	v_mul_f32_e32 v104, v104, v108
	ds_read_u16 v108, v154 offset:9248
	ds_read_u16 v109, v157 offset:32
	ds_read_u16 v112, v157 offset:9248
	ds_read_u16 v119, v154 offset:9280
	ds_read_u16 v120, v157 offset:64
	ds_read_u16 v121, v157 offset:96
	ds_read_u16 v122, v154 offset:9312
	ds_read_u16 v123, v154 offset:96
	s_waitcnt lgkmcnt(7)
	v_lshlrev_b32_e32 v108, 16, v108
	v_mul_f32_e32 v104, v104, v108
	v_cvt_pk_bf16_f32 v104, v104, s0
	ds_write_b16 v154, v104 offset:9248
	v_add_f32_e32 v104, v105, v144
	v_mul_f32_e32 v104, 0xbfb8aa3b, v104
	v_exp_f32_e32 v104, v104
	v_mul_f32_e32 v106, 0xbfb8aa3b, v106
	v_exp_f32_e32 v106, v106
	ds_read_u16 v105, v155 offset:32
	ds_read_u16 v108, v155 offset:9248
	ds_read_u16 v124, v155 offset:9280
	ds_read_u16 v125, v155 offset:64
	ds_read_u16 v126, v155 offset:96
	v_add_f32_e32 v104, 1.0, v104
	v_rcp_f32_e32 v104, v104
	s_waitcnt lgkmcnt(4)
	v_lshlrev_b32_e32 v105, 16, v105
	v_add_f32_e32 v100, v100, v143
	v_mul_f32_e32 v100, 0xbfb8aa3b, v100
	v_mul_f32_e32 v104, v104, v105
	s_waitcnt lgkmcnt(3)
	v_lshlrev_b32_e32 v105, 16, v108
	v_mul_f32_e32 v104, v104, v105
	v_add_f32_e32 v105, 1.0, v106
	v_rcp_f32_e32 v105, v105
	v_cvt_pk_bf16_f32 v104, v104, s0
	ds_write_b16 v155, v104 offset:9248
	v_lshlrev_b32_e32 v104, 16, v109
	v_mul_f32_e32 v104, v105, v104
	v_lshlrev_b32_e32 v105, 16, v112
	v_mul_f32_e32 v104, v104, v105
	v_add_f32_e32 v105, v107, v144
	v_mul_f32_e32 v105, 0xbfb8aa3b, v105
	v_exp_f32_e32 v105, v105
	v_exp_f32_e32 v100, v100
	v_add_f32_e32 v101, v101, v143
	v_cvt_pk_bf16_f32 v104, v104, s0
	v_add_f32_e32 v105, 1.0, v105
	v_rcp_f32_e32 v105, v105
	v_mul_f32_e32 v101, 0xbfb8aa3b, v101
	ds_write_b16 v157, v104 offset:9248
	v_lshlrev_b32_e32 v104, 16, v110
	v_add_f32_e32 v100, 1.0, v100
	v_exp_f32_e32 v101, v101
	v_mul_f32_e32 v104, v105, v104
	v_lshlrev_b32_e32 v105, 16, v114
	v_rcp_f32_e32 v100, v100
	v_mul_f32_e32 v104, v104, v105
	v_cvt_pk_bf16_f32 v104, v104, s0
	ds_write_b16 v158, v104 offset:9248
	v_lshlrev_b32_e32 v104, 16, v113
	v_add_f32_e32 v101, 1.0, v101
	v_add_f32_e32 v102, v102, v143
	v_mul_f32_e32 v100, v100, v104
	v_lshlrev_b32_e32 v104, 16, v119
	v_rcp_f32_e32 v101, v101
	v_mul_f32_e32 v102, 0xbfb8aa3b, v102
	v_mul_f32_e32 v100, v100, v104
	v_exp_f32_e32 v102, v102
	v_cvt_pk_bf16_f32 v100, v100, s0
	ds_write_b16 v154, v100 offset:9280
	s_waitcnt lgkmcnt(5)
	v_lshlrev_b32_e32 v100, 16, v125
	v_mul_f32_e32 v100, v101, v100
	v_lshlrev_b32_e32 v101, 16, v124
	v_mul_f32_e32 v100, v100, v101
	v_add_f32_e32 v101, 1.0, v102
	v_rcp_f32_e32 v101, v101
	v_cvt_pk_bf16_f32 v100, v100, s0
	ds_write_b16 v155, v100 offset:9280
	v_lshlrev_b32_e32 v100, 16, v120
	v_mul_f32_e32 v100, v101, v100
	ds_read_u16 v101, v157 offset:9280
	v_add_f32_e32 v102, v103, v143
	v_mul_f32_e32 v102, 0xbfb8aa3b, v102
	v_exp_f32_e32 v102, v102
	v_add_f32_e32 v96, v96, v142
	s_waitcnt lgkmcnt(0)
	v_lshlrev_b32_e32 v101, 16, v101
	v_mul_f32_e32 v96, 0xbfb8aa3b, v96
	v_mul_f32_e32 v100, v100, v101
	v_add_f32_e32 v101, 1.0, v102
	v_exp_f32_e32 v96, v96
	v_rcp_f32_e32 v101, v101
	v_add_f32_e32 v97, v97, v142
	v_cvt_pk_bf16_f32 v100, v100, s0
	v_mul_f32_e32 v97, 0xbfb8aa3b, v97
	ds_write_b16 v157, v100 offset:9280
	v_lshlrev_b32_e32 v100, 16, v115
	v_add_f32_e32 v96, 1.0, v96
	v_exp_f32_e32 v97, v97
	v_mul_f32_e32 v100, v101, v100
	v_lshlrev_b32_e32 v101, 16, v116
	v_rcp_f32_e32 v96, v96
	v_mul_f32_e32 v100, v100, v101
	v_cvt_pk_bf16_f32 v100, v100, s0
	ds_write_b16 v158, v100 offset:9280
	v_lshlrev_b32_e32 v100, 16, v123
	v_add_f32_e32 v97, 1.0, v97
	v_mul_f32_e32 v96, v96, v100
	v_lshlrev_b32_e32 v100, 16, v122
	v_rcp_f32_e32 v97, v97
	v_mul_f32_e32 v96, v96, v100
	v_cvt_pk_bf16_f32 v96, v96, s0
	ds_write_b16 v154, v96 offset:9312
	v_lshlrev_b32_e32 v96, 16, v126
	v_mul_f32_e32 v96, v97, v96
	v_lshlrev_b32_e32 v97, 16, v111
	v_mul_f32_e32 v96, v96, v97
	v_add_f32_e32 v97, v98, v142
	v_mul_f32_e32 v97, 0xbfb8aa3b, v97
	v_exp_f32_e32 v97, v97
	ds_read_u16 v103, v157 offset:9312
	v_add_f32_e32 v98, v99, v142
	v_mul_f32_e32 v98, 0xbfb8aa3b, v98
	v_add_f32_e32 v97, 1.0, v97
	v_rcp_f32_e32 v97, v97
	v_exp_f32_e32 v98, v98
	v_cvt_pk_bf16_f32 v96, v96, s0
	ds_write_b16 v155, v96 offset:9312
	v_lshlrev_b32_e32 v96, 16, v121
	v_mul_f32_e32 v96, v97, v96
	s_waitcnt lgkmcnt(1)
	v_lshlrev_b32_e32 v97, 16, v103
	v_mul_f32_e32 v96, v96, v97
	v_add_f32_e32 v97, 1.0, v98
	v_rcp_f32_e32 v97, v97
	v_cvt_pk_bf16_f32 v96, v96, s0
	ds_write_b16 v157, v96 offset:9312
	v_lshlrev_b32_e32 v96, 16, v118
	v_add_f32_e32 v92, v92, v145
	v_mul_f32_e32 v96, v97, v96
	v_lshlrev_b32_e32 v97, 16, v117
	v_mul_f32_e32 v92, 0xbfb8aa3b, v92
	v_mul_f32_e32 v96, v96, v97
	v_exp_f32_e32 v92, v92
	v_cvt_pk_bf16_f32 v96, v96, s0
	ds_write_b16 v158, v96 offset:9312
	ds_read_u16 v96, v159
	v_add_f32_e32 v92, 1.0, v92
	ds_read_u16 v97, v159 offset:9216
	v_rcp_f32_e32 v92, v92
	v_add_f32_e32 v93, v93, v145
	s_waitcnt lgkmcnt(1)
	v_lshlrev_b32_e32 v96, 16, v96
	v_mul_f32_e32 v93, 0xbfb8aa3b, v93
	v_mul_f32_e32 v92, v92, v96
	s_waitcnt lgkmcnt(0)
	v_lshlrev_b32_e32 v96, 16, v97
	v_mul_f32_e32 v92, v92, v96
	v_exp_f32_e32 v93, v93
	v_cvt_pk_bf16_f32 v92, v92, s0
	ds_write_b16 v159, v92 offset:9216
	ds_read_u16 v92, v161
	v_add_f32_e32 v93, 1.0, v93
	ds_read_u16 v96, v161 offset:9216
	v_rcp_f32_e32 v93, v93
	v_add_f32_e32 v88, v88, v144
	s_waitcnt lgkmcnt(1)
	v_lshlrev_b32_e32 v92, 16, v92
	v_mul_f32_e32 v88, 0xbfb8aa3b, v88
	v_mul_f32_e32 v92, v93, v92
	s_waitcnt lgkmcnt(0)
	v_lshlrev_b32_e32 v93, 16, v96
	v_mul_f32_e32 v92, v92, v93
	v_add_f32_e32 v93, v94, v145
	v_mul_f32_e32 v93, 0xbfb8aa3b, v93
	v_exp_f32_e32 v93, v93
	v_cvt_pk_bf16_f32 v92, v92, s0
	ds_write_b16 v161, v92 offset:9216
	ds_read_u16 v92, v162
	v_add_f32_e32 v93, 1.0, v93
	ds_read_u16 v94, v162 offset:9216
	v_rcp_f32_e32 v93, v93
	v_exp_f32_e32 v88, v88
	s_waitcnt lgkmcnt(1)
	v_lshlrev_b32_e32 v92, 16, v92
	v_add_f32_e32 v90, v90, v144
	v_mul_f32_e32 v92, v93, v92
	s_waitcnt lgkmcnt(0)
	v_lshlrev_b32_e32 v93, 16, v94
	v_mul_f32_e32 v92, v92, v93
	v_add_f32_e32 v93, v95, v145
	v_mul_f32_e32 v93, 0xbfb8aa3b, v93
	v_exp_f32_e32 v93, v93
	v_cvt_pk_bf16_f32 v92, v92, s0
	ds_write_b16 v162, v92 offset:9216
	ds_read_u16 v92, v164
	v_add_f32_e32 v93, 1.0, v93
	v_rcp_f32_e32 v93, v93
	ds_read_u16 v94, v164 offset:32
	ds_read_u16 v95, v161 offset:9312
	v_add_f32_e32 v88, 1.0, v88
	s_waitcnt lgkmcnt(2)
	v_lshlrev_b32_e32 v92, 16, v92
	v_mul_f32_e32 v92, v93, v92
	ds_read_u16 v93, v164 offset:9216
	ds_read_u16 v96, v160 offset:32
	ds_read_u16 v97, v160 offset:64
	ds_read_u16 v98, v164 offset:9248
	ds_read_u16 v99, v164 offset:64
	ds_read_u16 v100, v164 offset:9280
	ds_read_u16 v101, v164 offset:9312
	ds_read_u16 v102, v164 offset:96
	s_waitcnt lgkmcnt(7)
	v_lshlrev_b32_e32 v93, 16, v93
	v_rcp_f32_e32 v88, v88
	v_mul_f32_e32 v92, v92, v93
	v_cvt_pk_bf16_f32 v92, v92, s0
	ds_write_b16 v164, v92 offset:9216
	s_waitcnt lgkmcnt(7)
	v_lshlrev_b32_e32 v92, 16, v96
	v_mul_f32_e32 v88, v88, v92
	ds_read_u16 v92, v160 offset:9248
	ds_read_u16 v93, v163 offset:32
	ds_read_u16 v96, v163 offset:9248
	ds_read_u16 v103, v160 offset:9280
	ds_read_u16 v104, v163 offset:64
	ds_read_u16 v105, v163 offset:96
	ds_read_u16 v106, v160 offset:9312
	ds_read_u16 v107, v160 offset:96
	s_waitcnt lgkmcnt(7)
	v_lshlrev_b32_e32 v92, 16, v92
	v_mul_f32_e32 v88, v88, v92
	v_cvt_pk_bf16_f32 v88, v88, s0
	ds_write_b16 v160, v88 offset:9248
	v_add_f32_e32 v88, v89, v144
	v_mul_f32_e32 v88, 0xbfb8aa3b, v88
	v_exp_f32_e32 v88, v88
	v_mul_f32_e32 v90, 0xbfb8aa3b, v90
	v_exp_f32_e32 v90, v90
	ds_read_u16 v89, v161 offset:32
	ds_read_u16 v92, v161 offset:9248
	ds_read_u16 v108, v161 offset:9280
	ds_read_u16 v109, v161 offset:64
	ds_read_u16 v110, v161 offset:96
	v_add_f32_e32 v88, 1.0, v88
	v_rcp_f32_e32 v88, v88
	s_waitcnt lgkmcnt(4)
	v_lshlrev_b32_e32 v89, 16, v89
	v_add_f32_e32 v84, v84, v143
	v_mul_f32_e32 v84, 0xbfb8aa3b, v84
	v_mul_f32_e32 v88, v88, v89
	s_waitcnt lgkmcnt(3)
	v_lshlrev_b32_e32 v89, 16, v92
	v_mul_f32_e32 v88, v88, v89
	v_add_f32_e32 v89, 1.0, v90
	v_rcp_f32_e32 v89, v89
	v_cvt_pk_bf16_f32 v88, v88, s0
	ds_write_b16 v161, v88 offset:9248
	v_lshlrev_b32_e32 v88, 16, v93
	v_mul_f32_e32 v88, v89, v88
	v_lshlrev_b32_e32 v89, 16, v96
	v_mul_f32_e32 v88, v88, v89
	v_add_f32_e32 v89, v91, v144
	v_mul_f32_e32 v89, 0xbfb8aa3b, v89
	v_exp_f32_e32 v89, v89
	v_exp_f32_e32 v84, v84
	v_add_f32_e32 v85, v85, v143
	v_cvt_pk_bf16_f32 v88, v88, s0
	v_add_f32_e32 v89, 1.0, v89
	v_rcp_f32_e32 v89, v89
	v_mul_f32_e32 v85, 0xbfb8aa3b, v85
	ds_write_b16 v163, v88 offset:9248
	v_lshlrev_b32_e32 v88, 16, v94
	v_add_f32_e32 v84, 1.0, v84
	v_exp_f32_e32 v85, v85
	v_mul_f32_e32 v88, v89, v88
	v_lshlrev_b32_e32 v89, 16, v98
	v_rcp_f32_e32 v84, v84
	v_mul_f32_e32 v88, v88, v89
	v_cvt_pk_bf16_f32 v88, v88, s0
	ds_write_b16 v164, v88 offset:9248
	v_lshlrev_b32_e32 v88, 16, v97
	v_add_f32_e32 v85, 1.0, v85
	v_add_f32_e32 v86, v86, v143
	v_mul_f32_e32 v84, v84, v88
	v_lshlrev_b32_e32 v88, 16, v103
	v_rcp_f32_e32 v85, v85
	v_mul_f32_e32 v86, 0xbfb8aa3b, v86
	v_mul_f32_e32 v84, v84, v88
	v_exp_f32_e32 v86, v86
	v_cvt_pk_bf16_f32 v84, v84, s0
	ds_write_b16 v160, v84 offset:9280
	s_waitcnt lgkmcnt(5)
	v_lshlrev_b32_e32 v84, 16, v109
	v_mul_f32_e32 v84, v85, v84
	v_lshlrev_b32_e32 v85, 16, v108
	v_mul_f32_e32 v84, v84, v85
	v_add_f32_e32 v85, 1.0, v86
	v_rcp_f32_e32 v85, v85
	v_cvt_pk_bf16_f32 v84, v84, s0
	ds_write_b16 v161, v84 offset:9280
	v_lshlrev_b32_e32 v84, 16, v104
	v_mul_f32_e32 v84, v85, v84
	ds_read_u16 v85, v163 offset:9280
	v_add_f32_e32 v86, v87, v143
	v_mul_f32_e32 v86, 0xbfb8aa3b, v86
	v_exp_f32_e32 v86, v86
	v_add_f32_e32 v80, v80, v142
	s_waitcnt lgkmcnt(0)
	v_lshlrev_b32_e32 v85, 16, v85
	v_mul_f32_e32 v80, 0xbfb8aa3b, v80
	v_mul_f32_e32 v84, v84, v85
	v_add_f32_e32 v85, 1.0, v86
	v_exp_f32_e32 v80, v80
	v_rcp_f32_e32 v85, v85
	v_add_f32_e32 v81, v81, v142
	v_cvt_pk_bf16_f32 v84, v84, s0
	v_mul_f32_e32 v81, 0xbfb8aa3b, v81
	ds_write_b16 v163, v84 offset:9280
	v_lshlrev_b32_e32 v84, 16, v99
	v_add_f32_e32 v80, 1.0, v80
	v_exp_f32_e32 v81, v81
	v_mul_f32_e32 v84, v85, v84
	v_lshlrev_b32_e32 v85, 16, v100
	v_rcp_f32_e32 v80, v80
	v_mul_f32_e32 v84, v84, v85
	v_cvt_pk_bf16_f32 v84, v84, s0
	ds_write_b16 v164, v84 offset:9280
	v_lshlrev_b32_e32 v84, 16, v107
	v_add_f32_e32 v81, 1.0, v81
	v_mul_f32_e32 v80, v80, v84
	v_lshlrev_b32_e32 v84, 16, v106
	v_rcp_f32_e32 v81, v81
	v_mul_f32_e32 v80, v80, v84
	v_cvt_pk_bf16_f32 v80, v80, s0
	ds_write_b16 v160, v80 offset:9312
	v_lshlrev_b32_e32 v80, 16, v110
	v_mul_f32_e32 v80, v81, v80
	v_lshlrev_b32_e32 v81, 16, v95
	v_mul_f32_e32 v80, v80, v81
	v_add_f32_e32 v81, v82, v142
	v_mul_f32_e32 v81, 0xbfb8aa3b, v81
	v_exp_f32_e32 v81, v81
	ds_read_u16 v87, v163 offset:9312
	v_add_f32_e32 v82, v83, v142
	v_mul_f32_e32 v82, 0xbfb8aa3b, v82
	v_add_f32_e32 v81, 1.0, v81
	v_rcp_f32_e32 v81, v81
	v_exp_f32_e32 v82, v82
	v_cvt_pk_bf16_f32 v80, v80, s0
	ds_write_b16 v161, v80 offset:9312
	v_lshlrev_b32_e32 v80, 16, v105
	v_mul_f32_e32 v80, v81, v80
	s_waitcnt lgkmcnt(1)
	v_lshlrev_b32_e32 v81, 16, v87
	v_mul_f32_e32 v80, v80, v81
	v_add_f32_e32 v81, 1.0, v82
	v_rcp_f32_e32 v81, v81
	v_cvt_pk_bf16_f32 v80, v80, s0
	ds_write_b16 v163, v80 offset:9312
	v_lshlrev_b32_e32 v80, 16, v102
	v_add_f32_e32 v76, v76, v145
	v_mul_f32_e32 v80, v81, v80
	v_lshlrev_b32_e32 v81, 16, v101
	v_mul_f32_e32 v76, 0xbfb8aa3b, v76
	v_mul_f32_e32 v80, v80, v81
	v_exp_f32_e32 v76, v76
	v_cvt_pk_bf16_f32 v80, v80, s0
	ds_write_b16 v164, v80 offset:9312
	ds_read_u16 v80, v165
	v_add_f32_e32 v76, 1.0, v76
	ds_read_u16 v81, v165 offset:9216
	v_rcp_f32_e32 v76, v76
	v_add_f32_e32 v77, v77, v145
	s_waitcnt lgkmcnt(1)
	v_lshlrev_b32_e32 v80, 16, v80
	v_mul_f32_e32 v77, 0xbfb8aa3b, v77
	v_mul_f32_e32 v76, v76, v80
	s_waitcnt lgkmcnt(0)
	v_lshlrev_b32_e32 v80, 16, v81
	v_mul_f32_e32 v76, v76, v80
	v_exp_f32_e32 v77, v77
	v_cvt_pk_bf16_f32 v76, v76, s0
	ds_write_b16 v165, v76 offset:9216
	ds_read_u16 v76, v167
	v_add_f32_e32 v77, 1.0, v77
	ds_read_u16 v80, v167 offset:9216
	v_rcp_f32_e32 v77, v77
	v_add_f32_e32 v72, v72, v144
	s_waitcnt lgkmcnt(1)
	v_lshlrev_b32_e32 v76, 16, v76
	v_mul_f32_e32 v72, 0xbfb8aa3b, v72
	v_mul_f32_e32 v76, v77, v76
	s_waitcnt lgkmcnt(0)
	v_lshlrev_b32_e32 v77, 16, v80
	v_mul_f32_e32 v76, v76, v77
	v_add_f32_e32 v77, v78, v145
	v_mul_f32_e32 v77, 0xbfb8aa3b, v77
	v_exp_f32_e32 v77, v77
	v_cvt_pk_bf16_f32 v76, v76, s0
	ds_write_b16 v167, v76 offset:9216
	ds_read_u16 v76, v168
	v_add_f32_e32 v77, 1.0, v77
	ds_read_u16 v78, v168 offset:9216
	v_rcp_f32_e32 v77, v77
	v_exp_f32_e32 v72, v72
	s_waitcnt lgkmcnt(1)
	v_lshlrev_b32_e32 v76, 16, v76
	v_add_f32_e32 v74, v74, v144
	v_mul_f32_e32 v76, v77, v76
	s_waitcnt lgkmcnt(0)
	v_lshlrev_b32_e32 v77, 16, v78
	v_mul_f32_e32 v76, v76, v77
	v_add_f32_e32 v77, v79, v145
	v_mul_f32_e32 v77, 0xbfb8aa3b, v77
	v_exp_f32_e32 v77, v77
	v_cvt_pk_bf16_f32 v76, v76, s0
	ds_write_b16 v168, v76 offset:9216
	ds_read_u16 v76, v170
	v_add_f32_e32 v77, 1.0, v77
	v_rcp_f32_e32 v77, v77
	ds_read_u16 v78, v170 offset:32
	ds_read_u16 v79, v167 offset:9312
	v_add_f32_e32 v72, 1.0, v72
	s_waitcnt lgkmcnt(2)
	v_lshlrev_b32_e32 v76, 16, v76
	v_mul_f32_e32 v76, v77, v76
	ds_read_u16 v77, v170 offset:9216
	ds_read_u16 v80, v166 offset:32
	ds_read_u16 v81, v166 offset:64
	ds_read_u16 v82, v170 offset:9248
	ds_read_u16 v83, v170 offset:64
	ds_read_u16 v84, v170 offset:9280
	ds_read_u16 v85, v170 offset:9312
	ds_read_u16 v86, v170 offset:96
	s_waitcnt lgkmcnt(7)
	v_lshlrev_b32_e32 v77, 16, v77
	v_rcp_f32_e32 v72, v72
	v_mul_f32_e32 v76, v76, v77
	v_cvt_pk_bf16_f32 v76, v76, s0
	ds_write_b16 v170, v76 offset:9216
	s_waitcnt lgkmcnt(7)
	v_lshlrev_b32_e32 v76, 16, v80
	v_mul_f32_e32 v72, v72, v76
	ds_read_u16 v76, v166 offset:9248
	ds_read_u16 v77, v169 offset:32
	ds_read_u16 v80, v169 offset:9248
	ds_read_u16 v87, v166 offset:9280
	ds_read_u16 v88, v169 offset:64
	ds_read_u16 v89, v169 offset:96
	ds_read_u16 v90, v166 offset:9312
	ds_read_u16 v91, v166 offset:96
	s_waitcnt lgkmcnt(7)
	v_lshlrev_b32_e32 v76, 16, v76
	v_mul_f32_e32 v72, v72, v76
	v_cvt_pk_bf16_f32 v72, v72, s0
	ds_write_b16 v166, v72 offset:9248
	v_add_f32_e32 v72, v73, v144
	v_mul_f32_e32 v72, 0xbfb8aa3b, v72
	v_exp_f32_e32 v72, v72
	v_mul_f32_e32 v74, 0xbfb8aa3b, v74
	v_exp_f32_e32 v74, v74
	ds_read_u16 v73, v167 offset:32
	ds_read_u16 v76, v167 offset:9248
	ds_read_u16 v92, v167 offset:9280
	ds_read_u16 v93, v167 offset:64
	ds_read_u16 v94, v167 offset:96
	v_add_f32_e32 v72, 1.0, v72
	v_rcp_f32_e32 v72, v72
	s_waitcnt lgkmcnt(4)
	v_lshlrev_b32_e32 v73, 16, v73
	v_add_f32_e32 v68, v68, v143
	v_mul_f32_e32 v68, 0xbfb8aa3b, v68
	v_mul_f32_e32 v72, v72, v73
	s_waitcnt lgkmcnt(3)
	v_lshlrev_b32_e32 v73, 16, v76
	v_mul_f32_e32 v72, v72, v73
	v_add_f32_e32 v73, 1.0, v74
	v_rcp_f32_e32 v73, v73
	v_cvt_pk_bf16_f32 v72, v72, s0
	ds_write_b16 v167, v72 offset:9248
	v_lshlrev_b32_e32 v72, 16, v77
	v_mul_f32_e32 v72, v73, v72
	v_lshlrev_b32_e32 v73, 16, v80
	v_mul_f32_e32 v72, v72, v73
	v_add_f32_e32 v73, v75, v144
	v_mul_f32_e32 v73, 0xbfb8aa3b, v73
	v_exp_f32_e32 v73, v73
	v_exp_f32_e32 v68, v68
	v_add_f32_e32 v69, v69, v143
	v_cvt_pk_bf16_f32 v72, v72, s0
	v_add_f32_e32 v73, 1.0, v73
	v_rcp_f32_e32 v73, v73
	v_mul_f32_e32 v69, 0xbfb8aa3b, v69
	ds_write_b16 v169, v72 offset:9248
	v_lshlrev_b32_e32 v72, 16, v78
	v_add_f32_e32 v68, 1.0, v68
	v_exp_f32_e32 v69, v69
	v_mul_f32_e32 v72, v73, v72
	v_lshlrev_b32_e32 v73, 16, v82
	v_rcp_f32_e32 v68, v68
	v_mul_f32_e32 v72, v72, v73
	v_cvt_pk_bf16_f32 v72, v72, s0
	ds_write_b16 v170, v72 offset:9248
	v_lshlrev_b32_e32 v72, 16, v81
	v_add_f32_e32 v69, 1.0, v69
	v_add_f32_e32 v70, v70, v143
	v_mul_f32_e32 v68, v68, v72
	v_lshlrev_b32_e32 v72, 16, v87
	v_rcp_f32_e32 v69, v69
	v_mul_f32_e32 v70, 0xbfb8aa3b, v70
	v_mul_f32_e32 v68, v68, v72
	v_exp_f32_e32 v70, v70
	v_cvt_pk_bf16_f32 v68, v68, s0
	ds_write_b16 v166, v68 offset:9280
	s_waitcnt lgkmcnt(5)
	v_lshlrev_b32_e32 v68, 16, v93
	v_mul_f32_e32 v68, v69, v68
	v_lshlrev_b32_e32 v69, 16, v92
	v_mul_f32_e32 v68, v68, v69
	v_add_f32_e32 v69, 1.0, v70
	v_rcp_f32_e32 v69, v69
	v_cvt_pk_bf16_f32 v68, v68, s0
	ds_write_b16 v167, v68 offset:9280
	v_lshlrev_b32_e32 v68, 16, v88
	v_mul_f32_e32 v68, v69, v68
	ds_read_u16 v69, v169 offset:9280
	v_add_f32_e32 v70, v71, v143
	v_mul_f32_e32 v70, 0xbfb8aa3b, v70
	v_exp_f32_e32 v70, v70
	v_add_f32_e32 v64, v64, v142
	s_waitcnt lgkmcnt(0)
	v_lshlrev_b32_e32 v69, 16, v69
	v_mul_f32_e32 v64, 0xbfb8aa3b, v64
	v_mul_f32_e32 v68, v68, v69
	v_add_f32_e32 v69, 1.0, v70
	v_exp_f32_e32 v64, v64
	v_rcp_f32_e32 v69, v69
	v_add_f32_e32 v65, v65, v142
	v_cvt_pk_bf16_f32 v68, v68, s0
	v_mul_f32_e32 v65, 0xbfb8aa3b, v65
	ds_write_b16 v169, v68 offset:9280
	v_lshlrev_b32_e32 v68, 16, v83
	v_add_f32_e32 v64, 1.0, v64
	v_exp_f32_e32 v65, v65
	v_mul_f32_e32 v68, v69, v68
	v_lshlrev_b32_e32 v69, 16, v84
	v_rcp_f32_e32 v64, v64
	v_mul_f32_e32 v68, v68, v69
	v_cvt_pk_bf16_f32 v68, v68, s0
	ds_write_b16 v170, v68 offset:9280
	v_lshlrev_b32_e32 v68, 16, v91
	v_add_f32_e32 v65, 1.0, v65
	v_mul_f32_e32 v64, v64, v68
	v_lshlrev_b32_e32 v68, 16, v90
	v_rcp_f32_e32 v65, v65
	v_mul_f32_e32 v64, v64, v68
	v_cvt_pk_bf16_f32 v64, v64, s0
	ds_write_b16 v166, v64 offset:9312
	v_lshlrev_b32_e32 v64, 16, v94
	v_mul_f32_e32 v64, v65, v64
	v_lshlrev_b32_e32 v65, 16, v79
	v_mul_f32_e32 v64, v64, v65
	v_add_f32_e32 v65, v66, v142
	v_mul_f32_e32 v65, 0xbfb8aa3b, v65
	v_exp_f32_e32 v65, v65
	ds_read_u16 v71, v169 offset:9312
	v_add_f32_e32 v66, v67, v142
	v_mul_f32_e32 v66, 0xbfb8aa3b, v66
	v_add_f32_e32 v65, 1.0, v65
	v_rcp_f32_e32 v65, v65
	v_exp_f32_e32 v66, v66
	v_cvt_pk_bf16_f32 v64, v64, s0
	ds_write_b16 v167, v64 offset:9312
	v_lshlrev_b32_e32 v64, 16, v89
	v_mul_f32_e32 v64, v65, v64
	s_waitcnt lgkmcnt(1)
	v_lshlrev_b32_e32 v65, 16, v71
	v_mul_f32_e32 v64, v64, v65
	v_add_f32_e32 v65, 1.0, v66
	v_rcp_f32_e32 v65, v65
	v_cvt_pk_bf16_f32 v64, v64, s0
	ds_write_b16 v169, v64 offset:9312
	v_lshlrev_b32_e32 v64, 16, v86
	v_mul_f32_e32 v64, v65, v64
	v_lshlrev_b32_e32 v65, 16, v85
	v_mul_f32_e32 v64, v64, v65
	v_cvt_pk_bf16_f32 v64, v64, s0
	ds_write_b16 v170, v64 offset:9312
	s_waitcnt lgkmcnt(0)
	s_mov_b64 s[64:65], 0
	v_mov_b32_e32 v64, v130
.LBB0_679:
	v_lshl_add_u64 v[82:83], v[140:141], 0, s[64:65]
	v_add_co_u32_e32 v84, vcc, 0x6000000, v82
	ds_read_b128 v[66:69], v64
	ds_read_b128 v[70:73], v64 offset:1152
	ds_read_b128 v[74:77], v64 offset:2304
	ds_read_b128 v[78:81], v64 offset:3456
	v_addc_co_u32_e32 v85, vcc, 0, v83, vcc
	v_add_co_u32_e32 v86, vcc, 0x6008000, v82
	s_add_u32 s64, s64, 0x20000
	s_nop 0
	v_addc_co_u32_e32 v87, vcc, 0, v83, vcc
	v_add_co_u32_e32 v88, vcc, 0x6010000, v82
	s_addc_u32 s65, s65, 0
	s_nop 0
	v_addc_co_u32_e32 v89, vcc, 0, v83, vcc
	v_add_co_u32_e32 v82, vcc, 0x6018000, v82
	v_add_u32_e32 v64, 0x1200, v64
	s_cmp_lg_u32 s64, 0x40000
	v_addc_co_u32_e32 v83, vcc, 0, v83, vcc
	s_waitcnt lgkmcnt(3)
	global_store_dwordx4 v[84:85], v[66:69], off sc1
	s_waitcnt lgkmcnt(2)
	global_store_dwordx4 v[86:87], v[70:73], off sc1
	s_waitcnt lgkmcnt(1)
	global_store_dwordx4 v[88:89], v[74:77], off sc1
	s_waitcnt lgkmcnt(0)
	global_store_dwordx4 v[82:83], v[78:81], off sc1
	s_cbranch_scc1 .LBB0_679
	s_waitcnt lgkmcnt(0)
	s_mov_b64 s[64:65], 0
	v_mov_b32_e32 v64, v171
	s_waitcnt vmcnt(13)
	ds_write_b128 v171, v[194:197]
	s_waitcnt vmcnt(12)
	ds_write_b128 v171, v[198:201] offset:1152
	s_mov_b64 s[64:65], 0x8000
	global_load_dwordx4 v[194:197], v[250:251], off nt
	v_lshl_add_u64 v[250:251], v[250:251], 0, s[64:65]
	global_load_dwordx4 v[198:201], v[250:251], off nt
	s_waitcnt vmcnt(13)
	ds_write_b128 v171, v[202:205] offset:2304
	s_waitcnt vmcnt(12)
	ds_write_b128 v171, v[206:209] offset:3456
	s_waitcnt vmcnt(11)
	ds_write_b128 v171, v[210:213] offset:4608
	s_waitcnt vmcnt(10)
	ds_write_b128 v171, v[214:217] offset:5760
	s_waitcnt vmcnt(9)
	ds_write_b128 v171, v[218:221] offset:6912
	s_waitcnt vmcnt(8)
	ds_write_b128 v171, v[222:225] offset:8064
	s_waitcnt vmcnt(7)
	ds_write_b128 v130, v[226:229]
	s_waitcnt vmcnt(6)
	ds_write_b128 v130, v[230:233] offset:1152
	s_waitcnt vmcnt(5)
	ds_write_b128 v130, v[234:237] offset:2304
	s_waitcnt vmcnt(4)
	ds_write_b128 v130, v[238:241] offset:3456
	s_waitcnt vmcnt(3)
	ds_write_b128 v130, v[242:245] offset:4608
	s_waitcnt vmcnt(2)
	ds_write_b128 v130, v[246:249] offset:5760
	s_waitcnt vmcnt(1)
	ds_write_b128 v130, v[194:197] offset:6912
	s_waitcnt vmcnt(0)
	ds_write_b128 v130, v[198:201] offset:8064
	v_add_f32_e32 v60, v60, v145
	v_mul_f32_e32 v60, 0xbfb8aa3b, v60
	v_exp_f32_e32 v60, v60
	s_waitcnt lgkmcnt(0)
	ds_read_u16 v64, v148
	ds_read_u16 v65, v148 offset:9216
	v_add_f32_e32 v61, v61, v145
	v_add_f32_e32 v60, 1.0, v60
	v_rcp_f32_e32 v60, v60
	s_waitcnt lgkmcnt(1)
	v_lshlrev_b32_e32 v64, 16, v64
	s_waitcnt lgkmcnt(0)
	v_lshlrev_b32_e32 v65, 16, v65
	v_mul_f32_e32 v61, 0xbfb8aa3b, v61
	v_mul_f32_e32 v60, v60, v64
	v_mul_f32_e32 v60, v60, v65
	v_exp_f32_e32 v61, v61
	v_cvt_pk_bf16_f32 v60, v60, s0
	ds_write_b16 v148, v60 offset:9216
	ds_read_u16 v60, v147 offset:144
	v_add_f32_e32 v61, 1.0, v61
	ds_read_u16 v64, v147 offset:9360
	v_rcp_f32_e32 v61, v61
	v_add_f32_e32 v56, v56, v144
	s_waitcnt lgkmcnt(1)
	v_lshlrev_b32_e32 v60, 16, v60
	v_mul_f32_e32 v56, 0xbfb8aa3b, v56
	v_mul_f32_e32 v60, v61, v60
	s_waitcnt lgkmcnt(0)
	v_lshlrev_b32_e32 v61, 16, v64
	v_mul_f32_e32 v60, v60, v61
	v_add_f32_e32 v61, v62, v145
	v_mul_f32_e32 v61, 0xbfb8aa3b, v61
	v_exp_f32_e32 v61, v61
	v_cvt_pk_bf16_f32 v60, v60, s0
	ds_write_b16 v147, v60 offset:9360
	ds_read_u16 v60, v149
	v_add_f32_e32 v61, 1.0, v61
	ds_read_u16 v62, v149 offset:9216
	v_rcp_f32_e32 v61, v61
	v_exp_f32_e32 v56, v56
	s_waitcnt lgkmcnt(1)
	v_lshlrev_b32_e32 v60, 16, v60
	v_add_f32_e32 v57, v57, v144
	v_mul_f32_e32 v60, v61, v60
	s_waitcnt lgkmcnt(0)
	v_lshlrev_b32_e32 v61, 16, v62
	v_mul_f32_e32 v60, v60, v61
	v_add_f32_e32 v61, v63, v145
	v_mul_f32_e32 v61, 0xbfb8aa3b, v61
	v_exp_f32_e32 v61, v61
	v_cvt_pk_bf16_f32 v60, v60, s0
	ds_write_b16 v149, v60 offset:9216
	ds_read_u16 v60, v151
	v_add_f32_e32 v61, 1.0, v61
	v_rcp_f32_e32 v61, v61
	ds_read_u16 v62, v151 offset:9216
	ds_read_u16 v63, v152 offset:32
	ds_read_u16 v64, v152 offset:9248
	v_add_f32_e32 v56, 1.0, v56
	s_waitcnt lgkmcnt(3)
	v_lshlrev_b32_e32 v60, 16, v60
	v_mul_f32_e32 v60, v61, v60
	s_waitcnt lgkmcnt(2)
	v_lshlrev_b32_e32 v61, 16, v62
	v_rcp_f32_e32 v56, v56
	v_mul_f32_e32 v60, v60, v61
	v_cvt_pk_bf16_f32 v60, v60, s0
	ds_write_b16 v151, v60 offset:9216
	s_waitcnt lgkmcnt(2)
	v_lshlrev_b32_e32 v60, 16, v63
	v_mul_f32_e32 v56, v56, v60
	s_waitcnt lgkmcnt(1)
	v_lshlrev_b32_e32 v60, 16, v64
	v_mul_f32_e32 v57, 0xbfb8aa3b, v57
	v_mul_f32_e32 v56, v56, v60
	v_exp_f32_e32 v57, v57
	v_cvt_pk_bf16_f32 v56, v56, s0
	ds_write_b16 v152, v56 offset:9248
	ds_read_u16 v56, v147 offset:176
	v_add_f32_e32 v57, 1.0, v57
	ds_read_u16 v60, v147 offset:9392
	v_rcp_f32_e32 v57, v57
	v_add_f32_e32 v58, v58, v144
	v_mul_f32_e32 v58, 0xbfb8aa3b, v58
	s_waitcnt lgkmcnt(1)
	v_lshlrev_b32_e32 v56, 16, v56
	v_exp_f32_e32 v58, v58
	v_mul_f32_e32 v56, v57, v56
	s_waitcnt lgkmcnt(0)
	v_lshlrev_b32_e32 v57, 16, v60
	v_mul_f32_e32 v56, v56, v57
	v_cvt_pk_bf16_f32 v56, v56, s0
	ds_write_b16 v147, v56 offset:9392
	v_add_f32_e32 v56, 1.0, v58
	v_rcp_f32_e32 v56, v56
	ds_read_u16 v57, v150 offset:32
	ds_read_u16 v58, v150 offset:9248
	ds_read_u16 v60, v151 offset:32
	ds_read_u16 v61, v151 offset:9248
	ds_read_u16 v62, v152 offset:64
	ds_read_u16 v63, v152 offset:9280
	s_waitcnt lgkmcnt(5)
	v_lshlrev_b32_e32 v57, 16, v57
	v_add_f32_e32 v52, v52, v143
	v_mul_f32_e32 v56, v56, v57
	s_waitcnt lgkmcnt(4)
	v_lshlrev_b32_e32 v57, 16, v58
	v_mul_f32_e32 v56, v56, v57
	v_add_f32_e32 v57, v59, v144
	v_mul_f32_e32 v57, 0xbfb8aa3b, v57
	v_exp_f32_e32 v57, v57
	v_mul_f32_e32 v52, 0xbfb8aa3b, v52
	v_exp_f32_e32 v52, v52
	v_cvt_pk_bf16_f32 v56, v56, s0
	v_add_f32_e32 v57, 1.0, v57
	v_rcp_f32_e32 v57, v57
	ds_write_b16 v150, v56 offset:9248
	s_waitcnt lgkmcnt(4)
	v_lshlrev_b32_e32 v56, 16, v60
	v_add_f32_e32 v52, 1.0, v52
	v_mul_f32_e32 v56, v57, v56
	s_waitcnt lgkmcnt(3)
	v_lshlrev_b32_e32 v57, 16, v61
	v_rcp_f32_e32 v52, v52
	v_mul_f32_e32 v56, v56, v57
	v_cvt_pk_bf16_f32 v56, v56, s0
	ds_write_b16 v151, v56 offset:9248
	s_waitcnt lgkmcnt(3)
	v_lshlrev_b32_e32 v56, 16, v62
	v_add_f32_e32 v53, v53, v143
	v_mul_f32_e32 v52, v52, v56
	s_waitcnt lgkmcnt(2)
	v_lshlrev_b32_e32 v56, 16, v63
	v_mul_f32_e32 v53, 0xbfb8aa3b, v53
	v_mul_f32_e32 v52, v52, v56
	v_exp_f32_e32 v53, v53
	v_cvt_pk_bf16_f32 v52, v52, s0
	ds_write_b16 v152, v52 offset:9280
	ds_read_u16 v52, v147 offset:208
	v_add_f32_e32 v53, 1.0, v53
	ds_read_u16 v56, v147 offset:9424
	v_rcp_f32_e32 v53, v53
	v_add_f32_e32 v54, v54, v143
	v_mul_f32_e32 v54, 0xbfb8aa3b, v54
	s_waitcnt lgkmcnt(1)
	v_lshlrev_b32_e32 v52, 16, v52
	v_exp_f32_e32 v54, v54
	v_mul_f32_e32 v52, v53, v52
	s_waitcnt lgkmcnt(0)
	v_lshlrev_b32_e32 v53, 16, v56
	v_mul_f32_e32 v52, v52, v53
	v_cvt_pk_bf16_f32 v52, v52, s0
	ds_write_b16 v147, v52 offset:9424
	v_add_f32_e32 v52, 1.0, v54
	v_rcp_f32_e32 v52, v52
	ds_read_u16 v53, v150 offset:64
	ds_read_u16 v54, v150 offset:9280
	ds_read_u16 v56, v151 offset:64
	ds_read_u16 v57, v151 offset:9280
	ds_read_u16 v58, v152 offset:96
	ds_read_u16 v59, v152 offset:9312
	s_waitcnt lgkmcnt(5)
	v_lshlrev_b32_e32 v53, 16, v53
	v_add_f32_e32 v48, v48, v142
	v_mul_f32_e32 v52, v52, v53
	s_waitcnt lgkmcnt(4)
	v_lshlrev_b32_e32 v53, 16, v54
	v_mul_f32_e32 v52, v52, v53
	v_add_f32_e32 v53, v55, v143
	v_mul_f32_e32 v53, 0xbfb8aa3b, v53
	v_exp_f32_e32 v53, v53
	v_mul_f32_e32 v48, 0xbfb8aa3b, v48
	v_exp_f32_e32 v48, v48
	v_cvt_pk_bf16_f32 v52, v52, s0
	v_add_f32_e32 v53, 1.0, v53
	v_rcp_f32_e32 v53, v53
	ds_write_b16 v150, v52 offset:9280
	s_waitcnt lgkmcnt(4)
	v_lshlrev_b32_e32 v52, 16, v56
	v_add_f32_e32 v48, 1.0, v48
	v_mul_f32_e32 v52, v53, v52
	s_waitcnt lgkmcnt(3)
	v_lshlrev_b32_e32 v53, 16, v57
	v_rcp_f32_e32 v48, v48
	v_mul_f32_e32 v52, v52, v53
	v_cvt_pk_bf16_f32 v52, v52, s0
	ds_write_b16 v151, v52 offset:9280
	s_waitcnt lgkmcnt(3)
	v_lshlrev_b32_e32 v52, 16, v58
	v_add_f32_e32 v49, v49, v142
	v_mul_f32_e32 v48, v48, v52
	s_waitcnt lgkmcnt(2)
	v_lshlrev_b32_e32 v52, 16, v59
	v_mul_f32_e32 v49, 0xbfb8aa3b, v49
	v_mul_f32_e32 v48, v48, v52
	v_exp_f32_e32 v49, v49
	v_cvt_pk_bf16_f32 v48, v48, s0
	ds_write_b16 v152, v48 offset:9312
	ds_read_u16 v48, v147 offset:240
	v_add_f32_e32 v49, 1.0, v49
	ds_read_u16 v52, v147 offset:9456
	v_rcp_f32_e32 v49, v49
	v_add_f32_e32 v51, v51, v142
	s_waitcnt lgkmcnt(1)
	v_lshlrev_b32_e32 v48, 16, v48
	v_mul_f32_e32 v51, 0xbfb8aa3b, v51
	v_mul_f32_e32 v48, v49, v48
	s_waitcnt lgkmcnt(0)
	v_lshlrev_b32_e32 v49, 16, v52
	v_mul_f32_e32 v48, v48, v49
	v_add_f32_e32 v49, v50, v142
	v_mul_f32_e32 v49, 0xbfb8aa3b, v49
	v_exp_f32_e32 v49, v49
	v_cvt_pk_bf16_f32 v48, v48, s0
	ds_write_b16 v147, v48 offset:9456
	ds_read_u16 v48, v150 offset:96
	v_add_f32_e32 v49, 1.0, v49
	v_rcp_f32_e32 v49, v49
	ds_read_u16 v50, v150 offset:9312
	ds_read_u16 v52, v151 offset:96
	ds_read_u16 v53, v151 offset:9312
	v_exp_f32_e32 v51, v51
	s_waitcnt lgkmcnt(3)
	v_lshlrev_b32_e32 v48, 16, v48
	v_mul_f32_e32 v48, v49, v48
	s_waitcnt lgkmcnt(2)
	v_lshlrev_b32_e32 v49, 16, v50
	v_mul_f32_e32 v48, v48, v49
	v_add_f32_e32 v49, 1.0, v51
	v_rcp_f32_e32 v49, v49
	v_cvt_pk_bf16_f32 v48, v48, s0
	ds_write_b16 v150, v48 offset:9312
	s_waitcnt lgkmcnt(2)
	v_lshlrev_b32_e32 v48, 16, v52
	v_add_f32_e32 v44, v44, v145
	v_mul_f32_e32 v48, v49, v48
	s_waitcnt lgkmcnt(1)
	v_lshlrev_b32_e32 v49, 16, v53
	v_mul_f32_e32 v44, 0xbfb8aa3b, v44
	v_mul_f32_e32 v48, v48, v49
	v_exp_f32_e32 v44, v44
	v_cvt_pk_bf16_f32 v48, v48, s0
	ds_write_b16 v151, v48 offset:9312
	ds_read_u16 v48, v153
	v_add_f32_e32 v44, 1.0, v44
	ds_read_u16 v49, v153 offset:9216
	v_rcp_f32_e32 v44, v44
	v_add_f32_e32 v45, v45, v145
	s_waitcnt lgkmcnt(1)
	v_lshlrev_b32_e32 v48, 16, v48
	v_mul_f32_e32 v45, 0xbfb8aa3b, v45
	v_mul_f32_e32 v44, v44, v48
	s_waitcnt lgkmcnt(0)
	v_lshlrev_b32_e32 v48, 16, v49
	v_mul_f32_e32 v44, v44, v48
	v_exp_f32_e32 v45, v45
	v_cvt_pk_bf16_f32 v44, v44, s0
	ds_write_b16 v153, v44 offset:9216
	ds_read_u16 v44, v155
	v_add_f32_e32 v45, 1.0, v45
	ds_read_u16 v48, v155 offset:9216
	v_rcp_f32_e32 v45, v45
	v_add_f32_e32 v40, v40, v144
	s_waitcnt lgkmcnt(1)
	v_lshlrev_b32_e32 v44, 16, v44
	v_mul_f32_e32 v40, 0xbfb8aa3b, v40
	v_mul_f32_e32 v44, v45, v44
	s_waitcnt lgkmcnt(0)
	v_lshlrev_b32_e32 v45, 16, v48
	v_mul_f32_e32 v44, v44, v45
	v_add_f32_e32 v45, v46, v145
	v_mul_f32_e32 v45, 0xbfb8aa3b, v45
	v_exp_f32_e32 v45, v45
	v_cvt_pk_bf16_f32 v44, v44, s0
	ds_write_b16 v155, v44 offset:9216
	ds_read_u16 v44, v156
	v_add_f32_e32 v45, 1.0, v45
	ds_read_u16 v46, v156 offset:9216
	v_rcp_f32_e32 v45, v45
	v_exp_f32_e32 v40, v40
	s_waitcnt lgkmcnt(1)
	v_lshlrev_b32_e32 v44, 16, v44
	v_add_f32_e32 v42, v42, v144
	v_mul_f32_e32 v44, v45, v44
	s_waitcnt lgkmcnt(0)
	v_lshlrev_b32_e32 v45, 16, v46
	v_mul_f32_e32 v44, v44, v45
	v_add_f32_e32 v45, v47, v145
	v_mul_f32_e32 v45, 0xbfb8aa3b, v45
	v_exp_f32_e32 v45, v45
	v_cvt_pk_bf16_f32 v44, v44, s0
	ds_write_b16 v156, v44 offset:9216
	ds_read_u16 v44, v158
	v_add_f32_e32 v45, 1.0, v45
	v_rcp_f32_e32 v45, v45
	ds_read_u16 v46, v158 offset:32
	ds_read_u16 v47, v155 offset:9312
	v_add_f32_e32 v40, 1.0, v40
	s_waitcnt lgkmcnt(2)
	v_lshlrev_b32_e32 v44, 16, v44
	v_mul_f32_e32 v44, v45, v44
	ds_read_u16 v45, v158 offset:9216
	ds_read_u16 v48, v154 offset:32
	ds_read_u16 v49, v154 offset:64
	ds_read_u16 v50, v158 offset:9248
	ds_read_u16 v51, v158 offset:64
	ds_read_u16 v52, v158 offset:9280
	ds_read_u16 v53, v158 offset:9312
	ds_read_u16 v54, v158 offset:96
	s_waitcnt lgkmcnt(7)
	v_lshlrev_b32_e32 v45, 16, v45
	v_rcp_f32_e32 v40, v40
	v_mul_f32_e32 v44, v44, v45
	v_cvt_pk_bf16_f32 v44, v44, s0
	ds_write_b16 v158, v44 offset:9216
	s_waitcnt lgkmcnt(7)
	v_lshlrev_b32_e32 v44, 16, v48
	v_mul_f32_e32 v40, v40, v44
	ds_read_u16 v44, v154 offset:9248
	ds_read_u16 v45, v157 offset:32
	ds_read_u16 v48, v157 offset:9248
	ds_read_u16 v55, v154 offset:9280
	ds_read_u16 v56, v157 offset:64
	ds_read_u16 v57, v157 offset:96
	ds_read_u16 v58, v154 offset:9312
	ds_read_u16 v59, v154 offset:96
	s_waitcnt lgkmcnt(7)
	v_lshlrev_b32_e32 v44, 16, v44
	v_mul_f32_e32 v40, v40, v44
	v_cvt_pk_bf16_f32 v40, v40, s0
	ds_write_b16 v154, v40 offset:9248
	v_add_f32_e32 v40, v41, v144
	v_mul_f32_e32 v40, 0xbfb8aa3b, v40
	v_exp_f32_e32 v40, v40
	v_mul_f32_e32 v42, 0xbfb8aa3b, v42
	v_exp_f32_e32 v42, v42
	ds_read_u16 v41, v155 offset:32
	ds_read_u16 v44, v155 offset:9248
	ds_read_u16 v60, v155 offset:9280
	ds_read_u16 v61, v155 offset:64
	ds_read_u16 v62, v155 offset:96
	v_add_f32_e32 v40, 1.0, v40
	v_rcp_f32_e32 v40, v40
	s_waitcnt lgkmcnt(4)
	v_lshlrev_b32_e32 v41, 16, v41
	v_add_f32_e32 v36, v36, v143
	v_mul_f32_e32 v36, 0xbfb8aa3b, v36
	v_mul_f32_e32 v40, v40, v41
	s_waitcnt lgkmcnt(3)
	v_lshlrev_b32_e32 v41, 16, v44
	v_mul_f32_e32 v40, v40, v41
	v_add_f32_e32 v41, 1.0, v42
	v_rcp_f32_e32 v41, v41
	v_cvt_pk_bf16_f32 v40, v40, s0
	ds_write_b16 v155, v40 offset:9248
	v_lshlrev_b32_e32 v40, 16, v45
	v_mul_f32_e32 v40, v41, v40
	v_lshlrev_b32_e32 v41, 16, v48
	v_mul_f32_e32 v40, v40, v41
	v_add_f32_e32 v41, v43, v144
	v_mul_f32_e32 v41, 0xbfb8aa3b, v41
	v_exp_f32_e32 v41, v41
	v_exp_f32_e32 v36, v36
	v_add_f32_e32 v37, v37, v143
	v_cvt_pk_bf16_f32 v40, v40, s0
	v_add_f32_e32 v41, 1.0, v41
	v_rcp_f32_e32 v41, v41
	v_mul_f32_e32 v37, 0xbfb8aa3b, v37
	ds_write_b16 v157, v40 offset:9248
	v_lshlrev_b32_e32 v40, 16, v46
	v_add_f32_e32 v36, 1.0, v36
	v_exp_f32_e32 v37, v37
	v_mul_f32_e32 v40, v41, v40
	v_lshlrev_b32_e32 v41, 16, v50
	v_rcp_f32_e32 v36, v36
	v_mul_f32_e32 v40, v40, v41
	v_cvt_pk_bf16_f32 v40, v40, s0
	ds_write_b16 v158, v40 offset:9248
	v_lshlrev_b32_e32 v40, 16, v49
	v_add_f32_e32 v37, 1.0, v37
	v_add_f32_e32 v38, v38, v143
	v_mul_f32_e32 v36, v36, v40
	v_lshlrev_b32_e32 v40, 16, v55
	v_rcp_f32_e32 v37, v37
	v_mul_f32_e32 v38, 0xbfb8aa3b, v38
	v_mul_f32_e32 v36, v36, v40
	v_exp_f32_e32 v38, v38
	v_cvt_pk_bf16_f32 v36, v36, s0
	ds_write_b16 v154, v36 offset:9280
	s_waitcnt lgkmcnt(5)
	v_lshlrev_b32_e32 v36, 16, v61
	v_mul_f32_e32 v36, v37, v36
	v_lshlrev_b32_e32 v37, 16, v60
	v_mul_f32_e32 v36, v36, v37
	v_add_f32_e32 v37, 1.0, v38
	v_rcp_f32_e32 v37, v37
	v_cvt_pk_bf16_f32 v36, v36, s0
	ds_write_b16 v155, v36 offset:9280
	v_lshlrev_b32_e32 v36, 16, v56
	v_mul_f32_e32 v36, v37, v36
	ds_read_u16 v37, v157 offset:9280
	v_add_f32_e32 v38, v39, v143
	v_mul_f32_e32 v38, 0xbfb8aa3b, v38
	v_exp_f32_e32 v38, v38
	v_add_f32_e32 v32, v32, v142
	s_waitcnt lgkmcnt(0)
	v_lshlrev_b32_e32 v37, 16, v37
	v_mul_f32_e32 v32, 0xbfb8aa3b, v32
	v_mul_f32_e32 v36, v36, v37
	v_add_f32_e32 v37, 1.0, v38
	v_exp_f32_e32 v32, v32
	v_rcp_f32_e32 v37, v37
	v_add_f32_e32 v33, v33, v142
	v_cvt_pk_bf16_f32 v36, v36, s0
	v_mul_f32_e32 v33, 0xbfb8aa3b, v33
	ds_write_b16 v157, v36 offset:9280
	v_lshlrev_b32_e32 v36, 16, v51
	v_add_f32_e32 v32, 1.0, v32
	v_exp_f32_e32 v33, v33
	v_mul_f32_e32 v36, v37, v36
	v_lshlrev_b32_e32 v37, 16, v52
	v_rcp_f32_e32 v32, v32
	v_mul_f32_e32 v36, v36, v37
	v_cvt_pk_bf16_f32 v36, v36, s0
	ds_write_b16 v158, v36 offset:9280
	v_lshlrev_b32_e32 v36, 16, v59
	v_add_f32_e32 v33, 1.0, v33
	v_mul_f32_e32 v32, v32, v36
	v_lshlrev_b32_e32 v36, 16, v58
	v_rcp_f32_e32 v33, v33
	v_mul_f32_e32 v32, v32, v36
	v_cvt_pk_bf16_f32 v32, v32, s0
	ds_write_b16 v154, v32 offset:9312
	v_lshlrev_b32_e32 v32, 16, v62
	v_mul_f32_e32 v32, v33, v32
	v_lshlrev_b32_e32 v33, 16, v47
	v_mul_f32_e32 v32, v32, v33
	v_add_f32_e32 v33, v34, v142
	v_mul_f32_e32 v33, 0xbfb8aa3b, v33
	v_exp_f32_e32 v33, v33
	ds_read_u16 v39, v157 offset:9312
	v_add_f32_e32 v34, v35, v142
	v_mul_f32_e32 v34, 0xbfb8aa3b, v34
	v_add_f32_e32 v33, 1.0, v33
	v_rcp_f32_e32 v33, v33
	v_exp_f32_e32 v34, v34
	v_cvt_pk_bf16_f32 v32, v32, s0
	ds_write_b16 v155, v32 offset:9312
	v_lshlrev_b32_e32 v32, 16, v57
	v_mul_f32_e32 v32, v33, v32
	s_waitcnt lgkmcnt(1)
	v_lshlrev_b32_e32 v33, 16, v39
	v_mul_f32_e32 v32, v32, v33
	v_add_f32_e32 v33, 1.0, v34
	v_rcp_f32_e32 v33, v33
	v_cvt_pk_bf16_f32 v32, v32, s0
	ds_write_b16 v157, v32 offset:9312
	v_lshlrev_b32_e32 v32, 16, v54
	v_add_f32_e32 v28, v28, v145
	v_mul_f32_e32 v32, v33, v32
	v_lshlrev_b32_e32 v33, 16, v53
	v_mul_f32_e32 v28, 0xbfb8aa3b, v28
	v_mul_f32_e32 v32, v32, v33
	v_exp_f32_e32 v28, v28
	v_cvt_pk_bf16_f32 v32, v32, s0
	ds_write_b16 v158, v32 offset:9312
	ds_read_u16 v32, v159
	v_add_f32_e32 v28, 1.0, v28
	ds_read_u16 v33, v159 offset:9216
	v_rcp_f32_e32 v28, v28
	v_add_f32_e32 v29, v29, v145
	s_waitcnt lgkmcnt(1)
	v_lshlrev_b32_e32 v32, 16, v32
	v_mul_f32_e32 v29, 0xbfb8aa3b, v29
	v_mul_f32_e32 v28, v28, v32
	s_waitcnt lgkmcnt(0)
	v_lshlrev_b32_e32 v32, 16, v33
	v_mul_f32_e32 v28, v28, v32
	v_exp_f32_e32 v29, v29
	v_cvt_pk_bf16_f32 v28, v28, s0
	ds_write_b16 v159, v28 offset:9216
	ds_read_u16 v28, v161
	v_add_f32_e32 v29, 1.0, v29
	ds_read_u16 v32, v161 offset:9216
	v_rcp_f32_e32 v29, v29
	v_add_f32_e32 v24, v24, v144
	s_waitcnt lgkmcnt(1)
	v_lshlrev_b32_e32 v28, 16, v28
	v_mul_f32_e32 v24, 0xbfb8aa3b, v24
	v_mul_f32_e32 v28, v29, v28
	s_waitcnt lgkmcnt(0)
	v_lshlrev_b32_e32 v29, 16, v32
	v_mul_f32_e32 v28, v28, v29
	v_add_f32_e32 v29, v30, v145
	v_mul_f32_e32 v29, 0xbfb8aa3b, v29
	v_exp_f32_e32 v29, v29
	v_cvt_pk_bf16_f32 v28, v28, s0
	ds_write_b16 v161, v28 offset:9216
	ds_read_u16 v28, v162
	v_add_f32_e32 v29, 1.0, v29
	ds_read_u16 v30, v162 offset:9216
	v_rcp_f32_e32 v29, v29
	v_exp_f32_e32 v24, v24
	s_waitcnt lgkmcnt(1)
	v_lshlrev_b32_e32 v28, 16, v28
	v_add_f32_e32 v26, v26, v144
	v_mul_f32_e32 v28, v29, v28
	s_waitcnt lgkmcnt(0)
	v_lshlrev_b32_e32 v29, 16, v30
	v_mul_f32_e32 v28, v28, v29
	v_add_f32_e32 v29, v31, v145
	v_mul_f32_e32 v29, 0xbfb8aa3b, v29
	v_exp_f32_e32 v29, v29
	v_cvt_pk_bf16_f32 v28, v28, s0
	ds_write_b16 v162, v28 offset:9216
	ds_read_u16 v28, v164
	v_add_f32_e32 v29, 1.0, v29
	v_rcp_f32_e32 v29, v29
	ds_read_u16 v30, v164 offset:32
	ds_read_u16 v31, v161 offset:9312
	v_add_f32_e32 v24, 1.0, v24
	s_waitcnt lgkmcnt(2)
	v_lshlrev_b32_e32 v28, 16, v28
	v_mul_f32_e32 v28, v29, v28
	ds_read_u16 v29, v164 offset:9216
	ds_read_u16 v32, v160 offset:32
	ds_read_u16 v33, v160 offset:64
	ds_read_u16 v34, v164 offset:9248
	ds_read_u16 v35, v164 offset:64
	ds_read_u16 v36, v164 offset:9280
	ds_read_u16 v37, v164 offset:9312
	ds_read_u16 v38, v164 offset:96
	s_waitcnt lgkmcnt(7)
	v_lshlrev_b32_e32 v29, 16, v29
	v_rcp_f32_e32 v24, v24
	v_mul_f32_e32 v28, v28, v29
	v_cvt_pk_bf16_f32 v28, v28, s0
	ds_write_b16 v164, v28 offset:9216
	s_waitcnt lgkmcnt(7)
	v_lshlrev_b32_e32 v28, 16, v32
	v_mul_f32_e32 v24, v24, v28
	ds_read_u16 v28, v160 offset:9248
	ds_read_u16 v29, v163 offset:32
	ds_read_u16 v32, v163 offset:9248
	ds_read_u16 v39, v160 offset:9280
	ds_read_u16 v40, v163 offset:64
	ds_read_u16 v41, v163 offset:96
	ds_read_u16 v42, v160 offset:9312
	ds_read_u16 v43, v160 offset:96
	s_waitcnt lgkmcnt(7)
	v_lshlrev_b32_e32 v28, 16, v28
	v_mul_f32_e32 v24, v24, v28
	v_cvt_pk_bf16_f32 v24, v24, s0
	ds_write_b16 v160, v24 offset:9248
	v_add_f32_e32 v24, v25, v144
	v_mul_f32_e32 v24, 0xbfb8aa3b, v24
	v_exp_f32_e32 v24, v24
	v_mul_f32_e32 v26, 0xbfb8aa3b, v26
	v_exp_f32_e32 v26, v26
	ds_read_u16 v25, v161 offset:32
	ds_read_u16 v28, v161 offset:9248
	ds_read_u16 v44, v161 offset:9280
	ds_read_u16 v45, v161 offset:64
	ds_read_u16 v46, v161 offset:96
	v_add_f32_e32 v24, 1.0, v24
	v_rcp_f32_e32 v24, v24
	s_waitcnt lgkmcnt(4)
	v_lshlrev_b32_e32 v25, 16, v25
	v_add_f32_e32 v20, v20, v143
	v_mul_f32_e32 v20, 0xbfb8aa3b, v20
	v_mul_f32_e32 v24, v24, v25
	s_waitcnt lgkmcnt(3)
	v_lshlrev_b32_e32 v25, 16, v28
	v_mul_f32_e32 v24, v24, v25
	v_add_f32_e32 v25, 1.0, v26
	v_rcp_f32_e32 v25, v25
	v_cvt_pk_bf16_f32 v24, v24, s0
	ds_write_b16 v161, v24 offset:9248
	v_lshlrev_b32_e32 v24, 16, v29
	v_mul_f32_e32 v24, v25, v24
	v_lshlrev_b32_e32 v25, 16, v32
	v_mul_f32_e32 v24, v24, v25
	v_add_f32_e32 v25, v27, v144
	v_mul_f32_e32 v25, 0xbfb8aa3b, v25
	v_exp_f32_e32 v25, v25
	v_exp_f32_e32 v20, v20
	v_add_f32_e32 v21, v21, v143
	v_cvt_pk_bf16_f32 v24, v24, s0
	v_add_f32_e32 v25, 1.0, v25
	v_rcp_f32_e32 v25, v25
	v_mul_f32_e32 v21, 0xbfb8aa3b, v21
	ds_write_b16 v163, v24 offset:9248
	v_lshlrev_b32_e32 v24, 16, v30
	v_add_f32_e32 v20, 1.0, v20
	v_exp_f32_e32 v21, v21
	v_mul_f32_e32 v24, v25, v24
	v_lshlrev_b32_e32 v25, 16, v34
	v_rcp_f32_e32 v20, v20
	v_mul_f32_e32 v24, v24, v25
	v_cvt_pk_bf16_f32 v24, v24, s0
	ds_write_b16 v164, v24 offset:9248
	v_lshlrev_b32_e32 v24, 16, v33
	v_add_f32_e32 v21, 1.0, v21
	v_add_f32_e32 v22, v22, v143
	v_mul_f32_e32 v20, v20, v24
	v_lshlrev_b32_e32 v24, 16, v39
	v_rcp_f32_e32 v21, v21
	v_mul_f32_e32 v22, 0xbfb8aa3b, v22
	v_mul_f32_e32 v20, v20, v24
	v_exp_f32_e32 v22, v22
	v_cvt_pk_bf16_f32 v20, v20, s0
	ds_write_b16 v160, v20 offset:9280
	s_waitcnt lgkmcnt(5)
	v_lshlrev_b32_e32 v20, 16, v45
	v_mul_f32_e32 v20, v21, v20
	v_lshlrev_b32_e32 v21, 16, v44
	v_mul_f32_e32 v20, v20, v21
	v_add_f32_e32 v21, 1.0, v22
	v_rcp_f32_e32 v21, v21
	v_cvt_pk_bf16_f32 v20, v20, s0
	ds_write_b16 v161, v20 offset:9280
	v_lshlrev_b32_e32 v20, 16, v40
	v_mul_f32_e32 v20, v21, v20
	ds_read_u16 v21, v163 offset:9280
	v_add_f32_e32 v22, v23, v143
	v_mul_f32_e32 v22, 0xbfb8aa3b, v22
	v_exp_f32_e32 v22, v22
	v_add_f32_e32 v16, v16, v142
	s_waitcnt lgkmcnt(0)
	v_lshlrev_b32_e32 v21, 16, v21
	v_mul_f32_e32 v16, 0xbfb8aa3b, v16
	v_mul_f32_e32 v20, v20, v21
	v_add_f32_e32 v21, 1.0, v22
	v_exp_f32_e32 v16, v16
	v_rcp_f32_e32 v21, v21
	v_add_f32_e32 v17, v17, v142
	v_cvt_pk_bf16_f32 v20, v20, s0
	v_mul_f32_e32 v17, 0xbfb8aa3b, v17
	ds_write_b16 v163, v20 offset:9280
	v_lshlrev_b32_e32 v20, 16, v35
	v_add_f32_e32 v16, 1.0, v16
	v_exp_f32_e32 v17, v17
	v_mul_f32_e32 v20, v21, v20
	v_lshlrev_b32_e32 v21, 16, v36
	v_rcp_f32_e32 v16, v16
	v_mul_f32_e32 v20, v20, v21
	v_cvt_pk_bf16_f32 v20, v20, s0
	ds_write_b16 v164, v20 offset:9280
	v_lshlrev_b32_e32 v20, 16, v43
	v_add_f32_e32 v17, 1.0, v17
	v_mul_f32_e32 v16, v16, v20
	v_lshlrev_b32_e32 v20, 16, v42
	v_rcp_f32_e32 v17, v17
	v_mul_f32_e32 v16, v16, v20
	v_cvt_pk_bf16_f32 v16, v16, s0
	ds_write_b16 v160, v16 offset:9312
	v_lshlrev_b32_e32 v16, 16, v46
	v_mul_f32_e32 v16, v17, v16
	v_lshlrev_b32_e32 v17, 16, v31
	v_mul_f32_e32 v16, v16, v17
	v_add_f32_e32 v17, v18, v142
	v_mul_f32_e32 v17, 0xbfb8aa3b, v17
	v_exp_f32_e32 v17, v17
	ds_read_u16 v23, v163 offset:9312
	v_add_f32_e32 v18, v19, v142
	v_mul_f32_e32 v18, 0xbfb8aa3b, v18
	v_add_f32_e32 v17, 1.0, v17
	v_rcp_f32_e32 v17, v17
	v_exp_f32_e32 v18, v18
	v_cvt_pk_bf16_f32 v16, v16, s0
	ds_write_b16 v161, v16 offset:9312
	v_lshlrev_b32_e32 v16, 16, v41
	v_mul_f32_e32 v16, v17, v16
	s_waitcnt lgkmcnt(1)
	v_lshlrev_b32_e32 v17, 16, v23
	v_mul_f32_e32 v16, v16, v17
	v_add_f32_e32 v17, 1.0, v18
	v_rcp_f32_e32 v17, v17
	v_cvt_pk_bf16_f32 v16, v16, s0
	ds_write_b16 v163, v16 offset:9312
	v_lshlrev_b32_e32 v16, 16, v38
	v_add_f32_e32 v12, v12, v145
	v_mul_f32_e32 v16, v17, v16
	v_lshlrev_b32_e32 v17, 16, v37
	v_mul_f32_e32 v12, 0xbfb8aa3b, v12
	v_mul_f32_e32 v16, v16, v17
	v_exp_f32_e32 v12, v12
	v_cvt_pk_bf16_f32 v16, v16, s0
	ds_write_b16 v164, v16 offset:9312
	ds_read_u16 v16, v165
	v_add_f32_e32 v12, 1.0, v12
	ds_read_u16 v17, v165 offset:9216
	v_rcp_f32_e32 v12, v12
	v_add_f32_e32 v13, v13, v145
	s_waitcnt lgkmcnt(1)
	v_lshlrev_b32_e32 v16, 16, v16
	v_mul_f32_e32 v13, 0xbfb8aa3b, v13
	v_mul_f32_e32 v12, v12, v16
	s_waitcnt lgkmcnt(0)
	v_lshlrev_b32_e32 v16, 16, v17
	v_mul_f32_e32 v12, v12, v16
	v_exp_f32_e32 v13, v13
	v_cvt_pk_bf16_f32 v12, v12, s0
	ds_write_b16 v165, v12 offset:9216
	ds_read_u16 v12, v167
	v_add_f32_e32 v13, 1.0, v13
	ds_read_u16 v16, v167 offset:9216
	v_rcp_f32_e32 v13, v13
	v_add_f32_e32 v0, v0, v144
	s_waitcnt lgkmcnt(1)
	v_lshlrev_b32_e32 v12, 16, v12
	v_mul_f32_e32 v0, 0xbfb8aa3b, v0
	v_mul_f32_e32 v12, v13, v12
	s_waitcnt lgkmcnt(0)
	v_lshlrev_b32_e32 v13, 16, v16
	v_mul_f32_e32 v12, v12, v13
	v_add_f32_e32 v13, v14, v145
	v_mul_f32_e32 v13, 0xbfb8aa3b, v13
	v_exp_f32_e32 v13, v13
	v_cvt_pk_bf16_f32 v12, v12, s0
	ds_write_b16 v167, v12 offset:9216
	ds_read_u16 v12, v168
	v_add_f32_e32 v13, 1.0, v13
	ds_read_u16 v14, v168 offset:9216
	v_rcp_f32_e32 v13, v13
	v_exp_f32_e32 v0, v0
	s_waitcnt lgkmcnt(1)
	v_lshlrev_b32_e32 v12, 16, v12
	v_add_f32_e32 v2, v2, v144
	v_mul_f32_e32 v12, v13, v12
	s_waitcnt lgkmcnt(0)
	v_lshlrev_b32_e32 v13, 16, v14
	v_mul_f32_e32 v12, v12, v13
	v_add_f32_e32 v13, v15, v145
	v_mul_f32_e32 v13, 0xbfb8aa3b, v13
	v_exp_f32_e32 v13, v13
	v_cvt_pk_bf16_f32 v12, v12, s0
	ds_write_b16 v168, v12 offset:9216
	ds_read_u16 v12, v170
	v_add_f32_e32 v13, 1.0, v13
	v_rcp_f32_e32 v13, v13
	ds_read_u16 v14, v170 offset:32
	ds_read_u16 v15, v167 offset:9312
	v_add_f32_e32 v0, 1.0, v0
	s_waitcnt lgkmcnt(2)
	v_lshlrev_b32_e32 v12, 16, v12
	v_mul_f32_e32 v12, v13, v12
	ds_read_u16 v13, v170 offset:9216
	ds_read_u16 v16, v166 offset:32
	ds_read_u16 v17, v166 offset:64
	ds_read_u16 v18, v170 offset:9248
	ds_read_u16 v19, v170 offset:64
	ds_read_u16 v20, v170 offset:9280
	ds_read_u16 v21, v170 offset:9312
	ds_read_u16 v22, v170 offset:96
	s_waitcnt lgkmcnt(7)
	v_lshlrev_b32_e32 v13, 16, v13
	v_rcp_f32_e32 v0, v0
	v_mul_f32_e32 v12, v12, v13
	v_cvt_pk_bf16_f32 v12, v12, s0
	ds_write_b16 v170, v12 offset:9216
	s_waitcnt lgkmcnt(7)
	v_lshlrev_b32_e32 v12, 16, v16
	v_mul_f32_e32 v0, v0, v12
	ds_read_u16 v12, v166 offset:9248
	ds_read_u16 v13, v169 offset:32
	ds_read_u16 v16, v169 offset:9248
	ds_read_u16 v23, v166 offset:9280
	ds_read_u16 v24, v169 offset:64
	ds_read_u16 v25, v169 offset:96
	ds_read_u16 v26, v166 offset:9312
	ds_read_u16 v27, v166 offset:96
	s_waitcnt lgkmcnt(7)
	v_lshlrev_b32_e32 v12, 16, v12
	v_mul_f32_e32 v0, v0, v12
	v_cvt_pk_bf16_f32 v0, v0, s0
	ds_write_b16 v166, v0 offset:9248
	v_add_f32_e32 v0, v1, v144
	v_mul_f32_e32 v0, 0xbfb8aa3b, v0
	v_exp_f32_e32 v0, v0
	v_mul_f32_e32 v2, 0xbfb8aa3b, v2
	v_exp_f32_e32 v2, v2
	ds_read_u16 v1, v167 offset:32
	ds_read_u16 v12, v167 offset:9248
	ds_read_u16 v28, v167 offset:9280
	ds_read_u16 v29, v167 offset:64
	ds_read_u16 v30, v167 offset:96
	v_add_f32_e32 v0, 1.0, v0
	v_rcp_f32_e32 v0, v0
	s_waitcnt lgkmcnt(4)
	v_lshlrev_b32_e32 v1, 16, v1
	s_mov_b64 s[64:65], 0
	v_mul_f32_e32 v0, v0, v1
	s_waitcnt lgkmcnt(3)
	v_lshlrev_b32_e32 v1, 16, v12
	v_mul_f32_e32 v0, v0, v1
	v_add_f32_e32 v1, 1.0, v2
	v_rcp_f32_e32 v1, v1
	v_cvt_pk_bf16_f32 v0, v0, s0
	ds_write_b16 v167, v0 offset:9248
	v_lshlrev_b32_e32 v0, 16, v13
	v_mul_f32_e32 v0, v1, v0
	v_lshlrev_b32_e32 v1, 16, v16
	v_mul_f32_e32 v0, v0, v1
	v_add_f32_e32 v1, v3, v144
	v_mul_f32_e32 v1, 0xbfb8aa3b, v1
	v_exp_f32_e32 v1, v1
	v_add_f32_e32 v2, v8, v143
	v_mul_f32_e32 v2, 0xbfb8aa3b, v2
	v_exp_f32_e32 v2, v2
	v_add_f32_e32 v1, 1.0, v1
	v_rcp_f32_e32 v1, v1
	v_cvt_pk_bf16_f32 v0, v0, s0
	ds_write_b16 v169, v0 offset:9248
	v_lshlrev_b32_e32 v0, 16, v14
	v_mul_f32_e32 v0, v1, v0
	v_lshlrev_b32_e32 v1, 16, v18
	v_mul_f32_e32 v0, v0, v1
	v_add_f32_e32 v1, 1.0, v2
	v_rcp_f32_e32 v1, v1
	v_cvt_pk_bf16_f32 v0, v0, s0
	ds_write_b16 v170, v0 offset:9248
	v_lshlrev_b32_e32 v0, 16, v17
	v_mul_f32_e32 v0, v1, v0
	v_lshlrev_b32_e32 v1, 16, v23
	v_mul_f32_e32 v0, v0, v1
	v_add_f32_e32 v1, v9, v143
	v_mul_f32_e32 v1, 0xbfb8aa3b, v1
	v_exp_f32_e32 v1, v1
	v_add_f32_e32 v2, v10, v143
	v_mul_f32_e32 v2, 0xbfb8aa3b, v2
	v_exp_f32_e32 v2, v2
	v_add_f32_e32 v1, 1.0, v1
	v_rcp_f32_e32 v1, v1
	v_cvt_pk_bf16_f32 v0, v0, s0
	ds_write_b16 v166, v0 offset:9280
	s_waitcnt lgkmcnt(5)
	v_lshlrev_b32_e32 v0, 16, v29
	v_mul_f32_e32 v0, v1, v0
	v_lshlrev_b32_e32 v1, 16, v28
	v_mul_f32_e32 v0, v0, v1
	v_add_f32_e32 v1, 1.0, v2
	v_rcp_f32_e32 v1, v1
	v_cvt_pk_bf16_f32 v0, v0, s0
	ds_write_b16 v167, v0 offset:9280
	v_lshlrev_b32_e32 v0, 16, v24
	v_mul_f32_e32 v0, v1, v0
	ds_read_u16 v1, v169 offset:9280
	v_add_f32_e32 v2, v11, v143
	v_mul_f32_e32 v2, 0xbfb8aa3b, v2
	v_exp_f32_e32 v2, v2
	ds_read_u16 v3, v169 offset:9312
	s_waitcnt lgkmcnt(1)
	v_lshlrev_b32_e32 v1, 16, v1
	v_mul_f32_e32 v0, v0, v1
	v_add_f32_e32 v1, 1.0, v2
	v_rcp_f32_e32 v1, v1
	v_cvt_pk_bf16_f32 v0, v0, s0
	ds_write_b16 v169, v0 offset:9280
	v_lshlrev_b32_e32 v0, 16, v19
	v_mul_f32_e32 v0, v1, v0
	v_lshlrev_b32_e32 v1, 16, v20
	v_mul_f32_e32 v0, v0, v1
	v_add_f32_e32 v1, v4, v142
	v_mul_f32_e32 v1, 0xbfb8aa3b, v1
	v_exp_f32_e32 v1, v1
	v_add_f32_e32 v2, v5, v142
	v_mul_f32_e32 v2, 0xbfb8aa3b, v2
	v_exp_f32_e32 v2, v2
	v_add_f32_e32 v1, 1.0, v1
	v_rcp_f32_e32 v1, v1
	v_cvt_pk_bf16_f32 v0, v0, s0
	ds_write_b16 v170, v0 offset:9280
	v_lshlrev_b32_e32 v0, 16, v27
	v_mul_f32_e32 v0, v1, v0
	v_lshlrev_b32_e32 v1, 16, v26
	v_mul_f32_e32 v0, v0, v1
	v_add_f32_e32 v1, 1.0, v2
	v_rcp_f32_e32 v1, v1
	v_cvt_pk_bf16_f32 v0, v0, s0
	ds_write_b16 v166, v0 offset:9312
	v_lshlrev_b32_e32 v0, 16, v30
	v_mul_f32_e32 v0, v1, v0
	v_lshlrev_b32_e32 v1, 16, v15
	v_mul_f32_e32 v0, v0, v1
	v_add_f32_e32 v1, v6, v142
	v_mul_f32_e32 v1, 0xbfb8aa3b, v1
	v_exp_f32_e32 v1, v1
	v_add_f32_e32 v2, v7, v142
	v_mul_f32_e32 v2, 0xbfb8aa3b, v2
	v_exp_f32_e32 v2, v2
	v_add_f32_e32 v1, 1.0, v1
	v_rcp_f32_e32 v1, v1
	v_cvt_pk_bf16_f32 v0, v0, s0
	ds_write_b16 v167, v0 offset:9312
	v_lshlrev_b32_e32 v0, 16, v25
	v_mul_f32_e32 v0, v1, v0
	s_waitcnt lgkmcnt(4)
	v_lshlrev_b32_e32 v1, 16, v3
	v_mul_f32_e32 v0, v0, v1
	v_add_f32_e32 v1, 1.0, v2
	v_rcp_f32_e32 v1, v1
	v_cvt_pk_bf16_f32 v0, v0, s0
	ds_write_b16 v169, v0 offset:9312
	v_lshlrev_b32_e32 v0, 16, v22
	v_mul_f32_e32 v0, v1, v0
	v_lshlrev_b32_e32 v1, 16, v21
	v_mul_f32_e32 v0, v0, v1
	v_cvt_pk_bf16_f32 v0, v0, s0
	ds_write_b16 v170, v0 offset:9312
	s_waitcnt lgkmcnt(0)
	v_mov_b32_e32 v0, v130

.LBB0_745:
	s_add_i32 s60, s60, s82
	s_add_i32 s55, s55, s82
	v_and_b32_e32 v178, 15, v181
	v_bfe_u32 v138, v181, 4, 2
	v_lshlrev_b32_e32 v141, 4, v178
	s_movk_i32 s20, 0x110
	v_mad_u32_u24 v141, v138, s20, v141
	v_lshlrev_b32_e32 v139, 2, v178
	s_movk_i32 s20, 0x440
	v_mad_u32_u24 v139, v138, s20, v139
	v_lshlrev_b32_e32 v138, 12, v138
	v_lshl_add_u32 v138, v178, 4, v138
	v_lshrrev_b32_e32 v178, 6, v181
	v_mul_u32_u24_e32 v178, 0x4400, v178
	v_add_u32_e32 v141, v141, v178
	v_add_u32_e32 v139, v139, v178
	v_bfe_u32 v178, v181, 6, 2
	v_lshl_add_u32 v138, v178, 8, v138
	v_lshrrev_b32_e32 v178, 8, v181
	v_lshl_add_u32 v138, v178, 19, v138
	s_lshl_b32 s20, s46, 20
	v_add_u32_e32 v138, s20, v138
	s_lshl_b32 s20, s6, 10
	v_add_u32_e32 v138, s20, v138
	s_mov_b32 s48, s78
	s_mov_b32 s49, s79
	s_mov_b32 s50, s78
	s_mov_b32 s51, s79
	global_load_dwordx4 v[130:133], v138, s[48:49] nt
	s_add_u32 s48, s48, 0x4000
	s_addc_u32 s49, s49, 0
	global_load_dwordx4 v[134:137], v138, s[48:49] nt
	s_add_u32 s48, s48, 0x4000
	s_addc_u32 s49, s49, 0
	global_load_dwordx4 v[142:145], v138, s[48:49] nt
	s_add_u32 s48, s48, 0x4000
	s_addc_u32 s49, s49, 0
	global_load_dwordx4 v[146:149], v138, s[48:49] nt
	s_add_u32 s48, s48, 0x4000
	s_addc_u32 s49, s49, 0
	global_load_dwordx4 v[150:153], v138, s[48:49] nt
	s_add_u32 s48, s48, 0x4000
	s_addc_u32 s49, s49, 0
	global_load_dwordx4 v[154:157], v138, s[48:49] nt
	s_add_u32 s48, s48, 0x4000
	s_addc_u32 s49, s49, 0
	global_load_dwordx4 v[158:161], v138, s[48:49] nt
	s_add_u32 s48, s48, 0x4000
	s_addc_u32 s49, s49, 0
	global_load_dwordx4 v[162:165], v138, s[48:49] nt
	s_add_u32 s48, s48, 0x4000
	s_addc_u32 s49, s49, 0
	global_load_dwordx4 v[166:169], v138, s[48:49] nt
	s_add_u32 s48, s48, 0x4000
	s_addc_u32 s49, s49, 0
	global_load_dwordx4 v[170:173], v138, s[48:49] nt
	s_add_u32 s48, s48, 0x4000
	s_addc_u32 s49, s49, 0
	global_load_dwordx4 v[174:177], v138, s[48:49] nt
	s_add_u32 s48, s48, 0x4000
	s_addc_u32 s49, s49, 0
	global_load_dwordx4 v[182:185], v138, s[48:49] nt
	s_add_u32 s48, s48, 0x4000
	s_addc_u32 s49, s49, 0
	global_load_dwordx4 v[186:189], v138, s[48:49] nt
	s_add_u32 s48, s48, 0x4000
	s_addc_u32 s49, s49, 0
	global_load_dwordx4 v[190:193], v138, s[48:49] nt
	s_add_u32 s48, s48, 0x4000
	s_addc_u32 s49, s49, 0
	global_load_dwordx4 v[194:197], v138, s[48:49] nt
	s_add_u32 s48, s48, 0x4000
	s_addc_u32 s49, s49, 0
	global_load_dwordx4 v[198:201], v138, s[48:49] nt
	s_add_u32 s48, s48, 0x4000
	s_addc_u32 s49, s49, 0
	ds_write_b32 v139, v124
	ds_write_b32 v139, v125 offset:272
	ds_write_b32 v139, v126 offset:544
	ds_write_b32 v139, v127 offset:816
	ds_write_b32 v139, v120 offset:64
	ds_write_b32 v139, v121 offset:336
	ds_write_b32 v139, v122 offset:608
	ds_write_b32 v139, v123 offset:880
	ds_write_b32 v139, v116 offset:128
	ds_write_b32 v139, v117 offset:400
	ds_write_b32 v139, v118 offset:672
	ds_write_b32 v139, v119 offset:944
	ds_write_b32 v139, v112 offset:192
	ds_write_b32 v139, v113 offset:464
	ds_write_b32 v139, v114 offset:736
	ds_write_b32 v139, v115 offset:1008
	ds_write_b32 v139, v108 offset:4352
	ds_write_b32 v139, v109 offset:4624
	ds_write_b32 v139, v110 offset:4896
	ds_write_b32 v139, v111 offset:5168
	ds_write_b32 v139, v104 offset:4416
	ds_write_b32 v139, v105 offset:4688
	ds_write_b32 v139, v106 offset:4960
	ds_write_b32 v139, v107 offset:5232
	ds_write_b32 v139, v100 offset:4480
	ds_write_b32 v139, v101 offset:4752
	ds_write_b32 v139, v102 offset:5024
	ds_write_b32 v139, v103 offset:5296
	ds_write_b32 v139, v96 offset:4544
	ds_write_b32 v139, v97 offset:4816
	ds_write_b32 v139, v98 offset:5088
	ds_write_b32 v139, v99 offset:5360
	ds_write_b32 v139, v92 offset:8704
	ds_write_b32 v139, v93 offset:8976
	ds_write_b32 v139, v94 offset:9248
	ds_write_b32 v139, v95 offset:9520
	ds_write_b32 v139, v88 offset:8768
	ds_write_b32 v139, v89 offset:9040
	ds_write_b32 v139, v90 offset:9312
	ds_write_b32 v139, v91 offset:9584
	ds_write_b32 v139, v84 offset:8832
	ds_write_b32 v139, v85 offset:9104
	ds_write_b32 v139, v86 offset:9376
	ds_write_b32 v139, v87 offset:9648
	ds_write_b32 v139, v80 offset:8896
	ds_write_b32 v139, v81 offset:9168
	ds_write_b32 v139, v82 offset:9440
	ds_write_b32 v139, v83 offset:9712
	ds_write_b32 v139, v76 offset:13056
	ds_write_b32 v139, v77 offset:13328
	ds_write_b32 v139, v78 offset:13600
	ds_write_b32 v139, v79 offset:13872
	ds_write_b32 v139, v72 offset:13120
	ds_write_b32 v139, v73 offset:13392
	ds_write_b32 v139, v74 offset:13664
	ds_write_b32 v139, v75 offset:13936
	ds_write_b32 v139, v68 offset:13184
	ds_write_b32 v139, v69 offset:13456
	ds_write_b32 v139, v70 offset:13728
	ds_write_b32 v139, v71 offset:14000
	ds_write_b32 v139, v64 offset:13248
	ds_write_b32 v139, v65 offset:13520
	ds_write_b32 v139, v66 offset:13792
	ds_write_b32 v139, v67 offset:14064
	s_waitcnt lgkmcnt(0)
	ds_read_b128 v[202:205], v141
	ds_read_b128 v[206:209], v141 offset:1088
	ds_read_b128 v[210:213], v141 offset:2176
	ds_read_b128 v[214:217], v141 offset:3264
	ds_read_b128 v[218:221], v141 offset:4352
	ds_read_b128 v[222:225], v141 offset:5440
	ds_read_b128 v[226:229], v141 offset:6528
	ds_read_b128 v[230:233], v141 offset:7616
	s_waitcnt vmcnt(15) lgkmcnt(7)
	v_pk_add_f32 v[130:131], v[130:131], v[202:203]
	v_pk_add_f32 v[132:133], v[132:133], v[204:205]
	global_store_dwordx4 v138, v[130:133], s[50:51] sc1
	s_add_u32 s50, s50, 0x4000
	s_addc_u32 s51, s51, 0
	s_waitcnt vmcnt(15) lgkmcnt(6)
	v_pk_add_f32 v[134:135], v[134:135], v[206:207]
	v_pk_add_f32 v[136:137], v[136:137], v[208:209]
	global_store_dwordx4 v138, v[134:137], s[50:51] sc1
	s_add_u32 s50, s50, 0x4000
	s_addc_u32 s51, s51, 0
	s_waitcnt vmcnt(15) lgkmcnt(5)
	v_pk_add_f32 v[142:143], v[142:143], v[210:211]
	v_pk_add_f32 v[144:145], v[144:145], v[212:213]
	global_store_dwordx4 v138, v[142:145], s[50:51] sc1
	s_add_u32 s50, s50, 0x4000
	s_addc_u32 s51, s51, 0
	s_waitcnt vmcnt(15) lgkmcnt(4)
	v_pk_add_f32 v[146:147], v[146:147], v[214:215]
	v_pk_add_f32 v[148:149], v[148:149], v[216:217]
	global_store_dwordx4 v138, v[146:149], s[50:51] sc1
	s_add_u32 s50, s50, 0x4000
	s_addc_u32 s51, s51, 0
	s_waitcnt vmcnt(15) lgkmcnt(3)
	v_pk_add_f32 v[150:151], v[150:151], v[218:219]
	v_pk_add_f32 v[152:153], v[152:153], v[220:221]
	global_store_dwordx4 v138, v[150:153], s[50:51] sc1
	s_add_u32 s50, s50, 0x4000
	s_addc_u32 s51, s51, 0
	s_waitcnt vmcnt(15) lgkmcnt(2)
	v_pk_add_f32 v[154:155], v[154:155], v[222:223]
	v_pk_add_f32 v[156:157], v[156:157], v[224:225]
	global_store_dwordx4 v138, v[154:157], s[50:51] sc1
	s_add_u32 s50, s50, 0x4000
	s_addc_u32 s51, s51, 0
	s_waitcnt vmcnt(15) lgkmcnt(1)
	v_pk_add_f32 v[158:159], v[158:159], v[226:227]
	v_pk_add_f32 v[160:161], v[160:161], v[228:229]
	global_store_dwordx4 v138, v[158:161], s[50:51] sc1
	s_add_u32 s50, s50, 0x4000
	s_addc_u32 s51, s51, 0
	s_waitcnt vmcnt(15) lgkmcnt(0)
	v_pk_add_f32 v[162:163], v[162:163], v[230:231]
	v_pk_add_f32 v[164:165], v[164:165], v[232:233]
	global_store_dwordx4 v138, v[162:165], s[50:51] sc1
	s_add_u32 s50, s50, 0x4000
	s_addc_u32 s51, s51, 0
	global_load_dwordx4 v[130:133], v138, s[48:49] nt
	s_add_u32 s48, s48, 0x4000
	s_addc_u32 s49, s49, 0
	global_load_dwordx4 v[134:137], v138, s[48:49] nt
	s_add_u32 s48, s48, 0x4000
	s_addc_u32 s49, s49, 0
	global_load_dwordx4 v[142:145], v138, s[48:49] nt
	s_add_u32 s48, s48, 0x4000
	s_addc_u32 s49, s49, 0
	global_load_dwordx4 v[146:149], v138, s[48:49] nt
	s_add_u32 s48, s48, 0x4000
	s_addc_u32 s49, s49, 0
	global_load_dwordx4 v[150:153], v138, s[48:49] nt
	s_add_u32 s48, s48, 0x4000
	s_addc_u32 s49, s49, 0
	global_load_dwordx4 v[154:157], v138, s[48:49] nt
	s_add_u32 s48, s48, 0x4000
	s_addc_u32 s49, s49, 0
	global_load_dwordx4 v[158:161], v138, s[48:49] nt
	s_add_u32 s48, s48, 0x4000
	s_addc_u32 s49, s49, 0
	global_load_dwordx4 v[162:165], v138, s[48:49] nt
	s_add_u32 s48, s48, 0x4000
	s_addc_u32 s49, s49, 0
	ds_read_b128 v[202:205], v141 offset:8704
	ds_read_b128 v[206:209], v141 offset:9792
	ds_read_b128 v[210:213], v141 offset:10880
	ds_read_b128 v[214:217], v141 offset:11968
	ds_read_b128 v[218:221], v141 offset:13056
	ds_read_b128 v[222:225], v141 offset:14144
	ds_read_b128 v[226:229], v141 offset:15232
	ds_read_b128 v[230:233], v141 offset:16320
	s_waitcnt vmcnt(15) lgkmcnt(7)
	v_pk_add_f32 v[166:167], v[166:167], v[202:203]
	v_pk_add_f32 v[168:169], v[168:169], v[204:205]
	global_store_dwordx4 v138, v[166:169], s[50:51] sc1
	s_add_u32 s50, s50, 0x4000
	s_addc_u32 s51, s51, 0
	s_waitcnt vmcnt(15) lgkmcnt(6)
	v_pk_add_f32 v[170:171], v[170:171], v[206:207]
	v_pk_add_f32 v[172:173], v[172:173], v[208:209]
	global_store_dwordx4 v138, v[170:173], s[50:51] sc1
	s_add_u32 s50, s50, 0x4000
	s_addc_u32 s51, s51, 0
	s_waitcnt vmcnt(15) lgkmcnt(5)
	v_pk_add_f32 v[174:175], v[174:175], v[210:211]
	v_pk_add_f32 v[176:177], v[176:177], v[212:213]
	global_store_dwordx4 v138, v[174:177], s[50:51] sc1
	s_add_u32 s50, s50, 0x4000
	s_addc_u32 s51, s51, 0
	s_waitcnt vmcnt(15) lgkmcnt(4)
	v_pk_add_f32 v[182:183], v[182:183], v[214:215]
	v_pk_add_f32 v[184:185], v[184:185], v[216:217]
	global_store_dwordx4 v138, v[182:185], s[50:51] sc1
	s_add_u32 s50, s50, 0x4000
	s_addc_u32 s51, s51, 0
	s_waitcnt vmcnt(15) lgkmcnt(3)
	v_pk_add_f32 v[186:187], v[186:187], v[218:219]
	v_pk_add_f32 v[188:189], v[188:189], v[220:221]
	global_store_dwordx4 v138, v[186:189], s[50:51] sc1
	s_add_u32 s50, s50, 0x4000
	s_addc_u32 s51, s51, 0
	s_waitcnt vmcnt(15) lgkmcnt(2)
	v_pk_add_f32 v[190:191], v[190:191], v[222:223]
	v_pk_add_f32 v[192:193], v[192:193], v[224:225]
	global_store_dwordx4 v138, v[190:193], s[50:51] sc1
	s_add_u32 s50, s50, 0x4000
	s_addc_u32 s51, s51, 0
	s_waitcnt vmcnt(15) lgkmcnt(1)
	v_pk_add_f32 v[194:195], v[194:195], v[226:227]
	v_pk_add_f32 v[196:197], v[196:197], v[228:229]
	global_store_dwordx4 v138, v[194:197], s[50:51] sc1
	s_add_u32 s50, s50, 0x4000
	s_addc_u32 s51, s51, 0
	s_waitcnt vmcnt(15) lgkmcnt(0)
	v_pk_add_f32 v[198:199], v[198:199], v[230:231]
	v_pk_add_f32 v[200:201], v[200:201], v[232:233]
	global_store_dwordx4 v138, v[198:201], s[50:51] sc1
	s_add_u32 s50, s50, 0x4000
	s_addc_u32 s51, s51, 0
	s_waitcnt lgkmcnt(0)
	global_load_dwordx4 v[166:169], v138, s[48:49] nt
	s_add_u32 s48, s48, 0x4000
	s_addc_u32 s49, s49, 0
	global_load_dwordx4 v[170:173], v138, s[48:49] nt
	s_add_u32 s48, s48, 0x4000
	s_addc_u32 s49, s49, 0
	global_load_dwordx4 v[174:177], v138, s[48:49] nt
	s_add_u32 s48, s48, 0x4000
	s_addc_u32 s49, s49, 0
	global_load_dwordx4 v[182:185], v138, s[48:49] nt
	s_add_u32 s48, s48, 0x4000
	s_addc_u32 s49, s49, 0
	global_load_dwordx4 v[186:189], v138, s[48:49] nt
	s_add_u32 s48, s48, 0x4000
	s_addc_u32 s49, s49, 0
	global_load_dwordx4 v[190:193], v138, s[48:49] nt
	s_add_u32 s48, s48, 0x4000
	s_addc_u32 s49, s49, 0
	global_load_dwordx4 v[194:197], v138, s[48:49] nt
	s_add_u32 s48, s48, 0x4000
	s_addc_u32 s49, s49, 0
	global_load_dwordx4 v[198:201], v138, s[48:49] nt
	s_add_u32 s48, s48, 0x4000
	s_addc_u32 s49, s49, 0
	ds_write_b32 v139, v60
	ds_write_b32 v139, v61 offset:272
	ds_write_b32 v139, v62 offset:544
	ds_write_b32 v139, v63 offset:816
	ds_write_b32 v139, v56 offset:64
	ds_write_b32 v139, v57 offset:336
	ds_write_b32 v139, v58 offset:608
	ds_write_b32 v139, v59 offset:880
	ds_write_b32 v139, v52 offset:128
	ds_write_b32 v139, v53 offset:400
	ds_write_b32 v139, v54 offset:672
	ds_write_b32 v139, v55 offset:944
	ds_write_b32 v139, v48 offset:192
	ds_write_b32 v139, v49 offset:464
	ds_write_b32 v139, v50 offset:736
	ds_write_b32 v139, v51 offset:1008
	ds_write_b32 v139, v44 offset:4352
	ds_write_b32 v139, v45 offset:4624
	ds_write_b32 v139, v46 offset:4896
	ds_write_b32 v139, v47 offset:5168
	ds_write_b32 v139, v32 offset:4416
	ds_write_b32 v139, v33 offset:4688
	ds_write_b32 v139, v34 offset:4960
	ds_write_b32 v139, v35 offset:5232
	ds_write_b32 v139, v28 offset:4480
	ds_write_b32 v139, v29 offset:4752
	ds_write_b32 v139, v30 offset:5024
	ds_write_b32 v139, v31 offset:5296
	ds_write_b32 v139, v24 offset:4544
	ds_write_b32 v139, v25 offset:4816
	ds_write_b32 v139, v26 offset:5088
	ds_write_b32 v139, v27 offset:5360
	ds_write_b32 v139, v20 offset:8704
	ds_write_b32 v139, v21 offset:8976
	ds_write_b32 v139, v22 offset:9248
	ds_write_b32 v139, v23 offset:9520
	ds_write_b32 v139, v16 offset:8768
	ds_write_b32 v139, v17 offset:9040
	ds_write_b32 v139, v18 offset:9312
	ds_write_b32 v139, v19 offset:9584
	ds_write_b32 v139, v12 offset:8832
	ds_write_b32 v139, v13 offset:9104
	ds_write_b32 v139, v14 offset:9376
	ds_write_b32 v139, v15 offset:9648
	ds_write_b32 v139, v8 offset:8896
	ds_write_b32 v139, v9 offset:9168
	ds_write_b32 v139, v10 offset:9440
	ds_write_b32 v139, v11 offset:9712
	ds_write_b32 v139, v4 offset:13056
	ds_write_b32 v139, v5 offset:13328
	ds_write_b32 v139, v6 offset:13600
	ds_write_b32 v139, v7 offset:13872
	ds_write_b32 v139, v0 offset:13120
	ds_write_b32 v139, v1 offset:13392
	ds_write_b32 v139, v2 offset:13664
	ds_write_b32 v139, v3 offset:13936
	ds_write_b32 v139, v40 offset:13184
	ds_write_b32 v139, v41 offset:13456
	ds_write_b32 v139, v42 offset:13728
	ds_write_b32 v139, v43 offset:14000
	ds_write_b32 v139, v36 offset:13248
	ds_write_b32 v139, v37 offset:13520
	ds_write_b32 v139, v38 offset:13792
	ds_write_b32 v139, v39 offset:14064
	s_waitcnt lgkmcnt(0)
	ds_read_b128 v[202:205], v141
	ds_read_b128 v[206:209], v141 offset:1088
	ds_read_b128 v[210:213], v141 offset:2176
	ds_read_b128 v[214:217], v141 offset:3264
	ds_read_b128 v[218:221], v141 offset:4352
	ds_read_b128 v[222:225], v141 offset:5440
	ds_read_b128 v[226:229], v141 offset:6528
	ds_read_b128 v[230:233], v141 offset:7616
	s_waitcnt vmcnt(15) lgkmcnt(7)
	v_pk_add_f32 v[130:131], v[130:131], v[202:203]
	v_pk_add_f32 v[132:133], v[132:133], v[204:205]
	global_store_dwordx4 v138, v[130:133], s[50:51] sc1
	s_add_u32 s50, s50, 0x4000
	s_addc_u32 s51, s51, 0
	s_waitcnt vmcnt(15) lgkmcnt(6)
	v_pk_add_f32 v[134:135], v[134:135], v[206:207]
	v_pk_add_f32 v[136:137], v[136:137], v[208:209]
	global_store_dwordx4 v138, v[134:137], s[50:51] sc1
	s_add_u32 s50, s50, 0x4000
	s_addc_u32 s51, s51, 0
	s_waitcnt vmcnt(15) lgkmcnt(5)
	v_pk_add_f32 v[142:143], v[142:143], v[210:211]
	v_pk_add_f32 v[144:145], v[144:145], v[212:213]
	global_store_dwordx4 v138, v[142:145], s[50:51] sc1
	s_add_u32 s50, s50, 0x4000
	s_addc_u32 s51, s51, 0
	s_waitcnt vmcnt(15) lgkmcnt(4)
	v_pk_add_f32 v[146:147], v[146:147], v[214:215]
	v_pk_add_f32 v[148:149], v[148:149], v[216:217]
	global_store_dwordx4 v138, v[146:149], s[50:51] sc1
	s_add_u32 s50, s50, 0x4000
	s_addc_u32 s51, s51, 0
	s_waitcnt vmcnt(15) lgkmcnt(3)
	v_pk_add_f32 v[150:151], v[150:151], v[218:219]
	v_pk_add_f32 v[152:153], v[152:153], v[220:221]
	global_store_dwordx4 v138, v[150:153], s[50:51] sc1
	s_add_u32 s50, s50, 0x4000
	s_addc_u32 s51, s51, 0
	s_waitcnt vmcnt(15) lgkmcnt(2)
	v_pk_add_f32 v[154:155], v[154:155], v[222:223]
	v_pk_add_f32 v[156:157], v[156:157], v[224:225]
	global_store_dwordx4 v138, v[154:157], s[50:51] sc1
	s_add_u32 s50, s50, 0x4000
	s_addc_u32 s51, s51, 0
	s_waitcnt vmcnt(15) lgkmcnt(1)
	v_pk_add_f32 v[158:159], v[158:159], v[226:227]
	v_pk_add_f32 v[160:161], v[160:161], v[228:229]
	global_store_dwordx4 v138, v[158:161], s[50:51] sc1
	s_add_u32 s50, s50, 0x4000
	s_addc_u32 s51, s51, 0
	s_waitcnt vmcnt(15) lgkmcnt(0)
	v_pk_add_f32 v[162:163], v[162:163], v[230:231]
	v_pk_add_f32 v[164:165], v[164:165], v[232:233]
	global_store_dwordx4 v138, v[162:165], s[50:51] sc1
	s_add_u32 s50, s50, 0x4000
	s_addc_u32 s51, s51, 0
	ds_read_b128 v[202:205], v141 offset:8704
	ds_read_b128 v[206:209], v141 offset:9792
	ds_read_b128 v[210:213], v141 offset:10880
	ds_read_b128 v[214:217], v141 offset:11968
	ds_read_b128 v[218:221], v141 offset:13056
	ds_read_b128 v[222:225], v141 offset:14144
	ds_read_b128 v[226:229], v141 offset:15232
	ds_read_b128 v[230:233], v141 offset:16320
	s_waitcnt vmcnt(7) lgkmcnt(7)
	v_pk_add_f32 v[166:167], v[166:167], v[202:203]
	v_pk_add_f32 v[168:169], v[168:169], v[204:205]
	global_store_dwordx4 v138, v[166:169], s[50:51] sc1
	s_add_u32 s50, s50, 0x4000
	s_addc_u32 s51, s51, 0
	s_waitcnt vmcnt(7) lgkmcnt(6)
	v_pk_add_f32 v[170:171], v[170:171], v[206:207]
	v_pk_add_f32 v[172:173], v[172:173], v[208:209]
	global_store_dwordx4 v138, v[170:173], s[50:51] sc1
	s_add_u32 s50, s50, 0x4000
	s_addc_u32 s51, s51, 0
	s_waitcnt vmcnt(7) lgkmcnt(5)
	v_pk_add_f32 v[174:175], v[174:175], v[210:211]
	v_pk_add_f32 v[176:177], v[176:177], v[212:213]
	global_store_dwordx4 v138, v[174:177], s[50:51] sc1
	s_add_u32 s50, s50, 0x4000
	s_addc_u32 s51, s51, 0
	s_waitcnt vmcnt(7) lgkmcnt(4)
	v_pk_add_f32 v[182:183], v[182:183], v[214:215]
	v_pk_add_f32 v[184:185], v[184:185], v[216:217]
	global_store_dwordx4 v138, v[182:185], s[50:51] sc1
	s_add_u32 s50, s50, 0x4000
	s_addc_u32 s51, s51, 0
	s_waitcnt vmcnt(7) lgkmcnt(3)
	v_pk_add_f32 v[186:187], v[186:187], v[218:219]
	v_pk_add_f32 v[188:189], v[188:189], v[220:221]
	global_store_dwordx4 v138, v[186:189], s[50:51] sc1
	s_add_u32 s50, s50, 0x4000
	s_addc_u32 s51, s51, 0
	s_waitcnt vmcnt(7) lgkmcnt(2)
	v_pk_add_f32 v[190:191], v[190:191], v[222:223]
	v_pk_add_f32 v[192:193], v[192:193], v[224:225]
	global_store_dwordx4 v138, v[190:193], s[50:51] sc1
	s_add_u32 s50, s50, 0x4000
	s_addc_u32 s51, s51, 0
	s_waitcnt vmcnt(7) lgkmcnt(1)
	v_pk_add_f32 v[194:195], v[194:195], v[226:227]
	v_pk_add_f32 v[196:197], v[196:197], v[228:229]
	global_store_dwordx4 v138, v[194:197], s[50:51] sc1
	s_add_u32 s50, s50, 0x4000
	s_addc_u32 s51, s51, 0
	s_waitcnt vmcnt(7) lgkmcnt(0)
	v_pk_add_f32 v[198:199], v[198:199], v[230:231]
	v_pk_add_f32 v[200:201], v[200:201], v[232:233]
	global_store_dwordx4 v138, v[198:201], s[50:51] sc1
	s_add_u32 s50, s50, 0x4000
	s_addc_u32 s51, s51, 0
	s_cmpk_lt_i32 s60, 0x100
	s_cbranch_scc0 .LBB0_752

.LBB0_1330:
	s_add_i32 s58, s58, s82
	s_add_i32 s57, s57, s82
	v_and_b32_e32 v178, 15, v181
	v_bfe_u32 v138, v181, 4, 2
	v_lshlrev_b32_e32 v141, 4, v178
	s_movk_i32 s20, 0x110
	v_mad_u32_u24 v141, v138, s20, v141
	v_lshlrev_b32_e32 v139, 2, v178
	s_movk_i32 s20, 0x440
	v_mad_u32_u24 v139, v138, s20, v139
	v_lshlrev_b32_e32 v138, 12, v138
	v_lshl_add_u32 v138, v178, 4, v138
	v_lshrrev_b32_e32 v178, 6, v181
	v_mul_u32_u24_e32 v178, 0x4400, v178
	v_add_u32_e32 v141, v141, v178
	v_add_u32_e32 v139, v139, v178
	v_bfe_u32 v178, v181, 6, 2
	v_lshl_add_u32 v138, v178, 8, v138
	v_lshrrev_b32_e32 v178, 8, v181
	v_lshl_add_u32 v138, v178, 19, v138
	s_lshl_b32 s20, s42, 20
	v_add_u32_e32 v138, s20, v138
	s_lshl_b32 s20, s4, 10
	v_add_u32_e32 v138, s20, v138
	s_mov_b32 s44, s78
	s_mov_b32 s45, s79
	s_mov_b32 s46, s78
	s_mov_b32 s47, s79
	global_load_dwordx4 v[130:133], v138, s[44:45] nt
	s_add_u32 s44, s44, 0x4000
	s_addc_u32 s45, s45, 0
	global_load_dwordx4 v[134:137], v138, s[44:45] nt
	s_add_u32 s44, s44, 0x4000
	s_addc_u32 s45, s45, 0
	global_load_dwordx4 v[142:145], v138, s[44:45] nt
	s_add_u32 s44, s44, 0x4000
	s_addc_u32 s45, s45, 0
	global_load_dwordx4 v[146:149], v138, s[44:45] nt
	s_add_u32 s44, s44, 0x4000
	s_addc_u32 s45, s45, 0
	global_load_dwordx4 v[150:153], v138, s[44:45] nt
	s_add_u32 s44, s44, 0x4000
	s_addc_u32 s45, s45, 0
	global_load_dwordx4 v[154:157], v138, s[44:45] nt
	s_add_u32 s44, s44, 0x4000
	s_addc_u32 s45, s45, 0
	global_load_dwordx4 v[158:161], v138, s[44:45] nt
	s_add_u32 s44, s44, 0x4000
	s_addc_u32 s45, s45, 0
	global_load_dwordx4 v[162:165], v138, s[44:45] nt
	s_add_u32 s44, s44, 0x4000
	s_addc_u32 s45, s45, 0
	global_load_dwordx4 v[166:169], v138, s[44:45] nt
	s_add_u32 s44, s44, 0x4000
	s_addc_u32 s45, s45, 0
	global_load_dwordx4 v[170:173], v138, s[44:45] nt
	s_add_u32 s44, s44, 0x4000
	s_addc_u32 s45, s45, 0
	global_load_dwordx4 v[174:177], v138, s[44:45] nt
	s_add_u32 s44, s44, 0x4000
	s_addc_u32 s45, s45, 0
	global_load_dwordx4 v[182:185], v138, s[44:45] nt
	s_add_u32 s44, s44, 0x4000
	s_addc_u32 s45, s45, 0
	global_load_dwordx4 v[186:189], v138, s[44:45] nt
	s_add_u32 s44, s44, 0x4000
	s_addc_u32 s45, s45, 0
	global_load_dwordx4 v[190:193], v138, s[44:45] nt
	s_add_u32 s44, s44, 0x4000
	s_addc_u32 s45, s45, 0
	global_load_dwordx4 v[194:197], v138, s[44:45] nt
	s_add_u32 s44, s44, 0x4000
	s_addc_u32 s45, s45, 0
	global_load_dwordx4 v[198:201], v138, s[44:45] nt
	s_add_u32 s44, s44, 0x4000
	s_addc_u32 s45, s45, 0
	ds_write_b32 v139, v124
	ds_write_b32 v139, v125 offset:272
	ds_write_b32 v139, v126 offset:544
	ds_write_b32 v139, v127 offset:816
	ds_write_b32 v139, v120 offset:64
	ds_write_b32 v139, v121 offset:336
	ds_write_b32 v139, v122 offset:608
	ds_write_b32 v139, v123 offset:880
	ds_write_b32 v139, v116 offset:128
	ds_write_b32 v139, v117 offset:400
	ds_write_b32 v139, v118 offset:672
	ds_write_b32 v139, v119 offset:944
	ds_write_b32 v139, v112 offset:192
	ds_write_b32 v139, v113 offset:464
	ds_write_b32 v139, v114 offset:736
	ds_write_b32 v139, v115 offset:1008
	ds_write_b32 v139, v108 offset:4352
	ds_write_b32 v139, v109 offset:4624
	ds_write_b32 v139, v110 offset:4896
	ds_write_b32 v139, v111 offset:5168
	ds_write_b32 v139, v104 offset:4416
	ds_write_b32 v139, v105 offset:4688
	ds_write_b32 v139, v106 offset:4960
	ds_write_b32 v139, v107 offset:5232
	ds_write_b32 v139, v100 offset:4480
	ds_write_b32 v139, v101 offset:4752
	ds_write_b32 v139, v102 offset:5024
	ds_write_b32 v139, v103 offset:5296
	ds_write_b32 v139, v96 offset:4544
	ds_write_b32 v139, v97 offset:4816
	ds_write_b32 v139, v98 offset:5088
	ds_write_b32 v139, v99 offset:5360
	ds_write_b32 v139, v92 offset:8704
	ds_write_b32 v139, v93 offset:8976
	ds_write_b32 v139, v94 offset:9248
	ds_write_b32 v139, v95 offset:9520
	ds_write_b32 v139, v88 offset:8768
	ds_write_b32 v139, v89 offset:9040
	ds_write_b32 v139, v90 offset:9312
	ds_write_b32 v139, v91 offset:9584
	ds_write_b32 v139, v84 offset:8832
	ds_write_b32 v139, v85 offset:9104
	ds_write_b32 v139, v86 offset:9376
	ds_write_b32 v139, v87 offset:9648
	ds_write_b32 v139, v80 offset:8896
	ds_write_b32 v139, v81 offset:9168
	ds_write_b32 v139, v82 offset:9440
	ds_write_b32 v139, v83 offset:9712
	ds_write_b32 v139, v76 offset:13056
	ds_write_b32 v139, v77 offset:13328
	ds_write_b32 v139, v78 offset:13600
	ds_write_b32 v139, v79 offset:13872
	ds_write_b32 v139, v72 offset:13120
	ds_write_b32 v139, v73 offset:13392
	ds_write_b32 v139, v74 offset:13664
	ds_write_b32 v139, v75 offset:13936
	ds_write_b32 v139, v68 offset:13184
	ds_write_b32 v139, v69 offset:13456
	ds_write_b32 v139, v70 offset:13728
	ds_write_b32 v139, v71 offset:14000
	ds_write_b32 v139, v64 offset:13248
	ds_write_b32 v139, v65 offset:13520
	ds_write_b32 v139, v66 offset:13792
	ds_write_b32 v139, v67 offset:14064
	s_waitcnt lgkmcnt(0)
	ds_read_b128 v[202:205], v141
	ds_read_b128 v[206:209], v141 offset:1088
	ds_read_b128 v[210:213], v141 offset:2176
	ds_read_b128 v[214:217], v141 offset:3264
	ds_read_b128 v[218:221], v141 offset:4352
	ds_read_b128 v[222:225], v141 offset:5440
	ds_read_b128 v[226:229], v141 offset:6528
	ds_read_b128 v[230:233], v141 offset:7616
	s_waitcnt vmcnt(15) lgkmcnt(7)
	v_pk_add_f32 v[130:131], v[130:131], v[202:203]
	v_pk_add_f32 v[132:133], v[132:133], v[204:205]
	global_store_dwordx4 v138, v[130:133], s[46:47] sc1
	s_add_u32 s46, s46, 0x4000
	s_addc_u32 s47, s47, 0
	s_waitcnt vmcnt(15) lgkmcnt(6)
	v_pk_add_f32 v[134:135], v[134:135], v[206:207]
	v_pk_add_f32 v[136:137], v[136:137], v[208:209]
	global_store_dwordx4 v138, v[134:137], s[46:47] sc1
	s_add_u32 s46, s46, 0x4000
	s_addc_u32 s47, s47, 0
	s_waitcnt vmcnt(15) lgkmcnt(5)
	v_pk_add_f32 v[142:143], v[142:143], v[210:211]
	v_pk_add_f32 v[144:145], v[144:145], v[212:213]
	global_store_dwordx4 v138, v[142:145], s[46:47] sc1
	s_add_u32 s46, s46, 0x4000
	s_addc_u32 s47, s47, 0
	s_waitcnt vmcnt(15) lgkmcnt(4)
	v_pk_add_f32 v[146:147], v[146:147], v[214:215]
	v_pk_add_f32 v[148:149], v[148:149], v[216:217]
	global_store_dwordx4 v138, v[146:149], s[46:47] sc1
	s_add_u32 s46, s46, 0x4000
	s_addc_u32 s47, s47, 0
	s_waitcnt vmcnt(15) lgkmcnt(3)
	v_pk_add_f32 v[150:151], v[150:151], v[218:219]
	v_pk_add_f32 v[152:153], v[152:153], v[220:221]
	global_store_dwordx4 v138, v[150:153], s[46:47] sc1
	s_add_u32 s46, s46, 0x4000
	s_addc_u32 s47, s47, 0
	s_waitcnt vmcnt(15) lgkmcnt(2)
	v_pk_add_f32 v[154:155], v[154:155], v[222:223]
	v_pk_add_f32 v[156:157], v[156:157], v[224:225]
	global_store_dwordx4 v138, v[154:157], s[46:47] sc1
	s_add_u32 s46, s46, 0x4000
	s_addc_u32 s47, s47, 0
	s_waitcnt vmcnt(15) lgkmcnt(1)
	v_pk_add_f32 v[158:159], v[158:159], v[226:227]
	v_pk_add_f32 v[160:161], v[160:161], v[228:229]
	global_store_dwordx4 v138, v[158:161], s[46:47] sc1
	s_add_u32 s46, s46, 0x4000
	s_addc_u32 s47, s47, 0
	s_waitcnt vmcnt(15) lgkmcnt(0)
	v_pk_add_f32 v[162:163], v[162:163], v[230:231]
	v_pk_add_f32 v[164:165], v[164:165], v[232:233]
	global_store_dwordx4 v138, v[162:165], s[46:47] sc1
	s_add_u32 s46, s46, 0x4000
	s_addc_u32 s47, s47, 0
	global_load_dwordx4 v[130:133], v138, s[44:45] nt
	s_add_u32 s44, s44, 0x4000
	s_addc_u32 s45, s45, 0
	global_load_dwordx4 v[134:137], v138, s[44:45] nt
	s_add_u32 s44, s44, 0x4000
	s_addc_u32 s45, s45, 0
	global_load_dwordx4 v[142:145], v138, s[44:45] nt
	s_add_u32 s44, s44, 0x4000
	s_addc_u32 s45, s45, 0
	global_load_dwordx4 v[146:149], v138, s[44:45] nt
	s_add_u32 s44, s44, 0x4000
	s_addc_u32 s45, s45, 0
	global_load_dwordx4 v[150:153], v138, s[44:45] nt
	s_add_u32 s44, s44, 0x4000
	s_addc_u32 s45, s45, 0
	global_load_dwordx4 v[154:157], v138, s[44:45] nt
	s_add_u32 s44, s44, 0x4000
	s_addc_u32 s45, s45, 0
	global_load_dwordx4 v[158:161], v138, s[44:45] nt
	s_add_u32 s44, s44, 0x4000
	s_addc_u32 s45, s45, 0
	global_load_dwordx4 v[162:165], v138, s[44:45] nt
	s_add_u32 s44, s44, 0x4000
	s_addc_u32 s45, s45, 0
	ds_read_b128 v[202:205], v141 offset:8704
	ds_read_b128 v[206:209], v141 offset:9792
	ds_read_b128 v[210:213], v141 offset:10880
	ds_read_b128 v[214:217], v141 offset:11968
	ds_read_b128 v[218:221], v141 offset:13056
	ds_read_b128 v[222:225], v141 offset:14144
	ds_read_b128 v[226:229], v141 offset:15232
	ds_read_b128 v[230:233], v141 offset:16320
	s_waitcnt vmcnt(15) lgkmcnt(7)
	v_pk_add_f32 v[166:167], v[166:167], v[202:203]
	v_pk_add_f32 v[168:169], v[168:169], v[204:205]
	global_store_dwordx4 v138, v[166:169], s[46:47] sc1
	s_add_u32 s46, s46, 0x4000
	s_addc_u32 s47, s47, 0
	s_waitcnt vmcnt(15) lgkmcnt(6)
	v_pk_add_f32 v[170:171], v[170:171], v[206:207]
	v_pk_add_f32 v[172:173], v[172:173], v[208:209]
	global_store_dwordx4 v138, v[170:173], s[46:47] sc1
	s_add_u32 s46, s46, 0x4000
	s_addc_u32 s47, s47, 0
	s_waitcnt vmcnt(15) lgkmcnt(5)
	v_pk_add_f32 v[174:175], v[174:175], v[210:211]
	v_pk_add_f32 v[176:177], v[176:177], v[212:213]
	global_store_dwordx4 v138, v[174:177], s[46:47] sc1
	s_add_u32 s46, s46, 0x4000
	s_addc_u32 s47, s47, 0
	s_waitcnt vmcnt(15) lgkmcnt(4)
	v_pk_add_f32 v[182:183], v[182:183], v[214:215]
	v_pk_add_f32 v[184:185], v[184:185], v[216:217]
	global_store_dwordx4 v138, v[182:185], s[46:47] sc1
	s_add_u32 s46, s46, 0x4000
	s_addc_u32 s47, s47, 0
	s_waitcnt vmcnt(15) lgkmcnt(3)
	v_pk_add_f32 v[186:187], v[186:187], v[218:219]
	v_pk_add_f32 v[188:189], v[188:189], v[220:221]
	global_store_dwordx4 v138, v[186:189], s[46:47] sc1
	s_add_u32 s46, s46, 0x4000
	s_addc_u32 s47, s47, 0
	s_waitcnt vmcnt(15) lgkmcnt(2)
	v_pk_add_f32 v[190:191], v[190:191], v[222:223]
	v_pk_add_f32 v[192:193], v[192:193], v[224:225]
	global_store_dwordx4 v138, v[190:193], s[46:47] sc1
	s_add_u32 s46, s46, 0x4000
	s_addc_u32 s47, s47, 0
	s_waitcnt vmcnt(15) lgkmcnt(1)
	v_pk_add_f32 v[194:195], v[194:195], v[226:227]
	v_pk_add_f32 v[196:197], v[196:197], v[228:229]
	global_store_dwordx4 v138, v[194:197], s[46:47] sc1
	s_add_u32 s46, s46, 0x4000
	s_addc_u32 s47, s47, 0
	s_waitcnt vmcnt(15) lgkmcnt(0)
	v_pk_add_f32 v[198:199], v[198:199], v[230:231]
	v_pk_add_f32 v[200:201], v[200:201], v[232:233]
	global_store_dwordx4 v138, v[198:201], s[46:47] sc1
	s_add_u32 s46, s46, 0x4000
	s_addc_u32 s47, s47, 0
	s_waitcnt lgkmcnt(0)
	global_load_dwordx4 v[166:169], v138, s[44:45] nt
	s_add_u32 s44, s44, 0x4000
	s_addc_u32 s45, s45, 0
	global_load_dwordx4 v[170:173], v138, s[44:45] nt
	s_add_u32 s44, s44, 0x4000
	s_addc_u32 s45, s45, 0
	global_load_dwordx4 v[174:177], v138, s[44:45] nt
	s_add_u32 s44, s44, 0x4000
	s_addc_u32 s45, s45, 0
	global_load_dwordx4 v[182:185], v138, s[44:45] nt
	s_add_u32 s44, s44, 0x4000
	s_addc_u32 s45, s45, 0
	global_load_dwordx4 v[186:189], v138, s[44:45] nt
	s_add_u32 s44, s44, 0x4000
	s_addc_u32 s45, s45, 0
	global_load_dwordx4 v[190:193], v138, s[44:45] nt
	s_add_u32 s44, s44, 0x4000
	s_addc_u32 s45, s45, 0
	global_load_dwordx4 v[194:197], v138, s[44:45] nt
	s_add_u32 s44, s44, 0x4000
	s_addc_u32 s45, s45, 0
	global_load_dwordx4 v[198:201], v138, s[44:45] nt
	s_add_u32 s44, s44, 0x4000
	s_addc_u32 s45, s45, 0
	ds_write_b32 v139, v60
	ds_write_b32 v139, v61 offset:272
	ds_write_b32 v139, v62 offset:544
	ds_write_b32 v139, v63 offset:816
	ds_write_b32 v139, v56 offset:64
	ds_write_b32 v139, v57 offset:336
	ds_write_b32 v139, v58 offset:608
	ds_write_b32 v139, v59 offset:880
	ds_write_b32 v139, v52 offset:128
	ds_write_b32 v139, v53 offset:400
	ds_write_b32 v139, v54 offset:672
	ds_write_b32 v139, v55 offset:944
	ds_write_b32 v139, v48 offset:192
	ds_write_b32 v139, v49 offset:464
	ds_write_b32 v139, v50 offset:736
	ds_write_b32 v139, v51 offset:1008
	ds_write_b32 v139, v44 offset:4352
	ds_write_b32 v139, v45 offset:4624
	ds_write_b32 v139, v46 offset:4896
	ds_write_b32 v139, v47 offset:5168
	ds_write_b32 v139, v32 offset:4416
	ds_write_b32 v139, v33 offset:4688
	ds_write_b32 v139, v34 offset:4960
	ds_write_b32 v139, v35 offset:5232
	ds_write_b32 v139, v28 offset:4480
	ds_write_b32 v139, v29 offset:4752
	ds_write_b32 v139, v30 offset:5024
	ds_write_b32 v139, v31 offset:5296
	ds_write_b32 v139, v24 offset:4544
	ds_write_b32 v139, v25 offset:4816
	ds_write_b32 v139, v26 offset:5088
	ds_write_b32 v139, v27 offset:5360
	ds_write_b32 v139, v20 offset:8704
	ds_write_b32 v139, v21 offset:8976
	ds_write_b32 v139, v22 offset:9248
	ds_write_b32 v139, v23 offset:9520
	ds_write_b32 v139, v16 offset:8768
	ds_write_b32 v139, v17 offset:9040
	ds_write_b32 v139, v18 offset:9312
	ds_write_b32 v139, v19 offset:9584
	ds_write_b32 v139, v12 offset:8832
	ds_write_b32 v139, v13 offset:9104
	ds_write_b32 v139, v14 offset:9376
	ds_write_b32 v139, v15 offset:9648
	ds_write_b32 v139, v8 offset:8896
	ds_write_b32 v139, v9 offset:9168
	ds_write_b32 v139, v10 offset:9440
	ds_write_b32 v139, v11 offset:9712
	ds_write_b32 v139, v4 offset:13056
	ds_write_b32 v139, v5 offset:13328
	ds_write_b32 v139, v6 offset:13600
	ds_write_b32 v139, v7 offset:13872
	ds_write_b32 v139, v0 offset:13120
	ds_write_b32 v139, v1 offset:13392
	ds_write_b32 v139, v2 offset:13664
	ds_write_b32 v139, v3 offset:13936
	ds_write_b32 v139, v40 offset:13184
	ds_write_b32 v139, v41 offset:13456
	ds_write_b32 v139, v42 offset:13728
	ds_write_b32 v139, v43 offset:14000
	ds_write_b32 v139, v36 offset:13248
	ds_write_b32 v139, v37 offset:13520
	ds_write_b32 v139, v38 offset:13792
	ds_write_b32 v139, v39 offset:14064
	s_waitcnt lgkmcnt(0)
	ds_read_b128 v[202:205], v141
	ds_read_b128 v[206:209], v141 offset:1088
	ds_read_b128 v[210:213], v141 offset:2176
	ds_read_b128 v[214:217], v141 offset:3264
	ds_read_b128 v[218:221], v141 offset:4352
	ds_read_b128 v[222:225], v141 offset:5440
	ds_read_b128 v[226:229], v141 offset:6528
	ds_read_b128 v[230:233], v141 offset:7616
	s_waitcnt vmcnt(15) lgkmcnt(7)
	v_pk_add_f32 v[130:131], v[130:131], v[202:203]
	v_pk_add_f32 v[132:133], v[132:133], v[204:205]
	global_store_dwordx4 v138, v[130:133], s[46:47] sc1
	s_add_u32 s46, s46, 0x4000
	s_addc_u32 s47, s47, 0
	s_waitcnt vmcnt(15) lgkmcnt(6)
	v_pk_add_f32 v[134:135], v[134:135], v[206:207]
	v_pk_add_f32 v[136:137], v[136:137], v[208:209]
	global_store_dwordx4 v138, v[134:137], s[46:47] sc1
	s_add_u32 s46, s46, 0x4000
	s_addc_u32 s47, s47, 0
	s_waitcnt vmcnt(15) lgkmcnt(5)
	v_pk_add_f32 v[142:143], v[142:143], v[210:211]
	v_pk_add_f32 v[144:145], v[144:145], v[212:213]
	global_store_dwordx4 v138, v[142:145], s[46:47] sc1
	s_add_u32 s46, s46, 0x4000
	s_addc_u32 s47, s47, 0
	s_waitcnt vmcnt(15) lgkmcnt(4)
	v_pk_add_f32 v[146:147], v[146:147], v[214:215]
	v_pk_add_f32 v[148:149], v[148:149], v[216:217]
	global_store_dwordx4 v138, v[146:149], s[46:47] sc1
	s_add_u32 s46, s46, 0x4000
	s_addc_u32 s47, s47, 0
	s_waitcnt vmcnt(15) lgkmcnt(3)
	v_pk_add_f32 v[150:151], v[150:151], v[218:219]
	v_pk_add_f32 v[152:153], v[152:153], v[220:221]
	global_store_dwordx4 v138, v[150:153], s[46:47] sc1
	s_add_u32 s46, s46, 0x4000
	s_addc_u32 s47, s47, 0
	s_waitcnt vmcnt(15) lgkmcnt(2)
	v_pk_add_f32 v[154:155], v[154:155], v[222:223]
	v_pk_add_f32 v[156:157], v[156:157], v[224:225]
	global_store_dwordx4 v138, v[154:157], s[46:47] sc1
	s_add_u32 s46, s46, 0x4000
	s_addc_u32 s47, s47, 0
	s_waitcnt vmcnt(15) lgkmcnt(1)
	v_pk_add_f32 v[158:159], v[158:159], v[226:227]
	v_pk_add_f32 v[160:161], v[160:161], v[228:229]
	global_store_dwordx4 v138, v[158:161], s[46:47] sc1
	s_add_u32 s46, s46, 0x4000
	s_addc_u32 s47, s47, 0
	s_waitcnt vmcnt(15) lgkmcnt(0)
	v_pk_add_f32 v[162:163], v[162:163], v[230:231]
	v_pk_add_f32 v[164:165], v[164:165], v[232:233]
	global_store_dwordx4 v138, v[162:165], s[46:47] sc1
	s_add_u32 s46, s46, 0x4000
	s_addc_u32 s47, s47, 0
	ds_read_b128 v[202:205], v141 offset:8704
	ds_read_b128 v[206:209], v141 offset:9792
	ds_read_b128 v[210:213], v141 offset:10880
	ds_read_b128 v[214:217], v141 offset:11968
	ds_read_b128 v[218:221], v141 offset:13056
	ds_read_b128 v[222:225], v141 offset:14144
	ds_read_b128 v[226:229], v141 offset:15232
	ds_read_b128 v[230:233], v141 offset:16320
	s_waitcnt vmcnt(7) lgkmcnt(7)
	v_pk_add_f32 v[166:167], v[166:167], v[202:203]
	v_pk_add_f32 v[168:169], v[168:169], v[204:205]
	global_store_dwordx4 v138, v[166:169], s[46:47] sc1
	s_add_u32 s46, s46, 0x4000
	s_addc_u32 s47, s47, 0
	s_waitcnt vmcnt(7) lgkmcnt(6)
	v_pk_add_f32 v[170:171], v[170:171], v[206:207]
	v_pk_add_f32 v[172:173], v[172:173], v[208:209]
	global_store_dwordx4 v138, v[170:173], s[46:47] sc1
	s_add_u32 s46, s46, 0x4000
	s_addc_u32 s47, s47, 0
	s_waitcnt vmcnt(7) lgkmcnt(5)
	v_pk_add_f32 v[174:175], v[174:175], v[210:211]
	v_pk_add_f32 v[176:177], v[176:177], v[212:213]
	global_store_dwordx4 v138, v[174:177], s[46:47] sc1
	s_add_u32 s46, s46, 0x4000
	s_addc_u32 s47, s47, 0
	s_waitcnt vmcnt(7) lgkmcnt(4)
	v_pk_add_f32 v[182:183], v[182:183], v[214:215]
	v_pk_add_f32 v[184:185], v[184:185], v[216:217]
	global_store_dwordx4 v138, v[182:185], s[46:47] sc1
	s_add_u32 s46, s46, 0x4000
	s_addc_u32 s47, s47, 0
	s_waitcnt vmcnt(7) lgkmcnt(3)
	v_pk_add_f32 v[186:187], v[186:187], v[218:219]
	v_pk_add_f32 v[188:189], v[188:189], v[220:221]
	global_store_dwordx4 v138, v[186:189], s[46:47] sc1
	s_add_u32 s46, s46, 0x4000
	s_addc_u32 s47, s47, 0
	s_waitcnt vmcnt(7) lgkmcnt(2)
	v_pk_add_f32 v[190:191], v[190:191], v[222:223]
	v_pk_add_f32 v[192:193], v[192:193], v[224:225]
	global_store_dwordx4 v138, v[190:193], s[46:47] sc1
	s_add_u32 s46, s46, 0x4000
	s_addc_u32 s47, s47, 0
	s_waitcnt vmcnt(7) lgkmcnt(1)
	v_pk_add_f32 v[194:195], v[194:195], v[226:227]
	v_pk_add_f32 v[196:197], v[196:197], v[228:229]
	global_store_dwordx4 v138, v[194:197], s[46:47] sc1
	s_add_u32 s46, s46, 0x4000
	s_addc_u32 s47, s47, 0
	s_waitcnt vmcnt(7) lgkmcnt(0)
	v_pk_add_f32 v[198:199], v[198:199], v[230:231]
	v_pk_add_f32 v[200:201], v[200:201], v[232:233]
	global_store_dwordx4 v138, v[198:201], s[46:47] sc1
	s_add_u32 s46, s46, 0x4000
	s_addc_u32 s47, s47, 0
	s_cmpk_lt_i32 s58, 0x100
	s_cbranch_scc0 .LBB0_1337

.LBB0_1395:
	s_ashr_i32 s4, s17, 31
	s_lshr_b32 s4, s4, 29
	s_add_i32 s4, s17, s4
	s_ashr_i32 s12, s4, 3
	s_lshl_b32 s18, s12, 6
	v_or_b32_e32 v0, s18, v16
	v_lshl_add_u32 v1, s12, 5, v17
	v_add_u32_e32 v2, 0xfffff800, v0
	v_cmp_gt_i32_e32 vcc, s16, v0
	s_mul_i32 s8, s12, 0xffa00000
	v_add_u32_e32 v6, s8, v25
	v_cndmask_b32_e32 v10, v2, v1, vcc
	v_cmp_lt_i32_e64 s[4:5], -1, v10
	v_lshl_add_u64 v[4:5], v[10:11], 2, s[52:53]
	v_mov_b32_e32 v10, v11
	v_mov_b64_e32 v[0:1], v[10:11]
	v_mov_b64_e32 v[2:3], v[10:11]
	s_waitcnt vmcnt(63) expcnt(7) lgkmcnt(15)
	s_barrier
	s_and_saveexec_b64 s[8:9], s[4:5]
	s_cbranch_execz .LBB0_1397
	v_ashrrev_i32_e32 v7, 31, v6
	v_lshl_add_u64 v[0:1], v[6:7], 2, v[4:5]
	global_load_dwordx4 v[0:3], v[0:1], off nt
	v_add_u32_e32 v56, 0x30000, v6
	v_ashrrev_i32_e32 v57, 31, v56
	v_lshl_add_u64 v[56:57], v[56:57], 2, v[4:5]
	global_load_dwordx4 v[40:43], v[56:57], off nt
	v_add_u32_e32 v56, 0x60000, v6
	v_ashrrev_i32_e32 v57, 31, v56
	v_lshl_add_u64 v[56:57], v[56:57], 2, v[4:5]
	global_load_dwordx4 v[44:47], v[56:57], off nt
	v_add_u32_e32 v56, 0x90000, v6
	v_ashrrev_i32_e32 v57, 31, v56
	v_lshl_add_u64 v[56:57], v[56:57], 2, v[4:5]
	global_load_dwordx4 v[48:51], v[56:57], off nt
.LBB0_1397:
	s_or_b64 exec, exec, s[8:9]
	s_lshl_b32 s8, s12, 10
	s_and_b64 vcc, exec, s[0:1]
	s_sub_i32 s12, 0, s8
	s_cbranch_vccnz .LBB0_1399
	s_add_i32 s8, s12, s3
	v_add_u32_e32 v26, s8, v8
	v_ashrrev_i32_e32 v27, 31, v26
	v_lshl_add_u64 v[26:27], v[26:27], 2, s[50:51]
	global_load_dword v10, v[26:27], off nt
	global_load_dword v52, v[26:27], off offset:128 nt
	global_load_dword v53, v[26:27], off offset:256 nt
	global_load_dword v54, v[26:27], off offset:384 nt
	s_waitcnt vmcnt(0)
	v_pk_mul_f32 v[0:1], v[0:1], v[10:11] op_sel_hi:[1,0]
	v_pk_mul_f32 v[2:3], v[2:3], v[10:11] op_sel_hi:[1,0]

.LBB0_1418:
	s_ashr_i32 s5, s9, 31
	s_lshr_b32 s5, s5, 28
	s_add_i32 s5, s9, s5
	s_ashr_i32 s5, s5, 4
	s_lshl_b32 s6, s5, 11
	s_sub_i32 s6, 0, s6
	s_lshl_b32 s5, s5, 6
	v_mov_b32_e32 v0, 0
	s_andn2_b64 vcc, exec, s[0:1]
	v_mov_b32_e32 v1, 0
	v_mov_b32_e32 v2, 0
	v_mov_b32_e32 v3, 0
	v_mov_b32_e32 v4, 0
	v_mov_b32_e32 v5, 0
	v_mov_b32_e32 v6, 0
	v_mov_b32_e32 v7, 0
	s_cbranch_vccnz .LBB0_1415
	s_add_i32 s0, s6, s3
	v_add_u32_e32 v2, s0, v8
	v_or_b32_e32 v10, s5, v9
	v_ashrrev_i32_e32 v3, 31, v2
	v_add_u32_e32 v6, 32, v2
	v_lshl_add_u64 v[0:1], v[10:11], 2, s[30:31]
	v_lshlrev_b64 v[4:5], 12, v[2:3]
	v_ashrrev_i32_e32 v7, 31, v6
	v_lshl_add_u64 v[4:5], v[0:1], 0, v[4:5]
	v_lshlrev_b64 v[6:7], 12, v[6:7]
	v_lshl_add_u64 v[6:7], v[0:1], 0, v[6:7]
	global_load_dwordx4 v[22:25], v[4:5], off nt
	global_load_dwordx4 v[26:29], v[6:7], off nt
	v_add_u32_e32 v4, 64, v2
	v_ashrrev_i32_e32 v5, 31, v4
	v_add_u32_e32 v2, 0x60, v2
	v_lshlrev_b64 v[4:5], 12, v[4:5]
	v_ashrrev_i32_e32 v3, 31, v2
	v_lshl_add_u64 v[30:31], v[0:1], 0, v[4:5]
	v_lshlrev_b64 v[2:3], 12, v[2:3]
	v_lshl_add_u64 v[32:33], v[0:1], 0, v[2:3]
	global_load_dwordx4 v[4:7], v[30:31], off nt
	global_load_dwordx4 v[0:3], v[32:33], off nt
	s_waitcnt vmcnt(3)
	ds_write_b128 v14, v[22:25]
	s_waitcnt vmcnt(2)
	ds_write_b128 v17, v[26:29]
	s_branch .LBB0_1415

.LBB0_1635:
	s_add_i32 s44, s44, s82
	s_add_i32 s43, s43, s82
	v_and_b32_e32 v178, 15, v181
	v_bfe_u32 v138, v181, 4, 2
	v_lshlrev_b32_e32 v141, 4, v178
	s_movk_i32 s20, 0x110
	v_mad_u32_u24 v141, v138, s20, v141
	v_lshlrev_b32_e32 v139, 2, v178
	s_movk_i32 s20, 0x440
	v_mad_u32_u24 v139, v138, s20, v139
	v_lshlrev_b32_e32 v138, 12, v138
	v_lshl_add_u32 v138, v178, 4, v138
	v_lshrrev_b32_e32 v178, 6, v181
	v_mul_u32_u24_e32 v178, 0x4400, v178
	v_add_u32_e32 v141, v141, v178
	v_add_u32_e32 v139, v139, v178
	v_bfe_u32 v178, v181, 6, 2
	v_lshl_add_u32 v138, v178, 8, v138
	v_lshrrev_b32_e32 v178, 8, v181
	v_lshl_add_u32 v138, v178, 19, v138
	s_lshl_b32 s20, s30, 20
	v_add_u32_e32 v138, s20, v138
	s_lshl_b32 s20, s4, 10
	v_add_u32_e32 v138, s20, v138
	s_mov_b32 s36, s78
	s_mov_b32 s37, s79
	s_mov_b32 s38, s78
	s_mov_b32 s39, s79
	global_load_dwordx4 v[130:133], v138, s[36:37] nt
	s_add_u32 s36, s36, 0x4000
	s_addc_u32 s37, s37, 0
	global_load_dwordx4 v[134:137], v138, s[36:37] nt
	s_add_u32 s36, s36, 0x4000
	s_addc_u32 s37, s37, 0
	global_load_dwordx4 v[142:145], v138, s[36:37] nt
	s_add_u32 s36, s36, 0x4000
	s_addc_u32 s37, s37, 0
	global_load_dwordx4 v[146:149], v138, s[36:37] nt
	s_add_u32 s36, s36, 0x4000
	s_addc_u32 s37, s37, 0
	global_load_dwordx4 v[150:153], v138, s[36:37] nt
	s_add_u32 s36, s36, 0x4000
	s_addc_u32 s37, s37, 0
	global_load_dwordx4 v[154:157], v138, s[36:37] nt
	s_add_u32 s36, s36, 0x4000
	s_addc_u32 s37, s37, 0
	global_load_dwordx4 v[158:161], v138, s[36:37] nt
	s_add_u32 s36, s36, 0x4000
	s_addc_u32 s37, s37, 0
	global_load_dwordx4 v[162:165], v138, s[36:37] nt
	s_add_u32 s36, s36, 0x4000
	s_addc_u32 s37, s37, 0
	global_load_dwordx4 v[166:169], v138, s[36:37] nt
	s_add_u32 s36, s36, 0x4000
	s_addc_u32 s37, s37, 0
	global_load_dwordx4 v[170:173], v138, s[36:37] nt
	s_add_u32 s36, s36, 0x4000
	s_addc_u32 s37, s37, 0
	global_load_dwordx4 v[174:177], v138, s[36:37] nt
	s_add_u32 s36, s36, 0x4000
	s_addc_u32 s37, s37, 0
	global_load_dwordx4 v[182:185], v138, s[36:37] nt
	s_add_u32 s36, s36, 0x4000
	s_addc_u32 s37, s37, 0
	global_load_dwordx4 v[186:189], v138, s[36:37] nt
	s_add_u32 s36, s36, 0x4000
	s_addc_u32 s37, s37, 0
	global_load_dwordx4 v[190:193], v138, s[36:37] nt
	s_add_u32 s36, s36, 0x4000
	s_addc_u32 s37, s37, 0
	global_load_dwordx4 v[194:197], v138, s[36:37] nt
	s_add_u32 s36, s36, 0x4000
	s_addc_u32 s37, s37, 0
	global_load_dwordx4 v[198:201], v138, s[36:37] nt
	s_add_u32 s36, s36, 0x4000
	s_addc_u32 s37, s37, 0
	ds_write_b32 v139, v124
	ds_write_b32 v139, v125 offset:272
	ds_write_b32 v139, v126 offset:544
	ds_write_b32 v139, v127 offset:816
	ds_write_b32 v139, v120 offset:64
	ds_write_b32 v139, v121 offset:336
	ds_write_b32 v139, v122 offset:608
	ds_write_b32 v139, v123 offset:880
	ds_write_b32 v139, v116 offset:128
	ds_write_b32 v139, v117 offset:400
	ds_write_b32 v139, v118 offset:672
	ds_write_b32 v139, v119 offset:944
	ds_write_b32 v139, v112 offset:192
	ds_write_b32 v139, v113 offset:464
	ds_write_b32 v139, v114 offset:736
	ds_write_b32 v139, v115 offset:1008
	ds_write_b32 v139, v108 offset:4352
	ds_write_b32 v139, v109 offset:4624
	ds_write_b32 v139, v110 offset:4896
	ds_write_b32 v139, v111 offset:5168
	ds_write_b32 v139, v104 offset:4416
	ds_write_b32 v139, v105 offset:4688
	ds_write_b32 v139, v106 offset:4960
	ds_write_b32 v139, v107 offset:5232
	ds_write_b32 v139, v100 offset:4480
	ds_write_b32 v139, v101 offset:4752
	ds_write_b32 v139, v102 offset:5024
	ds_write_b32 v139, v103 offset:5296
	ds_write_b32 v139, v96 offset:4544
	ds_write_b32 v139, v97 offset:4816
	ds_write_b32 v139, v98 offset:5088
	ds_write_b32 v139, v99 offset:5360
	ds_write_b32 v139, v92 offset:8704
	ds_write_b32 v139, v93 offset:8976
	ds_write_b32 v139, v94 offset:9248
	ds_write_b32 v139, v95 offset:9520
	ds_write_b32 v139, v88 offset:8768
	ds_write_b32 v139, v89 offset:9040
	ds_write_b32 v139, v90 offset:9312
	ds_write_b32 v139, v91 offset:9584
	ds_write_b32 v139, v84 offset:8832
	ds_write_b32 v139, v85 offset:9104
	ds_write_b32 v139, v86 offset:9376
	ds_write_b32 v139, v87 offset:9648
	ds_write_b32 v139, v80 offset:8896
	ds_write_b32 v139, v81 offset:9168
	ds_write_b32 v139, v82 offset:9440
	ds_write_b32 v139, v83 offset:9712
	ds_write_b32 v139, v76 offset:13056
	ds_write_b32 v139, v77 offset:13328
	ds_write_b32 v139, v78 offset:13600
	ds_write_b32 v139, v79 offset:13872
	ds_write_b32 v139, v72 offset:13120
	ds_write_b32 v139, v73 offset:13392
	ds_write_b32 v139, v74 offset:13664
	ds_write_b32 v139, v75 offset:13936
	ds_write_b32 v139, v68 offset:13184
	ds_write_b32 v139, v69 offset:13456
	ds_write_b32 v139, v70 offset:13728
	ds_write_b32 v139, v71 offset:14000
	ds_write_b32 v139, v64 offset:13248
	ds_write_b32 v139, v65 offset:13520
	ds_write_b32 v139, v66 offset:13792
	ds_write_b32 v139, v67 offset:14064
	s_waitcnt lgkmcnt(0)
	ds_read_b128 v[202:205], v141
	ds_read_b128 v[206:209], v141 offset:1088
	ds_read_b128 v[210:213], v141 offset:2176
	ds_read_b128 v[214:217], v141 offset:3264
	ds_read_b128 v[218:221], v141 offset:4352
	ds_read_b128 v[222:225], v141 offset:5440
	ds_read_b128 v[226:229], v141 offset:6528
	ds_read_b128 v[230:233], v141 offset:7616
	s_waitcnt vmcnt(15) lgkmcnt(7)
	v_pk_add_f32 v[130:131], v[130:131], v[202:203]
	v_pk_add_f32 v[132:133], v[132:133], v[204:205]
	global_store_dwordx4 v138, v[130:133], s[38:39] sc1
	s_add_u32 s38, s38, 0x4000
	s_addc_u32 s39, s39, 0
	s_waitcnt vmcnt(15) lgkmcnt(6)
	v_pk_add_f32 v[134:135], v[134:135], v[206:207]
	v_pk_add_f32 v[136:137], v[136:137], v[208:209]
	global_store_dwordx4 v138, v[134:137], s[38:39] sc1
	s_add_u32 s38, s38, 0x4000
	s_addc_u32 s39, s39, 0
	s_waitcnt vmcnt(15) lgkmcnt(5)
	v_pk_add_f32 v[142:143], v[142:143], v[210:211]
	v_pk_add_f32 v[144:145], v[144:145], v[212:213]
	global_store_dwordx4 v138, v[142:145], s[38:39] sc1
	s_add_u32 s38, s38, 0x4000
	s_addc_u32 s39, s39, 0
	s_waitcnt vmcnt(15) lgkmcnt(4)
	v_pk_add_f32 v[146:147], v[146:147], v[214:215]
	v_pk_add_f32 v[148:149], v[148:149], v[216:217]
	global_store_dwordx4 v138, v[146:149], s[38:39] sc1
	s_add_u32 s38, s38, 0x4000
	s_addc_u32 s39, s39, 0
	s_waitcnt vmcnt(15) lgkmcnt(3)
	v_pk_add_f32 v[150:151], v[150:151], v[218:219]
	v_pk_add_f32 v[152:153], v[152:153], v[220:221]
	global_store_dwordx4 v138, v[150:153], s[38:39] sc1
	s_add_u32 s38, s38, 0x4000
	s_addc_u32 s39, s39, 0
	s_waitcnt vmcnt(15) lgkmcnt(2)
	v_pk_add_f32 v[154:155], v[154:155], v[222:223]
	v_pk_add_f32 v[156:157], v[156:157], v[224:225]
	global_store_dwordx4 v138, v[154:157], s[38:39] sc1
	s_add_u32 s38, s38, 0x4000
	s_addc_u32 s39, s39, 0
	s_waitcnt vmcnt(15) lgkmcnt(1)
	v_pk_add_f32 v[158:159], v[158:159], v[226:227]
	v_pk_add_f32 v[160:161], v[160:161], v[228:229]
	global_store_dwordx4 v138, v[158:161], s[38:39] sc1
	s_add_u32 s38, s38, 0x4000
	s_addc_u32 s39, s39, 0
	s_waitcnt vmcnt(15) lgkmcnt(0)
	v_pk_add_f32 v[162:163], v[162:163], v[230:231]
	v_pk_add_f32 v[164:165], v[164:165], v[232:233]
	global_store_dwordx4 v138, v[162:165], s[38:39] sc1
	s_add_u32 s38, s38, 0x4000
	s_addc_u32 s39, s39, 0
	global_load_dwordx4 v[130:133], v138, s[36:37] nt
	s_add_u32 s36, s36, 0x4000
	s_addc_u32 s37, s37, 0
	global_load_dwordx4 v[134:137], v138, s[36:37] nt
	s_add_u32 s36, s36, 0x4000
	s_addc_u32 s37, s37, 0
	global_load_dwordx4 v[142:145], v138, s[36:37] nt
	s_add_u32 s36, s36, 0x4000
	s_addc_u32 s37, s37, 0
	global_load_dwordx4 v[146:149], v138, s[36:37] nt
	s_add_u32 s36, s36, 0x4000
	s_addc_u32 s37, s37, 0
	global_load_dwordx4 v[150:153], v138, s[36:37] nt
	s_add_u32 s36, s36, 0x4000
	s_addc_u32 s37, s37, 0
	global_load_dwordx4 v[154:157], v138, s[36:37] nt
	s_add_u32 s36, s36, 0x4000
	s_addc_u32 s37, s37, 0
	global_load_dwordx4 v[158:161], v138, s[36:37] nt
	s_add_u32 s36, s36, 0x4000
	s_addc_u32 s37, s37, 0
	global_load_dwordx4 v[162:165], v138, s[36:37] nt
	s_add_u32 s36, s36, 0x4000
	s_addc_u32 s37, s37, 0
	ds_read_b128 v[202:205], v141 offset:8704
	ds_read_b128 v[206:209], v141 offset:9792
	ds_read_b128 v[210:213], v141 offset:10880
	ds_read_b128 v[214:217], v141 offset:11968
	ds_read_b128 v[218:221], v141 offset:13056
	ds_read_b128 v[222:225], v141 offset:14144
	ds_read_b128 v[226:229], v141 offset:15232
	ds_read_b128 v[230:233], v141 offset:16320
	s_waitcnt vmcnt(15) lgkmcnt(7)
	v_pk_add_f32 v[166:167], v[166:167], v[202:203]
	v_pk_add_f32 v[168:169], v[168:169], v[204:205]
	global_store_dwordx4 v138, v[166:169], s[38:39] sc1
	s_add_u32 s38, s38, 0x4000
	s_addc_u32 s39, s39, 0
	s_waitcnt vmcnt(15) lgkmcnt(6)
	v_pk_add_f32 v[170:171], v[170:171], v[206:207]
	v_pk_add_f32 v[172:173], v[172:173], v[208:209]
	global_store_dwordx4 v138, v[170:173], s[38:39] sc1
	s_add_u32 s38, s38, 0x4000
	s_addc_u32 s39, s39, 0
	s_waitcnt vmcnt(15) lgkmcnt(5)
	v_pk_add_f32 v[174:175], v[174:175], v[210:211]
	v_pk_add_f32 v[176:177], v[176:177], v[212:213]
	global_store_dwordx4 v138, v[174:177], s[38:39] sc1
	s_add_u32 s38, s38, 0x4000
	s_addc_u32 s39, s39, 0
	s_waitcnt vmcnt(15) lgkmcnt(4)
	v_pk_add_f32 v[182:183], v[182:183], v[214:215]
	v_pk_add_f32 v[184:185], v[184:185], v[216:217]
	global_store_dwordx4 v138, v[182:185], s[38:39] sc1
	s_add_u32 s38, s38, 0x4000
	s_addc_u32 s39, s39, 0
	s_waitcnt vmcnt(15) lgkmcnt(3)
	v_pk_add_f32 v[186:187], v[186:187], v[218:219]
	v_pk_add_f32 v[188:189], v[188:189], v[220:221]
	global_store_dwordx4 v138, v[186:189], s[38:39] sc1
	s_add_u32 s38, s38, 0x4000
	s_addc_u32 s39, s39, 0
	s_waitcnt vmcnt(15) lgkmcnt(2)
	v_pk_add_f32 v[190:191], v[190:191], v[222:223]
	v_pk_add_f32 v[192:193], v[192:193], v[224:225]
	global_store_dwordx4 v138, v[190:193], s[38:39] sc1
	s_add_u32 s38, s38, 0x4000
	s_addc_u32 s39, s39, 0
	s_waitcnt vmcnt(15) lgkmcnt(1)
	v_pk_add_f32 v[194:195], v[194:195], v[226:227]
	v_pk_add_f32 v[196:197], v[196:197], v[228:229]
	global_store_dwordx4 v138, v[194:197], s[38:39] sc1
	s_add_u32 s38, s38, 0x4000
	s_addc_u32 s39, s39, 0
	s_waitcnt vmcnt(15) lgkmcnt(0)
	v_pk_add_f32 v[198:199], v[198:199], v[230:231]
	v_pk_add_f32 v[200:201], v[200:201], v[232:233]
	global_store_dwordx4 v138, v[198:201], s[38:39] sc1
	s_add_u32 s38, s38, 0x4000
	s_addc_u32 s39, s39, 0
	s_waitcnt lgkmcnt(0)
	global_load_dwordx4 v[166:169], v138, s[36:37] nt
	s_add_u32 s36, s36, 0x4000
	s_addc_u32 s37, s37, 0
	global_load_dwordx4 v[170:173], v138, s[36:37] nt
	s_add_u32 s36, s36, 0x4000
	s_addc_u32 s37, s37, 0
	global_load_dwordx4 v[174:177], v138, s[36:37] nt
	s_add_u32 s36, s36, 0x4000
	s_addc_u32 s37, s37, 0
	global_load_dwordx4 v[182:185], v138, s[36:37] nt
	s_add_u32 s36, s36, 0x4000
	s_addc_u32 s37, s37, 0
	global_load_dwordx4 v[186:189], v138, s[36:37] nt
	s_add_u32 s36, s36, 0x4000
	s_addc_u32 s37, s37, 0
	global_load_dwordx4 v[190:193], v138, s[36:37] nt
	s_add_u32 s36, s36, 0x4000
	s_addc_u32 s37, s37, 0
	global_load_dwordx4 v[194:197], v138, s[36:37] nt
	s_add_u32 s36, s36, 0x4000
	s_addc_u32 s37, s37, 0
	global_load_dwordx4 v[198:201], v138, s[36:37] nt
	s_add_u32 s36, s36, 0x4000
	s_addc_u32 s37, s37, 0
	ds_write_b32 v139, v60
	ds_write_b32 v139, v61 offset:272
	ds_write_b32 v139, v62 offset:544
	ds_write_b32 v139, v63 offset:816
	ds_write_b32 v139, v56 offset:64
	ds_write_b32 v139, v57 offset:336
	ds_write_b32 v139, v58 offset:608
	ds_write_b32 v139, v59 offset:880
	ds_write_b32 v139, v52 offset:128
	ds_write_b32 v139, v53 offset:400
	ds_write_b32 v139, v54 offset:672
	ds_write_b32 v139, v55 offset:944
	ds_write_b32 v139, v48 offset:192
	ds_write_b32 v139, v49 offset:464
	ds_write_b32 v139, v50 offset:736
	ds_write_b32 v139, v51 offset:1008
	ds_write_b32 v139, v44 offset:4352
	ds_write_b32 v139, v45 offset:4624
	ds_write_b32 v139, v46 offset:4896
	ds_write_b32 v139, v47 offset:5168
	ds_write_b32 v139, v32 offset:4416
	ds_write_b32 v139, v33 offset:4688
	ds_write_b32 v139, v34 offset:4960
	ds_write_b32 v139, v35 offset:5232
	ds_write_b32 v139, v28 offset:4480
	ds_write_b32 v139, v29 offset:4752
	ds_write_b32 v139, v30 offset:5024
	ds_write_b32 v139, v31 offset:5296
	ds_write_b32 v139, v24 offset:4544
	ds_write_b32 v139, v25 offset:4816
	ds_write_b32 v139, v26 offset:5088
	ds_write_b32 v139, v27 offset:5360
	ds_write_b32 v139, v20 offset:8704
	ds_write_b32 v139, v21 offset:8976
	ds_write_b32 v139, v22 offset:9248
	ds_write_b32 v139, v23 offset:9520
	ds_write_b32 v139, v16 offset:8768
	ds_write_b32 v139, v17 offset:9040
	ds_write_b32 v139, v18 offset:9312
	ds_write_b32 v139, v19 offset:9584
	ds_write_b32 v139, v12 offset:8832
	ds_write_b32 v139, v13 offset:9104
	ds_write_b32 v139, v14 offset:9376
	ds_write_b32 v139, v15 offset:9648
	ds_write_b32 v139, v8 offset:8896
	ds_write_b32 v139, v9 offset:9168
	ds_write_b32 v139, v10 offset:9440
	ds_write_b32 v139, v11 offset:9712
	ds_write_b32 v139, v4 offset:13056
	ds_write_b32 v139, v5 offset:13328
	ds_write_b32 v139, v6 offset:13600
	ds_write_b32 v139, v7 offset:13872
	ds_write_b32 v139, v0 offset:13120
	ds_write_b32 v139, v1 offset:13392
	ds_write_b32 v139, v2 offset:13664
	ds_write_b32 v139, v3 offset:13936
	ds_write_b32 v139, v40 offset:13184
	ds_write_b32 v139, v41 offset:13456
	ds_write_b32 v139, v42 offset:13728
	ds_write_b32 v139, v43 offset:14000
	ds_write_b32 v139, v36 offset:13248
	ds_write_b32 v139, v37 offset:13520
	ds_write_b32 v139, v38 offset:13792
	ds_write_b32 v139, v39 offset:14064
	s_waitcnt lgkmcnt(0)
	ds_read_b128 v[202:205], v141
	ds_read_b128 v[206:209], v141 offset:1088
	ds_read_b128 v[210:213], v141 offset:2176
	ds_read_b128 v[214:217], v141 offset:3264
	ds_read_b128 v[218:221], v141 offset:4352
	ds_read_b128 v[222:225], v141 offset:5440
	ds_read_b128 v[226:229], v141 offset:6528
	ds_read_b128 v[230:233], v141 offset:7616
	s_waitcnt vmcnt(15) lgkmcnt(7)
	v_pk_add_f32 v[130:131], v[130:131], v[202:203]
	v_pk_add_f32 v[132:133], v[132:133], v[204:205]
	global_store_dwordx4 v138, v[130:133], s[38:39] sc1
	s_add_u32 s38, s38, 0x4000
	s_addc_u32 s39, s39, 0
	s_waitcnt vmcnt(15) lgkmcnt(6)
	v_pk_add_f32 v[134:135], v[134:135], v[206:207]
	v_pk_add_f32 v[136:137], v[136:137], v[208:209]
	global_store_dwordx4 v138, v[134:137], s[38:39] sc1
	s_add_u32 s38, s38, 0x4000
	s_addc_u32 s39, s39, 0
	s_waitcnt vmcnt(15) lgkmcnt(5)
	v_pk_add_f32 v[142:143], v[142:143], v[210:211]
	v_pk_add_f32 v[144:145], v[144:145], v[212:213]
	global_store_dwordx4 v138, v[142:145], s[38:39] sc1
	s_add_u32 s38, s38, 0x4000
	s_addc_u32 s39, s39, 0
	s_waitcnt vmcnt(15) lgkmcnt(4)
	v_pk_add_f32 v[146:147], v[146:147], v[214:215]
	v_pk_add_f32 v[148:149], v[148:149], v[216:217]
	global_store_dwordx4 v138, v[146:149], s[38:39] sc1
	s_add_u32 s38, s38, 0x4000
	s_addc_u32 s39, s39, 0
	s_waitcnt vmcnt(15) lgkmcnt(3)
	v_pk_add_f32 v[150:151], v[150:151], v[218:219]
	v_pk_add_f32 v[152:153], v[152:153], v[220:221]
	global_store_dwordx4 v138, v[150:153], s[38:39] sc1
	s_add_u32 s38, s38, 0x4000
	s_addc_u32 s39, s39, 0
	s_waitcnt vmcnt(15) lgkmcnt(2)
	v_pk_add_f32 v[154:155], v[154:155], v[222:223]
	v_pk_add_f32 v[156:157], v[156:157], v[224:225]
	global_store_dwordx4 v138, v[154:157], s[38:39] sc1
	s_add_u32 s38, s38, 0x4000
	s_addc_u32 s39, s39, 0
	s_waitcnt vmcnt(15) lgkmcnt(1)
	v_pk_add_f32 v[158:159], v[158:159], v[226:227]
	v_pk_add_f32 v[160:161], v[160:161], v[228:229]
	global_store_dwordx4 v138, v[158:161], s[38:39] sc1
	s_add_u32 s38, s38, 0x4000
	s_addc_u32 s39, s39, 0
	s_waitcnt vmcnt(15) lgkmcnt(0)
	v_pk_add_f32 v[162:163], v[162:163], v[230:231]
	v_pk_add_f32 v[164:165], v[164:165], v[232:233]
	global_store_dwordx4 v138, v[162:165], s[38:39] sc1
	s_add_u32 s38, s38, 0x4000
	s_addc_u32 s39, s39, 0
	ds_read_b128 v[202:205], v141 offset:8704
	ds_read_b128 v[206:209], v141 offset:9792
	ds_read_b128 v[210:213], v141 offset:10880
	ds_read_b128 v[214:217], v141 offset:11968
	ds_read_b128 v[218:221], v141 offset:13056
	ds_read_b128 v[222:225], v141 offset:14144
	ds_read_b128 v[226:229], v141 offset:15232
	ds_read_b128 v[230:233], v141 offset:16320
	s_waitcnt vmcnt(7) lgkmcnt(7)
	v_pk_add_f32 v[166:167], v[166:167], v[202:203]
	v_pk_add_f32 v[168:169], v[168:169], v[204:205]
	global_store_dwordx4 v138, v[166:169], s[38:39] sc1
	s_add_u32 s38, s38, 0x4000
	s_addc_u32 s39, s39, 0
	s_waitcnt vmcnt(7) lgkmcnt(6)
	v_pk_add_f32 v[170:171], v[170:171], v[206:207]
	v_pk_add_f32 v[172:173], v[172:173], v[208:209]
	global_store_dwordx4 v138, v[170:173], s[38:39] sc1
	s_add_u32 s38, s38, 0x4000
	s_addc_u32 s39, s39, 0
	s_waitcnt vmcnt(7) lgkmcnt(5)
	v_pk_add_f32 v[174:175], v[174:175], v[210:211]
	v_pk_add_f32 v[176:177], v[176:177], v[212:213]
	global_store_dwordx4 v138, v[174:177], s[38:39] sc1
	s_add_u32 s38, s38, 0x4000
	s_addc_u32 s39, s39, 0
	s_waitcnt vmcnt(7) lgkmcnt(4)
	v_pk_add_f32 v[182:183], v[182:183], v[214:215]
	v_pk_add_f32 v[184:185], v[184:185], v[216:217]
	global_store_dwordx4 v138, v[182:185], s[38:39] sc1
	s_add_u32 s38, s38, 0x4000
	s_addc_u32 s39, s39, 0
	s_waitcnt vmcnt(7) lgkmcnt(3)
	v_pk_add_f32 v[186:187], v[186:187], v[218:219]
	v_pk_add_f32 v[188:189], v[188:189], v[220:221]
	global_store_dwordx4 v138, v[186:189], s[38:39] sc1
	s_add_u32 s38, s38, 0x4000
	s_addc_u32 s39, s39, 0
	s_waitcnt vmcnt(7) lgkmcnt(2)
	v_pk_add_f32 v[190:191], v[190:191], v[222:223]
	v_pk_add_f32 v[192:193], v[192:193], v[224:225]
	global_store_dwordx4 v138, v[190:193], s[38:39] sc1
	s_add_u32 s38, s38, 0x4000
	s_addc_u32 s39, s39, 0
	s_waitcnt vmcnt(7) lgkmcnt(1)
	v_pk_add_f32 v[194:195], v[194:195], v[226:227]
	v_pk_add_f32 v[196:197], v[196:197], v[228:229]
	global_store_dwordx4 v138, v[194:197], s[38:39] sc1
	s_add_u32 s38, s38, 0x4000
	s_addc_u32 s39, s39, 0
	s_waitcnt vmcnt(7) lgkmcnt(0)
	v_pk_add_f32 v[198:199], v[198:199], v[230:231]
	v_pk_add_f32 v[200:201], v[200:201], v[232:233]
	global_store_dwordx4 v138, v[198:201], s[38:39] sc1
	s_add_u32 s38, s38, 0x4000
	s_addc_u32 s39, s39, 0
	s_cmpk_lt_i32 s44, 0x100
	s_cbranch_scc0 .LBB0_1642
